# streaming (nt) cache hint on single-use full-line loads: P2 Z element loads and prep_weights f32 weight loads
# speedup vs baseline: 1.0044x; 1.0044x over previous
; #define LAS __attribute__((address_space(3)))
; template <int MODE>
; __device__ __forceinline__ void transpose_item(const float* W, int K, int Nsrc, const float* g, bf16_t* WT, LAS float* scr, int kb, int nb, int lane) {
;     ...
;     for (int i = 0; i < 8; ++i) { const int kk = 8 * i + (lane >> 3); f32x4 v = {0.f, 0.f, 0.f, 0.f};
;         if (src >= 0) { v = *(const f32x4*)(W + (size_t)(k0 + kk) * Nsrc + src); if (g) v = v * g[k0 + kk]; }
;         LAS float* d = scr + kk * 33 + (lane & 7) * 4; d[0] = v[0]; d[1] = v[1]; d[2] = v[2]; d[3] = v[3]; }
; __device__ __forceinline__ void prep_weights(const Ctx& P, LAS unsigned char* lds, int l, int gw, int NGW) {
;     ...
;         transpose_item<0>(p_wdn + (size_t)l * DFF * D, DFF, D, nullptr, (bf16_t*)(ws + WS_WDN) + (size_t)l * D * DFF, scr, r / 32, r % 32, lane);
.LBB0_12:
	s_cmpk_gt_i32 s50, 0xe7f
	s_mov_b64 s[0:1], -1
	s_cbranch_scc0 .LBB0_46
	s_cmpk_gt_u32 s50, 0x107f
	s_cbranch_scc0 .LBB0_43
	s_cmpk_gt_u32 s50, 0x127f
	s_cbranch_scc0 .LBB0_40
	s_cmpk_gt_u32 s50, 0x147f
	s_cbranch_scc0 .LBB0_37
	s_cmpk_gt_u32 s50, 0x207f
	s_cbranch_scc0 .LBB0_18
	s_and_b32 s0, s45, 0x7fffffc0
	s_add_i32 s30, s0, 0xffffbf00
	s_and_b32 s0, s43, 0x3e0
	v_or_b32_e32 v2, s0, v1
	v_lshlrev_b32_e32 v10, 2, v2
	v_or_b32_e32 v2, s30, v8
	v_lshl_add_u64 v[24:25], s[28:29], 0, v[10:11]
	v_lshlrev_b32_e32 v10, 10, v2
	v_lshl_add_u64 v[2:3], v[10:11], 2, v[24:25]
	flat_load_dwordx4 v[2:5], v[2:3] nt
	v_or_b32_e32 v10, s30, v28
	v_lshlrev_b32_e32 v10, 10, v10
	v_lshl_add_u64 v[26:27], v[10:11], 2, v[24:25]
	v_or_b32_e32 v10, s30, v29
	v_lshlrev_b32_e32 v10, 10, v10
	v_or_b32_e32 v51, s0, v30
	v_mul_u32_u24_e32 v51, 0xc00, v51
	s_waitcnt vmcnt(0) lgkmcnt(0)
	ds_write2_b32 v36, v2, v3 offset1:1
	ds_write2_b32 v36, v4, v5 offset0:2 offset1:3
	flat_load_dwordx4 v[2:5], v[26:27] nt
	v_lshl_add_u64 v[26:27], v[10:11], 2, v[24:25]
	v_or_b32_e32 v10, s30, v30
	v_lshlrev_b32_e32 v10, 10, v10
	s_waitcnt vmcnt(0) lgkmcnt(0)
	ds_write2_b32 v37, v2, v3 offset1:1
	ds_write2_b32 v38, v4, v5 offset1:1
	flat_load_dwordx4 v[2:5], v[26:27] nt
	v_lshl_add_u64 v[26:27], v[10:11], 2, v[24:25]
	v_or_b32_e32 v10, s30, v31
	v_lshlrev_b32_e32 v10, 10, v10
	s_waitcnt vmcnt(0) lgkmcnt(0)
	ds_write2_b32 v39, v2, v3 offset1:1
	ds_write2_b32 v40, v4, v5 offset1:1
	flat_load_dwordx4 v[2:5], v[26:27] nt
	v_lshl_add_u64 v[26:27], v[10:11], 2, v[24:25]
	v_or_b32_e32 v10, s30, v32
	v_lshlrev_b32_e32 v10, 10, v10
	s_waitcnt vmcnt(0) lgkmcnt(0)
	ds_write2_b32 v41, v2, v3 offset1:1
	ds_write2_b32 v42, v4, v5 offset1:1
	flat_load_dwordx4 v[2:5], v[26:27] nt
	v_lshl_add_u64 v[26:27], v[10:11], 2, v[24:25]
	v_or_b32_e32 v10, s30, v33
	v_lshlrev_b32_e32 v10, 10, v10
	s_waitcnt vmcnt(0) lgkmcnt(0)
	ds_write2_b32 v43, v2, v3 offset1:1
	ds_write2_b32 v44, v4, v5 offset1:1
	flat_load_dwordx4 v[2:5], v[26:27] nt
	v_lshl_add_u64 v[26:27], v[10:11], 2, v[24:25]
	v_or_b32_e32 v10, s30, v34
	v_lshlrev_b32_e32 v10, 10, v10
	v_lshl_add_u64 v[24:25], v[10:11], 2, v[24:25]
	v_or_b32_e32 v10, s0, v8
	v_mul_u32_u24_e32 v10, 0xc00, v10
	v_lshlrev_b32_e32 v10, 1, v10
	s_waitcnt vmcnt(0) lgkmcnt(0)
	ds_write2_b32 v45, v2, v3 offset1:1
	ds_write2_b32 v46, v4, v5 offset1:1
	flat_load_dwordx4 v[2:5], v[26:27] nt
	v_or_b32_e32 v26, s0, v28
	v_or_b32_e32 v27, s0, v29
	v_mul_u32_u24_e32 v26, 0xc00, v26
	v_mul_u32_u24_e32 v27, 0xc00, v27
	s_mov_b64 s[0:1], 0
	s_waitcnt vmcnt(0) lgkmcnt(0)
	ds_write2_b32 v47, v2, v3 offset1:1
	ds_write2_b32 v48, v4, v5 offset1:1
	flat_load_dwordx4 v[2:5], v[24:25] nt
	v_lshl_add_u64 v[24:25], s[30:31], 1, v[14:15]
	v_lshl_add_u64 v[60:61], v[24:25], 0, v[10:11]
	v_lshlrev_b32_e32 v10, 1, v26
	v_lshl_add_u64 v[62:63], v[24:25], 0, v[10:11]
	v_lshlrev_b32_e32 v10, 1, v27
	v_lshl_add_u64 v[64:65], v[24:25], 0, v[10:11]
	v_lshlrev_b32_e32 v10, 1, v51
	v_lshl_add_u64 v[66:67], v[24:25], 0, v[10:11]
	s_waitcnt vmcnt(0) lgkmcnt(0)
	ds_write2_b32 v49, v2, v3 offset1:1
	ds_write2_b32 v50, v4, v5 offset1:1
	s_waitcnt lgkmcnt(0)
	ds_read2_b32 v[24:25], v35 offset0:33 offset1:41
	ds_read2_b32 v[26:27], v35 offset1:8
	ds_read2_b32 v[52:53], v35 offset0:66 offset1:74
	ds_read2_b32 v[54:55], v35 offset0:99 offset1:107
	ds_read2_b32 v[56:57], v35 offset0:132 offset1:140
	ds_read2_b32 v[58:59], v35 offset0:165 offset1:173
	ds_read2_b32 v[68:69], v35 offset0:198 offset1:206
	ds_read2_b32 v[70:71], v35 offset0:231 offset1:239
	ds_read2_b32 v[72:73], v35 offset0:16 offset1:24
	ds_read2_b32 v[74:75], v35 offset0:49 offset1:57
	ds_read2_b32 v[76:77], v35 offset0:82 offset1:90
	ds_read2_b32 v[78:79], v35 offset0:115 offset1:123
	ds_read2_b32 v[80:81], v35 offset0:148 offset1:156
	ds_read2_b32 v[82:83], v35 offset0:181 offset1:189
	ds_read2_b32 v[84:85], v35 offset0:214 offset1:222
	ds_read2_b32 v[86:87], v35 offset0:247 offset1:255
	s_waitcnt lgkmcnt(14)
	v_cvt_pk_bf16_f32 v2, v26, v24
	s_waitcnt lgkmcnt(12)
	v_cvt_pk_bf16_f32 v3, v52, v54
	s_waitcnt lgkmcnt(10)
	v_cvt_pk_bf16_f32 v4, v56, v58
	s_waitcnt lgkmcnt(8)
	v_cvt_pk_bf16_f32 v5, v68, v70
	v_cvt_pk_bf16_f32 v24, v27, v25
	v_cvt_pk_bf16_f32 v25, v53, v55
	v_cvt_pk_bf16_f32 v26, v57, v59
	v_cvt_pk_bf16_f32 v27, v69, v71
	s_waitcnt lgkmcnt(6)
	v_cvt_pk_bf16_f32 v52, v72, v74
	s_waitcnt lgkmcnt(4)
	v_cvt_pk_bf16_f32 v53, v76, v78
	s_waitcnt lgkmcnt(2)
	v_cvt_pk_bf16_f32 v54, v80, v82
	s_waitcnt lgkmcnt(0)
	v_cvt_pk_bf16_f32 v55, v84, v86
	v_cvt_pk_bf16_f32 v56, v73, v75
	v_cvt_pk_bf16_f32 v57, v77, v79
	v_cvt_pk_bf16_f32 v58, v81, v83
	v_cvt_pk_bf16_f32 v59, v85, v87
	global_store_dwordx4 v[60:61], v[2:5], off
	global_store_dwordx4 v[62:63], v[24:27], off
	global_store_dwordx4 v[64:65], v[52:55], off
	global_store_dwordx4 v[66:67], v[56:59], off
	s_waitcnt lgkmcnt(0)
; #define LAS __attribute__((address_space(3)))
; template <int MODE>
; __device__ __forceinline__ void transpose_item(const float* W, int K, int Nsrc, const float* g, bf16_t* WT, LAS float* scr, int kb, int nb, int lane) {
;     ...
;     for (int i = 0; i < 8; ++i) { const int kk = 8 * i + (lane >> 3); f32x4 v = {0.f, 0.f, 0.f, 0.f};
;         if (src >= 0) { v = *(const f32x4*)(W + (size_t)(k0 + kk) * Nsrc + src); if (g) v = v * g[k0 + kk]; }
;         LAS float* d = scr + kk * 33 + (lane & 7) * 4; d[0] = v[0]; d[1] = v[1]; d[2] = v[2]; d[3] = v[3]; }
; __device__ __forceinline__ void prep_weights(const Ctx& P, LAS unsigned char* lds, int l, int gw, int NGW) {
;     ...
;         if (r < I_UP) { transpose_item<0>(p_wup + (size_t)l * D * DUP, D, DUP, p_g2 + l * D, (bf16_t*)(ws + WS_WUP) + (size_t)l * DUP * D, scr, r / 192, r % 192, lane); continue; } r -= I_UP;
.LBB0_18:
	s_andn2_b64 vcc, exec, s[0:1]
	s_cbranch_vccnz .LBB0_36
	s_add_i32 s0, s50, 0xeb80
	s_and_b32 s1, s0, 0xffff
	s_mul_i32 s1, s1, 0xaaab
	s_lshr_b32 s1, s1, 23
	s_mul_i32 s4, s1, 0xc0
	s_sub_i32 s0, s0, s4
	s_lshl_b32 s0, s0, 5
	s_lshl_b32 s5, s1, 6
	s_and_b32 s4, s0, 0xffe0
	v_or_b32_e32 v2, s4, v1
	v_or_b32_e32 v26, s5, v8
	v_lshlrev_b32_e32 v10, 2, v2
	v_mul_u32_u24_e32 v2, 0x1800, v26
	v_lshl_add_u64 v[24:25], s[24:25], 0, v[10:11]
	v_lshlrev_b32_e32 v10, 2, v2
	v_lshl_add_u64 v[2:3], v[24:25], 0, v[10:11]
	flat_load_dwordx4 v[2:5], v[2:3] nt
	v_cndmask_b32_e64 v10, 0, 1, s[34:35]
	v_cmp_ne_u32_e64 s[0:1], 1, v10
	s_andn2_b64 vcc, exec, s[34:35]
	s_cbranch_vccnz .LBB0_21
	v_lshlrev_b32_e32 v10, 2, v26
	v_lshl_add_u64 v[26:27], s[26:27], 0, v[10:11]
	flat_load_dword v10, v[26:27]
	s_waitcnt vmcnt(0) lgkmcnt(0)
	v_pk_mul_f32 v[4:5], v[4:5], v[10:11] op_sel_hi:[1,0]
	v_pk_mul_f32 v[2:3], v[2:3], v[10:11] op_sel_hi:[1,0]
.LBB0_21:
	s_waitcnt vmcnt(0) lgkmcnt(0)
	ds_write2_b32 v36, v2, v3 offset1:1
	ds_write2_b32 v36, v4, v5 offset0:2 offset1:3
	v_or_b32_e32 v2, s5, v28
	v_mul_u32_u24_e32 v2, 0x1800, v2
	v_lshlrev_b32_e32 v10, 2, v2
	v_lshl_add_u64 v[2:3], v[24:25], 0, v[10:11]
	flat_load_dwordx4 v[2:5], v[2:3] nt
	s_and_b64 vcc, exec, s[0:1]
	v_add_lshl_u32 v26, v8, s5, 2
	s_cbranch_vccnz .LBB0_23
	v_mov_b32_e32 v27, v11
	v_lshl_add_u64 v[52:53], s[26:27], 0, v[26:27]
	flat_load_dword v10, v[52:53] offset:32
	s_waitcnt vmcnt(0) lgkmcnt(0)
	v_pk_mul_f32 v[4:5], v[4:5], v[10:11] op_sel_hi:[1,0]
	v_pk_mul_f32 v[2:3], v[2:3], v[10:11] op_sel_hi:[1,0]
.LBB0_23:
	s_waitcnt vmcnt(0) lgkmcnt(0)
	ds_write2_b32 v37, v2, v3 offset1:1
	ds_write2_b32 v38, v4, v5 offset1:1
	v_or_b32_e32 v2, s5, v29
	v_mul_u32_u24_e32 v2, 0x1800, v2
	v_lshlrev_b32_e32 v10, 2, v2
	v_lshl_add_u64 v[2:3], v[24:25], 0, v[10:11]
	flat_load_dwordx4 v[2:5], v[2:3] nt
	s_and_b64 vcc, exec, s[0:1]
	s_cbranch_vccnz .LBB0_25
	v_mov_b32_e32 v27, v11
	v_lshl_add_u64 v[52:53], s[26:27], 0, v[26:27]
	flat_load_dword v10, v[52:53] offset:64
	s_waitcnt vmcnt(0) lgkmcnt(0)
	v_pk_mul_f32 v[4:5], v[4:5], v[10:11] op_sel_hi:[1,0]
	v_pk_mul_f32 v[2:3], v[2:3], v[10:11] op_sel_hi:[1,0]
.LBB0_25:
	s_waitcnt vmcnt(0) lgkmcnt(0)
	ds_write2_b32 v39, v2, v3 offset1:1
	ds_write2_b32 v40, v4, v5 offset1:1
	v_or_b32_e32 v2, s5, v30
	v_mul_u32_u24_e32 v2, 0x1800, v2
	v_lshlrev_b32_e32 v10, 2, v2
	v_lshl_add_u64 v[2:3], v[24:25], 0, v[10:11]
	flat_load_dwordx4 v[2:5], v[2:3] nt
	s_and_b64 vcc, exec, s[0:1]
	s_cbranch_vccnz .LBB0_27
	v_mov_b32_e32 v27, v11
	v_lshl_add_u64 v[52:53], s[26:27], 0, v[26:27]
	flat_load_dword v10, v[52:53] offset:96
	s_waitcnt vmcnt(0) lgkmcnt(0)
	v_pk_mul_f32 v[4:5], v[4:5], v[10:11] op_sel_hi:[1,0]
	v_pk_mul_f32 v[2:3], v[2:3], v[10:11] op_sel_hi:[1,0]
.LBB0_27:
	s_waitcnt vmcnt(0) lgkmcnt(0)
	ds_write2_b32 v41, v2, v3 offset1:1
	ds_write2_b32 v42, v4, v5 offset1:1
	v_or_b32_e32 v2, s5, v31
	v_mul_u32_u24_e32 v2, 0x1800, v2
	v_lshlrev_b32_e32 v10, 2, v2
	v_lshl_add_u64 v[2:3], v[24:25], 0, v[10:11]
	flat_load_dwordx4 v[2:5], v[2:3] nt
	s_and_b64 vcc, exec, s[0:1]
	s_cbranch_vccnz .LBB0_29
	v_mov_b32_e32 v27, v11
	v_lshl_add_u64 v[52:53], s[26:27], 0, v[26:27]
	flat_load_dword v10, v[52:53] offset:128
	s_waitcnt vmcnt(0) lgkmcnt(0)
	v_pk_mul_f32 v[4:5], v[4:5], v[10:11] op_sel_hi:[1,0]
	v_pk_mul_f32 v[2:3], v[2:3], v[10:11] op_sel_hi:[1,0]
.LBB0_29:
	s_waitcnt vmcnt(0) lgkmcnt(0)
	ds_write2_b32 v43, v2, v3 offset1:1
	ds_write2_b32 v44, v4, v5 offset1:1
	v_or_b32_e32 v2, s5, v32
	v_mul_u32_u24_e32 v2, 0x1800, v2
	v_lshlrev_b32_e32 v10, 2, v2
	v_lshl_add_u64 v[2:3], v[24:25], 0, v[10:11]
	flat_load_dwordx4 v[2:5], v[2:3] nt
	s_and_b64 vcc, exec, s[0:1]
	s_cbranch_vccnz .LBB0_31
	v_mov_b32_e32 v27, v11
	v_lshl_add_u64 v[52:53], s[26:27], 0, v[26:27]
	flat_load_dword v10, v[52:53] offset:160
	s_waitcnt vmcnt(0) lgkmcnt(0)
	v_pk_mul_f32 v[4:5], v[4:5], v[10:11] op_sel_hi:[1,0]
	v_pk_mul_f32 v[2:3], v[2:3], v[10:11] op_sel_hi:[1,0]
.LBB0_31:
	s_waitcnt vmcnt(0) lgkmcnt(0)
	ds_write2_b32 v45, v2, v3 offset1:1
	ds_write2_b32 v46, v4, v5 offset1:1
	v_or_b32_e32 v2, s5, v33
	v_mul_u32_u24_e32 v2, 0x1800, v2
	v_lshlrev_b32_e32 v10, 2, v2
	v_lshl_add_u64 v[2:3], v[24:25], 0, v[10:11]
	flat_load_dwordx4 v[2:5], v[2:3] nt
	s_and_b64 vcc, exec, s[0:1]
	s_cbranch_vccnz .LBB0_33
	v_mov_b32_e32 v27, v11
	v_lshl_add_u64 v[52:53], s[26:27], 0, v[26:27]
	flat_load_dword v10, v[52:53] offset:192
	s_waitcnt vmcnt(0) lgkmcnt(0)
	v_pk_mul_f32 v[4:5], v[4:5], v[10:11] op_sel_hi:[1,0]
	v_pk_mul_f32 v[2:3], v[2:3], v[10:11] op_sel_hi:[1,0]
.LBB0_33:
	s_waitcnt vmcnt(0) lgkmcnt(0)
	ds_write2_b32 v47, v2, v3 offset1:1
	ds_write2_b32 v48, v4, v5 offset1:1
	v_or_b32_e32 v2, s5, v34
	v_mul_u32_u24_e32 v2, 0x1800, v2
	v_lshlrev_b32_e32 v10, 2, v2
	v_lshl_add_u64 v[2:3], v[24:25], 0, v[10:11]
	flat_load_dwordx4 v[2:5], v[2:3] nt
	s_and_b64 vcc, exec, s[0:1]
	s_cbranch_vccnz .LBB0_35
	v_mov_b32_e32 v27, v11
	v_lshl_add_u64 v[24:25], s[26:27], 0, v[26:27]
	flat_load_dword v10, v[24:25] offset:224
	s_waitcnt vmcnt(0) lgkmcnt(0)
	v_pk_mul_f32 v[4:5], v[4:5], v[10:11] op_sel_hi:[1,0]
	v_pk_mul_f32 v[2:3], v[2:3], v[10:11] op_sel_hi:[1,0]

; #define LAS __attribute__((address_space(3)))
; template <int MODE>
; __device__ __forceinline__ void transpose_item(const float* W, int K, int Nsrc, const float* g, bf16_t* WT, LAS float* scr, int kb, int nb, int lane) {
;     ...
;     for (int i = 0; i < 8; ++i) { const int kk = 8 * i + (lane >> 3); f32x4 v = {0.f, 0.f, 0.f, 0.f};
;         if (src >= 0) { v = *(const f32x4*)(W + (size_t)(k0 + kk) * Nsrc + src); if (g) v = v * g[k0 + kk]; }
;         LAS float* d = scr + kk * 33 + (lane & 7) * 4; d[0] = v[0]; d[1] = v[1]; d[2] = v[2]; d[3] = v[3]; }
; __device__ __forceinline__ void prep_weights(const Ctx& P, LAS unsigned char* lds, int l, int gw, int NGW) {
;     ...
;         if (r < I_SQ) { transpose_item<0>(p_wo + (size_t)l * D * D, D, D, nullptr, (bf16_t*)(ws + WS_WO) + (size_t)l * D * D, scr, r / 32, r % 32, lane); continue; } r -= I_SQ;
.LBB0_37:
	s_andn2_b64 vcc, exec, s[0:1]
	s_cbranch_vccnz .LBB0_39
	s_and_b32 s0, s45, 0x3fc0
	s_add_i32 s30, s0, 0xffffdb00
	s_and_b32 s0, s43, 0x3e0
	v_or_b32_e32 v2, s0, v1
	v_lshlrev_b32_e32 v10, 2, v2
	v_or_b32_e32 v2, s30, v8
	v_lshl_add_u64 v[24:25], s[22:23], 0, v[10:11]
	v_lshlrev_b32_e32 v10, 10, v2
	v_lshl_add_u64 v[2:3], v[10:11], 2, v[24:25]
	flat_load_dwordx4 v[2:5], v[2:3] nt
	v_or_b32_e32 v10, s30, v28
	v_lshlrev_b32_e32 v10, 10, v10
	v_lshl_add_u64 v[26:27], v[10:11], 2, v[24:25]
	v_or_b32_e32 v10, s30, v29
	v_lshlrev_b32_e32 v10, 10, v10
	v_or_b32_e32 v51, s0, v30
	s_waitcnt vmcnt(0) lgkmcnt(0)
	ds_write2_b32 v36, v2, v3 offset1:1
	ds_write2_b32 v36, v4, v5 offset0:2 offset1:3
	flat_load_dwordx4 v[2:5], v[26:27] nt
	v_lshl_add_u64 v[26:27], v[10:11], 2, v[24:25]
	v_or_b32_e32 v10, s30, v30
	v_lshlrev_b32_e32 v10, 10, v10
	s_waitcnt vmcnt(0) lgkmcnt(0)
	ds_write2_b32 v37, v2, v3 offset1:1
	ds_write2_b32 v38, v4, v5 offset1:1
	flat_load_dwordx4 v[2:5], v[26:27] nt
	v_lshl_add_u64 v[26:27], v[10:11], 2, v[24:25]
	v_or_b32_e32 v10, s30, v31
	v_lshlrev_b32_e32 v10, 10, v10
	s_waitcnt vmcnt(0) lgkmcnt(0)
	ds_write2_b32 v39, v2, v3 offset1:1
	ds_write2_b32 v40, v4, v5 offset1:1
	flat_load_dwordx4 v[2:5], v[26:27] nt
	v_lshl_add_u64 v[26:27], v[10:11], 2, v[24:25]
	v_or_b32_e32 v10, s30, v32
	v_lshlrev_b32_e32 v10, 10, v10
	s_waitcnt vmcnt(0) lgkmcnt(0)
	ds_write2_b32 v41, v2, v3 offset1:1
	ds_write2_b32 v42, v4, v5 offset1:1
	flat_load_dwordx4 v[2:5], v[26:27] nt
	v_lshl_add_u64 v[26:27], v[10:11], 2, v[24:25]
	v_or_b32_e32 v10, s30, v33
	v_lshlrev_b32_e32 v10, 10, v10
	s_waitcnt vmcnt(0) lgkmcnt(0)
	ds_write2_b32 v43, v2, v3 offset1:1
	ds_write2_b32 v44, v4, v5 offset1:1
	flat_load_dwordx4 v[2:5], v[26:27] nt
	v_lshl_add_u64 v[26:27], v[10:11], 2, v[24:25]
	v_or_b32_e32 v10, s30, v34
	v_lshlrev_b32_e32 v10, 10, v10
	v_lshl_add_u64 v[24:25], v[10:11], 2, v[24:25]
	v_or_b32_e32 v10, s0, v8
	v_lshlrev_b32_e32 v10, 11, v10
	s_waitcnt vmcnt(0) lgkmcnt(0)
	ds_write2_b32 v45, v2, v3 offset1:1
	ds_write2_b32 v46, v4, v5 offset1:1
	flat_load_dwordx4 v[2:5], v[26:27] nt
	v_or_b32_e32 v26, s0, v28
	v_or_b32_e32 v27, s0, v29
	s_waitcnt vmcnt(0) lgkmcnt(0)
	ds_write2_b32 v47, v2, v3 offset1:1
	ds_write2_b32 v48, v4, v5 offset1:1
	flat_load_dwordx4 v[2:5], v[24:25] nt
	v_lshl_add_u64 v[24:25], s[30:31], 1, v[18:19]
	v_lshl_add_u64 v[60:61], v[24:25], 0, v[10:11]
	v_lshlrev_b32_e32 v10, 11, v26
	v_lshl_add_u64 v[62:63], v[24:25], 0, v[10:11]
	v_lshlrev_b32_e32 v10, 11, v27
	v_lshl_add_u64 v[64:65], v[24:25], 0, v[10:11]
	v_lshlrev_b32_e32 v10, 11, v51
	v_lshl_add_u64 v[66:67], v[24:25], 0, v[10:11]
	s_waitcnt vmcnt(0) lgkmcnt(0)
	ds_write2_b32 v49, v2, v3 offset1:1
	ds_write2_b32 v50, v4, v5 offset1:1
	s_waitcnt lgkmcnt(0)
	ds_read2_b32 v[24:25], v35 offset0:33 offset1:41
	ds_read2_b32 v[26:27], v35 offset1:8
	ds_read2_b32 v[52:53], v35 offset0:66 offset1:74
	ds_read2_b32 v[54:55], v35 offset0:99 offset1:107
	ds_read2_b32 v[56:57], v35 offset0:132 offset1:140
	ds_read2_b32 v[58:59], v35 offset0:165 offset1:173
	ds_read2_b32 v[68:69], v35 offset0:198 offset1:206
	ds_read2_b32 v[70:71], v35 offset0:231 offset1:239
	ds_read2_b32 v[72:73], v35 offset0:49 offset1:57
	ds_read2_b32 v[74:75], v35 offset0:16 offset1:24
	ds_read2_b32 v[76:77], v35 offset0:82 offset1:90
	ds_read2_b32 v[78:79], v35 offset0:115 offset1:123
	ds_read2_b32 v[80:81], v35 offset0:148 offset1:156
	ds_read2_b32 v[82:83], v35 offset0:181 offset1:189
	ds_read2_b32 v[84:85], v35 offset0:214 offset1:222
	ds_read2_b32 v[86:87], v35 offset0:247 offset1:255
	s_waitcnt lgkmcnt(14)
	v_cvt_pk_bf16_f32 v2, v26, v24
	s_waitcnt lgkmcnt(12)
	v_cvt_pk_bf16_f32 v3, v52, v54
	s_waitcnt lgkmcnt(10)
	v_cvt_pk_bf16_f32 v4, v56, v58
	s_waitcnt lgkmcnt(8)
	v_cvt_pk_bf16_f32 v5, v68, v70
	v_cvt_pk_bf16_f32 v24, v27, v25
	v_cvt_pk_bf16_f32 v25, v53, v55
	v_cvt_pk_bf16_f32 v26, v57, v59
	v_cvt_pk_bf16_f32 v27, v69, v71
	s_waitcnt lgkmcnt(6)
	v_cvt_pk_bf16_f32 v52, v74, v72
	s_waitcnt lgkmcnt(4)
	v_cvt_pk_bf16_f32 v53, v76, v78
	s_waitcnt lgkmcnt(2)
	v_cvt_pk_bf16_f32 v54, v80, v82
	s_waitcnt lgkmcnt(0)
	v_cvt_pk_bf16_f32 v55, v84, v86
	v_cvt_pk_bf16_f32 v56, v75, v73
	v_cvt_pk_bf16_f32 v57, v77, v79
	v_cvt_pk_bf16_f32 v58, v81, v83
	v_cvt_pk_bf16_f32 v59, v85, v87
	global_store_dwordx4 v[60:61], v[2:5], off
	global_store_dwordx4 v[62:63], v[24:27], off
	global_store_dwordx4 v[64:65], v[52:55], off
	global_store_dwordx4 v[66:67], v[56:59], off
	s_waitcnt lgkmcnt(0)

; #define LAS __attribute__((address_space(3)))
; template <int MODE>
; __device__ __forceinline__ void transpose_item(const float* W, int K, int Nsrc, const float* g, bf16_t* WT, LAS float* scr, int kb, int nb, int lane) {
;     ...
;     for (int i = 0; i < 8; ++i) { const int kk = 8 * i + (lane >> 3); f32x4 v = {0.f, 0.f, 0.f, 0.f};
;         if (src >= 0) { v = *(const f32x4*)(W + (size_t)(k0 + kk) * Nsrc + src); if (g) v = v * g[k0 + kk]; }
;         LAS float* d = scr + kk * 33 + (lane & 7) * 4; d[0] = v[0]; d[1] = v[1]; d[2] = v[2]; d[3] = v[3]; }
; __device__ __forceinline__ void prep_weights(const Ctx& P, LAS unsigned char* lds, int l, int gw, int NGW) {
;     ...
;         if (r < I_SQ) { transpose_item<0>(p_wb + (size_t)l * D * D, D, D, nullptr, (bf16_t*)(ws + WS_WB) + (size_t)l * D * D, scr, r / 32, r % 32, lane); continue; } r -= I_SQ;
.LBB0_40:
	s_andn2_b64 vcc, exec, s[0:1]
	s_cbranch_vccnz .LBB0_42
	s_and_b32 s0, s45, 0x3fc0
	s_add_i32 s30, s0, 0xffffdf00
	s_and_b32 s0, s43, 0x3e0
	v_or_b32_e32 v2, s0, v1
	v_lshlrev_b32_e32 v10, 2, v2
	v_or_b32_e32 v2, s30, v8
	v_lshl_add_u64 v[24:25], s[18:19], 0, v[10:11]
	v_lshlrev_b32_e32 v10, 10, v2
	v_lshl_add_u64 v[2:3], v[10:11], 2, v[24:25]
	flat_load_dwordx4 v[2:5], v[2:3] nt
	v_or_b32_e32 v10, s30, v28
	v_lshlrev_b32_e32 v10, 10, v10
	v_lshl_add_u64 v[26:27], v[10:11], 2, v[24:25]
	v_or_b32_e32 v10, s30, v29
	v_lshlrev_b32_e32 v10, 10, v10
	v_or_b32_e32 v51, s0, v30
	s_waitcnt vmcnt(0) lgkmcnt(0)
	ds_write2_b32 v36, v2, v3 offset1:1
	ds_write2_b32 v36, v4, v5 offset0:2 offset1:3
	flat_load_dwordx4 v[2:5], v[26:27] nt
	v_lshl_add_u64 v[26:27], v[10:11], 2, v[24:25]
	v_or_b32_e32 v10, s30, v30
	v_lshlrev_b32_e32 v10, 10, v10
	s_waitcnt vmcnt(0) lgkmcnt(0)
	ds_write2_b32 v37, v2, v3 offset1:1
	ds_write2_b32 v38, v4, v5 offset1:1
	flat_load_dwordx4 v[2:5], v[26:27] nt
	v_lshl_add_u64 v[26:27], v[10:11], 2, v[24:25]
	v_or_b32_e32 v10, s30, v31
	v_lshlrev_b32_e32 v10, 10, v10
	s_waitcnt vmcnt(0) lgkmcnt(0)
	ds_write2_b32 v39, v2, v3 offset1:1
	ds_write2_b32 v40, v4, v5 offset1:1
	flat_load_dwordx4 v[2:5], v[26:27] nt
	v_lshl_add_u64 v[26:27], v[10:11], 2, v[24:25]
	v_or_b32_e32 v10, s30, v32
	v_lshlrev_b32_e32 v10, 10, v10
	s_waitcnt vmcnt(0) lgkmcnt(0)
	ds_write2_b32 v41, v2, v3 offset1:1
	ds_write2_b32 v42, v4, v5 offset1:1
	flat_load_dwordx4 v[2:5], v[26:27] nt
	v_lshl_add_u64 v[26:27], v[10:11], 2, v[24:25]
	v_or_b32_e32 v10, s30, v33
	v_lshlrev_b32_e32 v10, 10, v10
	s_waitcnt vmcnt(0) lgkmcnt(0)
	ds_write2_b32 v43, v2, v3 offset1:1
	ds_write2_b32 v44, v4, v5 offset1:1
	flat_load_dwordx4 v[2:5], v[26:27] nt
	v_lshl_add_u64 v[26:27], v[10:11], 2, v[24:25]
	v_or_b32_e32 v10, s30, v34
	v_lshlrev_b32_e32 v10, 10, v10
	v_lshl_add_u64 v[24:25], v[10:11], 2, v[24:25]
	v_or_b32_e32 v10, s0, v8
	v_lshlrev_b32_e32 v10, 11, v10
	s_waitcnt vmcnt(0) lgkmcnt(0)
	ds_write2_b32 v45, v2, v3 offset1:1
	ds_write2_b32 v46, v4, v5 offset1:1
	flat_load_dwordx4 v[2:5], v[26:27] nt
	v_or_b32_e32 v26, s0, v28
	v_or_b32_e32 v27, s0, v29
	s_waitcnt vmcnt(0) lgkmcnt(0)
	ds_write2_b32 v47, v2, v3 offset1:1
	ds_write2_b32 v48, v4, v5 offset1:1
	flat_load_dwordx4 v[2:5], v[24:25] nt
	v_lshl_add_u64 v[24:25], s[30:31], 1, v[20:21]
	v_lshl_add_u64 v[60:61], v[24:25], 0, v[10:11]
	v_lshlrev_b32_e32 v10, 11, v26
	v_lshl_add_u64 v[62:63], v[24:25], 0, v[10:11]
	v_lshlrev_b32_e32 v10, 11, v27
	v_lshl_add_u64 v[64:65], v[24:25], 0, v[10:11]
	v_lshlrev_b32_e32 v10, 11, v51
	v_lshl_add_u64 v[66:67], v[24:25], 0, v[10:11]
	s_waitcnt vmcnt(0) lgkmcnt(0)
	ds_write2_b32 v49, v2, v3 offset1:1
	ds_write2_b32 v50, v4, v5 offset1:1
	s_waitcnt lgkmcnt(0)
	ds_read2_b32 v[24:25], v35 offset0:33 offset1:41
	ds_read2_b32 v[26:27], v35 offset1:8
	ds_read2_b32 v[52:53], v35 offset0:66 offset1:74
	ds_read2_b32 v[54:55], v35 offset0:99 offset1:107
	ds_read2_b32 v[56:57], v35 offset0:132 offset1:140
	ds_read2_b32 v[58:59], v35 offset0:165 offset1:173
	ds_read2_b32 v[68:69], v35 offset0:198 offset1:206
	ds_read2_b32 v[70:71], v35 offset0:231 offset1:239
	ds_read2_b32 v[72:73], v35 offset0:49 offset1:57
	ds_read2_b32 v[74:75], v35 offset0:16 offset1:24
	ds_read2_b32 v[76:77], v35 offset0:82 offset1:90
	ds_read2_b32 v[78:79], v35 offset0:115 offset1:123
	ds_read2_b32 v[80:81], v35 offset0:148 offset1:156
	ds_read2_b32 v[82:83], v35 offset0:181 offset1:189
	ds_read2_b32 v[84:85], v35 offset0:214 offset1:222
	ds_read2_b32 v[86:87], v35 offset0:247 offset1:255
	s_waitcnt lgkmcnt(14)
	v_cvt_pk_bf16_f32 v2, v26, v24
	s_waitcnt lgkmcnt(12)
	v_cvt_pk_bf16_f32 v3, v52, v54
	s_waitcnt lgkmcnt(10)
	v_cvt_pk_bf16_f32 v4, v56, v58
	s_waitcnt lgkmcnt(8)
	v_cvt_pk_bf16_f32 v5, v68, v70
	v_cvt_pk_bf16_f32 v24, v27, v25
	v_cvt_pk_bf16_f32 v25, v53, v55
	v_cvt_pk_bf16_f32 v26, v57, v59
	v_cvt_pk_bf16_f32 v27, v69, v71
	s_waitcnt lgkmcnt(6)
	v_cvt_pk_bf16_f32 v52, v74, v72
	s_waitcnt lgkmcnt(4)
	v_cvt_pk_bf16_f32 v53, v76, v78
	s_waitcnt lgkmcnt(2)
	v_cvt_pk_bf16_f32 v54, v80, v82
	s_waitcnt lgkmcnt(0)
	v_cvt_pk_bf16_f32 v55, v84, v86
	v_cvt_pk_bf16_f32 v56, v75, v73
	v_cvt_pk_bf16_f32 v57, v77, v79
	v_cvt_pk_bf16_f32 v58, v81, v83
	v_cvt_pk_bf16_f32 v59, v85, v87
	global_store_dwordx4 v[60:61], v[2:5], off
	global_store_dwordx4 v[62:63], v[24:27], off
	global_store_dwordx4 v[64:65], v[52:55], off
	global_store_dwordx4 v[66:67], v[56:59], off
	s_waitcnt lgkmcnt(0)

; #define LAS __attribute__((address_space(3)))
; template <int MODE>
; __device__ __forceinline__ void transpose_item(const float* W, int K, int Nsrc, const float* g, bf16_t* WT, LAS float* scr, int kb, int nb, int lane) {
;     ...
;     for (int i = 0; i < 8; ++i) { const int kk = 8 * i + (lane >> 3); f32x4 v = {0.f, 0.f, 0.f, 0.f};
;         if (src >= 0) { v = *(const f32x4*)(W + (size_t)(k0 + kk) * Nsrc + src); if (g) v = v * g[k0 + kk]; }
;         LAS float* d = scr + kk * 33 + (lane & 7) * 4; d[0] = v[0]; d[1] = v[1]; d[2] = v[2]; d[3] = v[3]; }
; __device__ __forceinline__ void prep_weights(const Ctx& P, LAS unsigned char* lds, int l, int gw, int NGW) {
;     ...
;         if (r < I_SQ) { transpose_item<0>(p_wa + (size_t)l * D * D, D, D, nullptr, (bf16_t*)(ws + WS_WA) + (size_t)l * D * D, scr, r / 32, r % 32, lane); continue; } r -= I_SQ;
.LBB0_43:
	s_andn2_b64 vcc, exec, s[0:1]
	s_cbranch_vccnz .LBB0_45
	s_and_b32 s0, s45, 0x3fc0
	s_add_i32 s30, s0, 0xffffe300
	s_and_b32 s0, s43, 0x3e0
	v_or_b32_e32 v2, s0, v1
	v_lshlrev_b32_e32 v10, 2, v2
	v_or_b32_e32 v2, s30, v8
	v_lshl_add_u64 v[24:25], s[16:17], 0, v[10:11]
	v_lshlrev_b32_e32 v10, 10, v2
	v_lshl_add_u64 v[2:3], v[10:11], 2, v[24:25]
	flat_load_dwordx4 v[2:5], v[2:3] nt
	v_or_b32_e32 v10, s30, v28
	v_lshlrev_b32_e32 v10, 10, v10
	v_lshl_add_u64 v[26:27], v[10:11], 2, v[24:25]
	v_or_b32_e32 v10, s30, v29
	v_lshlrev_b32_e32 v10, 10, v10
	v_or_b32_e32 v51, s0, v30
	s_waitcnt vmcnt(0) lgkmcnt(0)
	ds_write2_b32 v36, v2, v3 offset1:1
	ds_write2_b32 v36, v4, v5 offset0:2 offset1:3
	flat_load_dwordx4 v[2:5], v[26:27] nt
	v_lshl_add_u64 v[26:27], v[10:11], 2, v[24:25]
	v_or_b32_e32 v10, s30, v30
	v_lshlrev_b32_e32 v10, 10, v10
	s_waitcnt vmcnt(0) lgkmcnt(0)
	ds_write2_b32 v37, v2, v3 offset1:1
	ds_write2_b32 v38, v4, v5 offset1:1
	flat_load_dwordx4 v[2:5], v[26:27] nt
	v_lshl_add_u64 v[26:27], v[10:11], 2, v[24:25]
	v_or_b32_e32 v10, s30, v31
	v_lshlrev_b32_e32 v10, 10, v10
	s_waitcnt vmcnt(0) lgkmcnt(0)
	ds_write2_b32 v39, v2, v3 offset1:1
	ds_write2_b32 v40, v4, v5 offset1:1
	flat_load_dwordx4 v[2:5], v[26:27] nt
	v_lshl_add_u64 v[26:27], v[10:11], 2, v[24:25]
	v_or_b32_e32 v10, s30, v32
	v_lshlrev_b32_e32 v10, 10, v10
	s_waitcnt vmcnt(0) lgkmcnt(0)
	ds_write2_b32 v41, v2, v3 offset1:1
	ds_write2_b32 v42, v4, v5 offset1:1
	flat_load_dwordx4 v[2:5], v[26:27] nt
	v_lshl_add_u64 v[26:27], v[10:11], 2, v[24:25]
	v_or_b32_e32 v10, s30, v33
	v_lshlrev_b32_e32 v10, 10, v10
	s_waitcnt vmcnt(0) lgkmcnt(0)
	ds_write2_b32 v43, v2, v3 offset1:1
	ds_write2_b32 v44, v4, v5 offset1:1
	flat_load_dwordx4 v[2:5], v[26:27] nt
	v_lshl_add_u64 v[26:27], v[10:11], 2, v[24:25]
	v_or_b32_e32 v10, s30, v34
	v_lshlrev_b32_e32 v10, 10, v10
	v_lshl_add_u64 v[24:25], v[10:11], 2, v[24:25]
	v_or_b32_e32 v10, s0, v8
	v_lshlrev_b32_e32 v10, 11, v10
	s_waitcnt vmcnt(0) lgkmcnt(0)
	ds_write2_b32 v45, v2, v3 offset1:1
	ds_write2_b32 v46, v4, v5 offset1:1
	flat_load_dwordx4 v[2:5], v[26:27] nt
	v_or_b32_e32 v26, s0, v28
	v_or_b32_e32 v27, s0, v29
	s_waitcnt vmcnt(0) lgkmcnt(0)
	ds_write2_b32 v47, v2, v3 offset1:1
	ds_write2_b32 v48, v4, v5 offset1:1
	flat_load_dwordx4 v[2:5], v[24:25] nt
	v_lshl_add_u64 v[24:25], s[30:31], 1, v[22:23]
	v_lshl_add_u64 v[60:61], v[24:25], 0, v[10:11]
	v_lshlrev_b32_e32 v10, 11, v26
	v_lshl_add_u64 v[62:63], v[24:25], 0, v[10:11]
	v_lshlrev_b32_e32 v10, 11, v27
	v_lshl_add_u64 v[64:65], v[24:25], 0, v[10:11]
	v_lshlrev_b32_e32 v10, 11, v51
	v_lshl_add_u64 v[66:67], v[24:25], 0, v[10:11]
	s_waitcnt vmcnt(0) lgkmcnt(0)
	ds_write2_b32 v49, v2, v3 offset1:1
	ds_write2_b32 v50, v4, v5 offset1:1
	s_waitcnt lgkmcnt(0)
	ds_read2_b32 v[4:5], v35 offset0:33 offset1:41
	ds_read2_b32 v[24:25], v35 offset1:8
	ds_read2_b32 v[26:27], v35 offset0:66 offset1:74
	ds_read2_b32 v[52:53], v35 offset0:99 offset1:107
	ds_read2_b32 v[54:55], v35 offset0:132 offset1:140
	ds_read2_b32 v[56:57], v35 offset0:165 offset1:173
	ds_read2_b32 v[58:59], v35 offset0:198 offset1:206
	ds_read2_b32 v[68:69], v35 offset0:231 offset1:239
	ds_read2_b32 v[70:71], v35 offset0:49 offset1:57
	ds_read2_b32 v[72:73], v35 offset0:16 offset1:24
	ds_read2_b32 v[74:75], v35 offset0:82 offset1:90
	ds_read2_b32 v[76:77], v35 offset0:115 offset1:123
	ds_read2_b32 v[78:79], v35 offset0:148 offset1:156
	ds_read2_b32 v[80:81], v35 offset0:181 offset1:189
	ds_read2_b32 v[82:83], v35 offset0:214 offset1:222
	ds_read2_b32 v[84:85], v35 offset0:247 offset1:255
	s_waitcnt lgkmcnt(14)
	v_cvt_pk_bf16_f32 v2, v24, v4
	s_waitcnt lgkmcnt(12)
	v_cvt_pk_bf16_f32 v3, v26, v52
	v_cvt_pk_bf16_f32 v24, v25, v5
	s_waitcnt lgkmcnt(10)
	v_cvt_pk_bf16_f32 v4, v54, v56
	s_waitcnt lgkmcnt(8)
	v_cvt_pk_bf16_f32 v5, v58, v68
	v_cvt_pk_bf16_f32 v25, v27, v53
	v_cvt_pk_bf16_f32 v26, v55, v57
	v_cvt_pk_bf16_f32 v27, v59, v69
	s_waitcnt lgkmcnt(6)
	v_cvt_pk_bf16_f32 v52, v72, v70
	s_waitcnt lgkmcnt(4)
	v_cvt_pk_bf16_f32 v53, v74, v76
	s_waitcnt lgkmcnt(2)
	v_cvt_pk_bf16_f32 v54, v78, v80
	s_waitcnt lgkmcnt(0)
	v_cvt_pk_bf16_f32 v55, v82, v84
	v_cvt_pk_bf16_f32 v56, v73, v71
	v_cvt_pk_bf16_f32 v57, v75, v77
	v_cvt_pk_bf16_f32 v58, v79, v81
	v_cvt_pk_bf16_f32 v59, v83, v85
	global_store_dwordx4 v[60:61], v[2:5], off
	global_store_dwordx4 v[62:63], v[24:27], off
	global_store_dwordx4 v[64:65], v[52:55], off
	global_store_dwordx4 v[66:67], v[56:59], off
	s_waitcnt lgkmcnt(0)

; #define LAS __attribute__((address_space(3)))
; template <int MODE>
; __device__ __forceinline__ void transpose_item(const float* W, int K, int Nsrc, const float* g, bf16_t* WT, LAS float* scr, int kb, int nb, int lane) {
;     ...
;     int src = nd;
;     if (MODE == 1) src = nd < 4096 ? nd : (nd < 7168 ? nd + 16 : (nd < 7184 ? nd - 7168 + 4096 : -1));
; #pragma unroll
;     for (int i = 0; i < 8; ++i) { const int kk = 8 * i + (lane >> 3); f32x4 v = {0.f, 0.f, 0.f, 0.f};
;         if (src >= 0) { v = *(const f32x4*)(W + (size_t)(k0 + kk) * Nsrc + src); if (g) v = v * g[k0 + kk]; }
;         LAS float* d = scr + kk * 33 + (lane & 7) * 4; d[0] = v[0]; d[1] = v[1]; d[2] = v[2]; d[3] = v[3]; }
.LBB0_54:
	s_or_saveexec_b64 s[40:41], s[0:1]
	v_cndmask_b32_e64 v2, 0, 1, s[36:37]
	s_lshl_b32 s38, s38, 6
	v_lshl_add_u64 v[24:25], v[10:11], 2, s[12:13]
	v_mov_b32_e32 v5, 0
	v_cmp_ne_u32_e64 s[0:1], 1, v2
	v_mov_b32_e32 v4, 0
	v_mov_b32_e32 v3, 0
	v_mov_b32_e32 v2, 0
	s_xor_b64 exec, exec, s[40:41]
	s_cbranch_execz .LBB0_59
	v_or_b32_e32 v26, s38, v8
	v_mad_i64_i32 v[2:3], s[52:53], v26, s49, v[24:25]
	flat_load_dwordx4 v[2:5], v[2:3] nt
	s_and_b64 vcc, exec, s[0:1]
	s_cbranch_vccnz .LBB0_57
	v_ashrrev_i32_e32 v27, 31, v26
	v_lshl_add_u64 v[26:27], v[26:27], 2, s[14:15]
	flat_load_dword v10, v[26:27]
	s_waitcnt vmcnt(0) lgkmcnt(0)
	v_pk_mul_f32 v[4:5], v[4:5], v[10:11] op_sel_hi:[1,0]
	v_pk_mul_f32 v[2:3], v[2:3], v[10:11] op_sel_hi:[1,0]
.LBB0_57:
	s_waitcnt vmcnt(0) lgkmcnt(0)
	ds_write2_b32 v36, v2, v3 offset1:1
	ds_write2_b32 v36, v4, v5 offset0:2 offset1:3
	v_or_b32_e32 v2, s38, v28
	v_mad_i64_i32 v[2:3], s[52:53], v2, s49, v[24:25]
	flat_load_dwordx4 v[2:5], v[2:3] nt
	s_and_b64 vcc, exec, s[0:1]
	s_cbranch_vccnz .LBB0_59
	s_ashr_i32 s39, s38, 31
	v_lshl_add_u64 v[26:27], s[38:39], 0, v[8:9]
	v_lshl_add_u64 v[26:27], v[26:27], 2, s[14:15]
	flat_load_dword v10, v[26:27] offset:32
	s_waitcnt vmcnt(0) lgkmcnt(0)
	v_pk_mul_f32 v[4:5], v[4:5], v[10:11] op_sel_hi:[1,0]
	v_pk_mul_f32 v[2:3], v[2:3], v[10:11] op_sel_hi:[1,0]

; #define LAS __attribute__((address_space(3)))
; template <int MODE>
; __device__ __forceinline__ void transpose_item(const float* W, int K, int Nsrc, const float* g, bf16_t* WT, LAS float* scr, int kb, int nb, int lane) {
;     ...
;     int src = nd;
;     if (MODE == 1) src = nd < 4096 ? nd : (nd < 7168 ? nd + 16 : (nd < 7184 ? nd - 7168 + 4096 : -1));
; #pragma unroll
;     for (int i = 0; i < 8; ++i) { const int kk = 8 * i + (lane >> 3); f32x4 v = {0.f, 0.f, 0.f, 0.f};
;         if (src >= 0) { v = *(const f32x4*)(W + (size_t)(k0 + kk) * Nsrc + src); if (g) v = v * g[k0 + kk]; }
;         LAS float* d = scr + kk * 33 + (lane & 7) * 4; d[0] = v[0]; d[1] = v[1]; d[2] = v[2]; d[3] = v[3]; }
.LBB0_61:
	s_or_saveexec_b64 s[40:41], s[40:41]
	v_mov_b32_e32 v5, 0
	v_mov_b32_e32 v4, 0
	v_mov_b32_e32 v3, 0
	v_mov_b32_e32 v2, 0
	s_xor_b64 exec, exec, s[40:41]
	s_cbranch_execz .LBB0_66
	v_or_b32_e32 v2, s38, v29
	v_mad_i64_i32 v[2:3], s[52:53], v2, s49, v[24:25]
	flat_load_dwordx4 v[2:5], v[2:3] nt
	s_and_b64 vcc, exec, s[0:1]
	s_cbranch_vccnz .LBB0_64
	s_ashr_i32 s39, s38, 31
	v_lshl_add_u64 v[26:27], s[38:39], 0, v[8:9]
	v_lshl_add_u64 v[26:27], v[26:27], 2, s[14:15]
	flat_load_dword v10, v[26:27] offset:64
	s_waitcnt vmcnt(0) lgkmcnt(0)
	v_pk_mul_f32 v[4:5], v[4:5], v[10:11] op_sel_hi:[1,0]
	v_pk_mul_f32 v[2:3], v[2:3], v[10:11] op_sel_hi:[1,0]
.LBB0_64:
	s_waitcnt vmcnt(0) lgkmcnt(0)
	ds_write2_b32 v39, v2, v3 offset1:1
	ds_write2_b32 v40, v4, v5 offset1:1
	v_or_b32_e32 v2, s38, v30
	v_mad_i64_i32 v[2:3], s[52:53], v2, s49, v[24:25]
	flat_load_dwordx4 v[2:5], v[2:3] nt
	s_and_b64 vcc, exec, s[0:1]
	s_cbranch_vccnz .LBB0_66
	s_ashr_i32 s39, s38, 31
	v_lshl_add_u64 v[26:27], s[38:39], 0, v[8:9]
	v_lshl_add_u64 v[26:27], v[26:27], 2, s[14:15]
	flat_load_dword v10, v[26:27] offset:96
	s_waitcnt vmcnt(0) lgkmcnt(0)
	v_pk_mul_f32 v[4:5], v[4:5], v[10:11] op_sel_hi:[1,0]
	v_pk_mul_f32 v[2:3], v[2:3], v[10:11] op_sel_hi:[1,0]

; #define LAS __attribute__((address_space(3)))
; template <int MODE>
; __device__ __forceinline__ void transpose_item(const float* W, int K, int Nsrc, const float* g, bf16_t* WT, LAS float* scr, int kb, int nb, int lane) {
;     ...
;     int src = nd;
;     if (MODE == 1) src = nd < 4096 ? nd : (nd < 7168 ? nd + 16 : (nd < 7184 ? nd - 7168 + 4096 : -1));
; #pragma unroll
;     for (int i = 0; i < 8; ++i) { const int kk = 8 * i + (lane >> 3); f32x4 v = {0.f, 0.f, 0.f, 0.f};
;         if (src >= 0) { v = *(const f32x4*)(W + (size_t)(k0 + kk) * Nsrc + src); if (g) v = v * g[k0 + kk]; }
;         LAS float* d = scr + kk * 33 + (lane & 7) * 4; d[0] = v[0]; d[1] = v[1]; d[2] = v[2]; d[3] = v[3]; }
.LBB0_68:
	s_or_saveexec_b64 s[40:41], s[40:41]
	v_mov_b32_e32 v5, 0
	v_mov_b32_e32 v4, 0
	v_mov_b32_e32 v3, 0
	v_mov_b32_e32 v2, 0
	s_xor_b64 exec, exec, s[40:41]
	s_cbranch_execz .LBB0_73
	v_or_b32_e32 v2, s38, v31
	v_mad_i64_i32 v[2:3], s[52:53], v2, s49, v[24:25]
	flat_load_dwordx4 v[2:5], v[2:3] nt
	s_and_b64 vcc, exec, s[0:1]
	s_cbranch_vccnz .LBB0_71
	s_ashr_i32 s39, s38, 31
	v_lshl_add_u64 v[26:27], s[38:39], 0, v[8:9]
	v_lshl_add_u64 v[26:27], v[26:27], 2, s[14:15]
	flat_load_dword v10, v[26:27] offset:128
	s_waitcnt vmcnt(0) lgkmcnt(0)
	v_pk_mul_f32 v[4:5], v[4:5], v[10:11] op_sel_hi:[1,0]
	v_pk_mul_f32 v[2:3], v[2:3], v[10:11] op_sel_hi:[1,0]
.LBB0_71:
	s_waitcnt vmcnt(0) lgkmcnt(0)
	ds_write2_b32 v43, v2, v3 offset1:1
	ds_write2_b32 v44, v4, v5 offset1:1
	v_or_b32_e32 v2, s38, v32
	v_mad_i64_i32 v[2:3], s[52:53], v2, s49, v[24:25]
	flat_load_dwordx4 v[2:5], v[2:3] nt
	s_and_b64 vcc, exec, s[0:1]
	s_cbranch_vccnz .LBB0_73
	s_ashr_i32 s39, s38, 31
	v_lshl_add_u64 v[26:27], s[38:39], 0, v[8:9]
	v_lshl_add_u64 v[26:27], v[26:27], 2, s[14:15]
	flat_load_dword v10, v[26:27] offset:160
	s_waitcnt vmcnt(0) lgkmcnt(0)
	v_pk_mul_f32 v[4:5], v[4:5], v[10:11] op_sel_hi:[1,0]
	v_pk_mul_f32 v[2:3], v[2:3], v[10:11] op_sel_hi:[1,0]

; #define LAS __attribute__((address_space(3)))
; template <int MODE>
; __device__ __forceinline__ void transpose_item(const float* W, int K, int Nsrc, const float* g, bf16_t* WT, LAS float* scr, int kb, int nb, int lane) {
;     ...
;     int src = nd;
;     if (MODE == 1) src = nd < 4096 ? nd : (nd < 7168 ? nd + 16 : (nd < 7184 ? nd - 7168 + 4096 : -1));
; #pragma unroll
;     for (int i = 0; i < 8; ++i) { const int kk = 8 * i + (lane >> 3); f32x4 v = {0.f, 0.f, 0.f, 0.f};
;         if (src >= 0) { v = *(const f32x4*)(W + (size_t)(k0 + kk) * Nsrc + src); if (g) v = v * g[k0 + kk]; }
;         LAS float* d = scr + kk * 33 + (lane & 7) * 4; d[0] = v[0]; d[1] = v[1]; d[2] = v[2]; d[3] = v[3]; }
.LBB0_75:
	s_or_saveexec_b64 s[4:5], s[4:5]
	v_mov_b32_e32 v5, 0
	v_mov_b32_e32 v4, 0
	v_mov_b32_e32 v3, 0
	v_mov_b32_e32 v2, 0
	s_xor_b64 exec, exec, s[4:5]
	s_cbranch_execz .LBB0_10
	v_or_b32_e32 v2, s38, v33
	v_mad_i64_i32 v[2:3], s[40:41], v2, s49, v[24:25]
	flat_load_dwordx4 v[2:5], v[2:3] nt
	s_and_b64 vcc, exec, s[0:1]
	s_cbranch_vccnz .LBB0_78
	s_ashr_i32 s39, s38, 31
	v_lshl_add_u64 v[26:27], s[38:39], 0, v[8:9]
	v_lshl_add_u64 v[26:27], v[26:27], 2, s[14:15]
	flat_load_dword v10, v[26:27] offset:192
	s_waitcnt vmcnt(0) lgkmcnt(0)
	v_pk_mul_f32 v[4:5], v[4:5], v[10:11] op_sel_hi:[1,0]
	v_pk_mul_f32 v[2:3], v[2:3], v[10:11] op_sel_hi:[1,0]
.LBB0_78:
	s_waitcnt vmcnt(0) lgkmcnt(0)
	ds_write2_b32 v47, v2, v3 offset1:1
	ds_write2_b32 v48, v4, v5 offset1:1
	v_or_b32_e32 v2, s38, v34
	v_mad_i64_i32 v[2:3], s[40:41], v2, s49, v[24:25]
	flat_load_dwordx4 v[2:5], v[2:3] nt
	s_and_b64 vcc, exec, s[0:1]
	s_cbranch_vccnz .LBB0_10
	s_ashr_i32 s39, s38, 31
	v_lshl_add_u64 v[24:25], s[38:39], 0, v[8:9]
	v_lshl_add_u64 v[24:25], v[24:25], 2, s[14:15]
	flat_load_dword v10, v[24:25] offset:224
	s_waitcnt vmcnt(0) lgkmcnt(0)
	v_pk_mul_f32 v[4:5], v[4:5], v[10:11] op_sel_hi:[1,0]
	v_pk_mul_f32 v[2:3], v[2:3], v[10:11] op_sel_hi:[1,0]
	s_branch .LBB0_10

; __device__ __forceinline__ void gla_vt_item(const Ctx& P, int wi, int lane) {
;     const int eg = wi & 3, h = (wi >> 2) & 3, c = (wi >> 4) % NCH, b = wi / (16 * NCH);
;     const int L = c == 0 ? 16 : 64, t0 = c == 0 ? 0 : 16 + 64 * (c - 1), row0 = b * TP + t0, e = eg * 64 + lane;
;     const bf16_t* Z = (const bf16_t*)(P.ws + WS_Z);
;     bf16_t* VT = (bf16_t*)(P.ws + WS_VT) + (((size_t)b * NCH + c) * 4 + h) * 16384;
;     unsigned v[64];
; #pragma unroll
;     for (int t = 0; t < 64; ++t) v[t] = t < L ? (unsigned)Z[(size_t)(row0 + t) * NZ + ZC_V + h * 256 + e] : 0u;
.LBB0_211:
	s_not_b32 s0, s42
	s_add_i32 s4, s29, s0
	s_and_b64 s[0:1], s[12:13], exec
	s_cselect_b32 s0, s42, s4
	v_readlane_b32 s1, v250, 0
	s_mul_i32 s45, s0, s1
	s_add_i32 s45, s45, s28
	s_cmpk_gt_i32 s45, 0x107f
	s_mov_b64 s[0:1], -1
	s_cbranch_scc0 .LBB0_338
	s_cmpk_gt_u32 s45, 0x18bf
	s_cbranch_scc0 .LBB0_264
	s_add_i32 s0, s45, 0xffffe740
	s_lshr_b32 s1, s0, 4
	s_mul_hi_u32 s5, s1, 0xf83e0f9
	s_lshr_b32 s5, s5, 1
	s_mul_i32 s5, s5, 33
	s_mul_hi_u32 s0, s0, 0x3e0f83e1
	s_bfe_u32 s4, s45, 0x20002
	s_sub_i32 s5, s1, s5
	s_lshr_b32 s14, s0, 7
	s_cmp_lg_u32 s5, 0
	s_cselect_b64 s[0:1], -1, 0
	s_lshl_b32 s15, s5, 6
	s_sub_i32 s15, s15, 48
	s_cmp_eq_u32 s5, 0
	s_cselect_b64 s[22:23], -1, 0
	s_and_b64 vcc, s[22:23], exec
	s_cselect_b32 s15, 0, s15
	s_mul_i32 s22, s14, 0x810
	s_lshl_b32 s30, s4, 9
	s_add_i32 s15, s15, s22
	v_lshl_add_u64 v[2:3], v[74:75], 0, s[30:31]
	v_mad_i64_i32 v[4:5], s[22:23], s15, v194, v[2:3]
	s_or_b32 s22, s15, 1
	global_load_ushort v0, v[4:5], off nt
	v_mad_i64_i32 v[4:5], s[22:23], s22, v194, v[2:3]
	s_or_b32 s22, s15, 2
	s_nop 0
	v_mad_i64_i32 v[6:7], s[22:23], s22, v194, v[2:3]
	s_or_b32 s22, s15, 3
	global_load_ushort v4, v[4:5], off nt
	v_mov_b32_e32 v20, 0
	global_load_ushort v5, v[6:7], off nt
	v_mad_i64_i32 v[6:7], s[22:23], s22, v194, v[2:3]
	s_or_b32 s22, s15, 4
	s_nop 0
	v_mad_i64_i32 v[8:9], s[22:23], s22, v194, v[2:3]
	s_or_b32 s22, s15, 5
	global_load_ushort v6, v[6:7], off nt
	s_nop 0
	global_load_ushort v7, v[8:9], off nt
	v_mad_i64_i32 v[8:9], s[22:23], s22, v194, v[2:3]
	s_or_b32 s22, s15, 6
	s_nop 0
	v_mad_i64_i32 v[10:11], s[22:23], s22, v194, v[2:3]
	s_or_b32 s22, s15, 7
	global_load_ushort v8, v[8:9], off nt
	s_nop 0
	global_load_ushort v9, v[10:11], off nt
	v_mad_i64_i32 v[10:11], s[22:23], s22, v194, v[2:3]
	s_or_b32 s22, s15, 8
	s_nop 0
	v_mad_i64_i32 v[12:13], s[22:23], s22, v194, v[2:3]
	s_or_b32 s22, s15, 9
	global_load_ushort v11, v[10:11], off nt
	s_nop 0
	global_load_ushort v10, v[12:13], off nt
	v_mad_i64_i32 v[12:13], s[22:23], s22, v194, v[2:3]
	s_or_b32 s22, s15, 10
	s_waitcnt lgkmcnt(0)
	v_mad_i64_i32 v[14:15], s[22:23], s22, v194, v[2:3]
	s_or_b32 s22, s15, 11
	global_load_ushort v12, v[12:13], off nt
	s_nop 0
	global_load_ushort v13, v[14:15], off nt
	v_mad_i64_i32 v[14:15], s[22:23], s22, v194, v[2:3]
	s_or_b32 s22, s15, 12
	s_nop 0
	v_mad_i64_i32 v[16:17], s[22:23], s22, v194, v[2:3]
	s_or_b32 s22, s15, 13
	global_load_ushort v14, v[14:15], off nt
	s_nop 0
	global_load_ushort v15, v[16:17], off nt
	v_mad_i64_i32 v[16:17], s[22:23], s22, v194, v[2:3]
	s_or_b32 s22, s15, 14
	s_nop 0
	v_mad_i64_i32 v[18:19], s[22:23], s22, v194, v[2:3]
	s_or_b32 s22, s15, 15
	global_load_ushort v16, v[16:17], off nt
	s_nop 0
	global_load_ushort v17, v[18:19], off nt
	v_mad_i64_i32 v[18:19], s[22:23], s22, v194, v[2:3]
	global_load_ushort v19, v[18:19], off nt
	v_mov_b32_e32 v18, 0
	s_cbranch_vccnz .LBB0_215
	s_add_i32 s22, s15, 16
	v_mad_i64_i32 v[20:21], s[22:23], s22, v194, v[2:3]
	global_load_ushort v20, v[20:21], off nt

; __device__ __forceinline__ void gla_vt_item(const Ctx& P, int wi, int lane) {
;     ...
;     for (int t = 0; t < 64; ++t) v[t] = t < L ? (unsigned)Z[(size_t)(row0 + t) * NZ + ZC_V + h * 256 + e] : 0u;
.LBB0_262:
	s_add_i32 s15, s15, 63
	v_mad_u64_u32 v[2:3], s[0:1], s15, v194, v[2:3]
	global_load_ushort v66, v[2:3], off nt

; __device__ __forceinline__ void gla_qk_item(const Ctx& P, int l, int wi, LAS unsigned char* wl, int lane) {
;     ...
;     for (int hf = 0; hf < 2; ++hf) { unsigned qr[32], kr[32];
; #pragma unroll
;         for (int i = 0; i < 32; ++i) { const int t = hf * 32 + i; qr[i] = 0u; kr[i] = 0u;
;             if (t < L) { qr[i] = Z[(size_t)(row0 + t) * NZ + ZC_Q + col]; kr[i] = Z[(size_t)(row0 + t) * NZ + ZC_K + col]; } }
.LBB0_273:
	s_lshl_b32 s4, s30, 5
	v_mov_b32_e32 v71, 0
	s_cmp_ge_u32 s4, s38
	v_lshlrev_b32_e32 v0, 1, v41
	v_mov_b32_e32 v67, 0
	v_mov_b32_e32 v36, 0
	s_cbranch_scc1 .LBB0_275
	s_add_i32 s5, s4, s39
	s_mul_hi_i32 s47, s5, 0x3a00
	s_mulk_i32 s5, 0x3a00
	s_add_u32 s46, s16, s5
	s_addc_u32 s47, s17, s47
	v_lshl_add_u64 v[6:7], s[46:47], 0, v[0:1]
	v_add_co_u32_e32 v6, vcc, 0x1000, v6
	s_nop 1
	v_addc_co_u32_e32 v7, vcc, 0, v7, vcc
	global_load_ushort v67, v[6:7], off nt
	s_nop 0
	global_load_ushort v36, v[6:7], off offset:1024 nt
.LBB0_275:
	s_or_b32 s83, s4, 1
	s_cmp_ge_u32 s83, s38
	v_mov_b32_e32 v37, 0
	s_cbranch_scc1 .LBB0_277
	s_add_i32 s5, s83, s39
	s_mul_hi_i32 s47, s5, 0x3a00
	s_mulk_i32 s5, 0x3a00
	s_add_u32 s46, s16, s5
	s_addc_u32 s47, s17, s47
	v_lshl_add_u64 v[6:7], s[46:47], 0, v[0:1]
	v_add_co_u32_e32 v6, vcc, 0x1000, v6
	s_nop 1
	v_addc_co_u32_e32 v7, vcc, 0, v7, vcc
	global_load_ushort v71, v[6:7], off nt
	s_nop 0
	global_load_ushort v37, v[6:7], off offset:1024 nt
.LBB0_277:
	s_or_b32 s82, s4, 2
	v_mov_b32_e32 v69, 0
	s_cmp_ge_u32 s82, s38
	v_mov_b32_e32 v70, 0
	v_mov_b32_e32 v34, 0
	s_cbranch_scc1 .LBB0_279
	s_add_i32 s5, s82, s39
	s_mul_hi_i32 s47, s5, 0x3a00
	s_mulk_i32 s5, 0x3a00
	s_add_u32 s46, s16, s5
	s_addc_u32 s47, s17, s47
	v_lshl_add_u64 v[6:7], s[46:47], 0, v[0:1]
	v_add_co_u32_e32 v6, vcc, 0x1000, v6
	s_nop 1
	v_addc_co_u32_e32 v7, vcc, 0, v7, vcc
	global_load_ushort v70, v[6:7], off nt
	s_nop 0
	global_load_ushort v34, v[6:7], off offset:1024 nt
.LBB0_279:
	s_or_b32 s81, s4, 3
	s_cmp_ge_u32 s81, s38
	v_mov_b32_e32 v35, 0
	s_cbranch_scc1 .LBB0_281
	s_add_i32 s5, s81, s39
	s_mul_hi_i32 s47, s5, 0x3a00
	s_mulk_i32 s5, 0x3a00
	s_add_u32 s46, s16, s5
	s_addc_u32 s47, s17, s47
	v_lshl_add_u64 v[6:7], s[46:47], 0, v[0:1]
	v_add_co_u32_e32 v6, vcc, 0x1000, v6
	s_nop 1
	v_addc_co_u32_e32 v7, vcc, 0, v7, vcc
	global_load_ushort v69, v[6:7], off nt
	s_nop 0
	global_load_ushort v35, v[6:7], off offset:1024 nt
.LBB0_281:
	s_or_b32 s80, s4, 4
	v_mov_b32_e32 v38, 0
	s_cmp_ge_u32 s80, s38
	v_mov_b32_e32 v68, 0
	v_mov_b32_e32 v32, 0
	s_cbranch_scc1 .LBB0_283
	s_add_i32 s5, s80, s39
	s_mul_hi_i32 s47, s5, 0x3a00
	s_mulk_i32 s5, 0x3a00
	s_add_u32 s46, s16, s5
	s_addc_u32 s47, s17, s47
	v_lshl_add_u64 v[6:7], s[46:47], 0, v[0:1]
	v_add_co_u32_e32 v6, vcc, 0x1000, v6
	s_nop 1
	v_addc_co_u32_e32 v7, vcc, 0, v7, vcc
	global_load_ushort v68, v[6:7], off nt
	s_nop 0
	global_load_ushort v32, v[6:7], off offset:1024 nt
.LBB0_283:
	s_or_b32 s79, s4, 5
	s_cmp_ge_u32 s79, s38
	v_mov_b32_e32 v33, 0
	s_cbranch_scc1 .LBB0_285
	s_add_i32 s5, s79, s39
	s_mul_hi_i32 s47, s5, 0x3a00
	s_mulk_i32 s5, 0x3a00
	s_add_u32 s46, s16, s5
	s_addc_u32 s47, s17, s47
	v_lshl_add_u64 v[6:7], s[46:47], 0, v[0:1]
	v_add_co_u32_e32 v6, vcc, 0x1000, v6
	s_nop 1
	v_addc_co_u32_e32 v7, vcc, 0, v7, vcc
	global_load_ushort v38, v[6:7], off nt
	s_nop 0
	global_load_ushort v33, v[6:7], off offset:1024 nt
.LBB0_285:
	s_or_b32 s78, s4, 6
	v_mov_b32_e32 v65, 0
	s_cmp_ge_u32 s78, s38
	v_mov_b32_e32 v39, 0
	v_mov_b32_e32 v30, 0
	s_cbranch_scc1 .LBB0_287
	s_add_i32 s5, s78, s39
	s_mul_hi_i32 s47, s5, 0x3a00
	s_mulk_i32 s5, 0x3a00
	s_add_u32 s46, s16, s5
	s_addc_u32 s47, s17, s47
	v_lshl_add_u64 v[6:7], s[46:47], 0, v[0:1]
	v_add_co_u32_e32 v6, vcc, 0x1000, v6
	s_nop 1
	v_addc_co_u32_e32 v7, vcc, 0, v7, vcc
	global_load_ushort v39, v[6:7], off nt
	s_nop 0
	global_load_ushort v30, v[6:7], off offset:1024 nt
.LBB0_287:
	s_or_b32 s77, s4, 7
	s_cmp_ge_u32 s77, s38
	v_mov_b32_e32 v31, 0
	s_cbranch_scc1 .LBB0_289
	s_add_i32 s5, s77, s39
	s_mul_hi_i32 s47, s5, 0x3a00
	s_mulk_i32 s5, 0x3a00
	s_add_u32 s46, s16, s5
	s_addc_u32 s47, s17, s47
	v_lshl_add_u64 v[6:7], s[46:47], 0, v[0:1]
	v_add_co_u32_e32 v6, vcc, 0x1000, v6
	s_nop 1
	v_addc_co_u32_e32 v7, vcc, 0, v7, vcc
	global_load_ushort v65, v[6:7], off nt
	s_nop 0
	global_load_ushort v31, v[6:7], off offset:1024 nt
.LBB0_289:
	s_or_b32 s76, s4, 8
	v_mov_b32_e32 v64, 0
	s_cmp_ge_u32 s76, s38
	v_mov_b32_e32 v66, 0
	v_mov_b32_e32 v28, 0
	s_cbranch_scc1 .LBB0_291
	s_add_i32 s5, s76, s39
	s_mul_hi_i32 s47, s5, 0x3a00
	s_mulk_i32 s5, 0x3a00
	s_add_u32 s46, s16, s5
	s_addc_u32 s47, s17, s47
	v_lshl_add_u64 v[6:7], s[46:47], 0, v[0:1]
	v_add_co_u32_e32 v6, vcc, 0x1000, v6
	s_nop 1
	v_addc_co_u32_e32 v7, vcc, 0, v7, vcc
	global_load_ushort v66, v[6:7], off nt
	s_nop 0
	global_load_ushort v28, v[6:7], off offset:1024 nt
.LBB0_291:
	s_or_b32 s75, s4, 9
	s_cmp_ge_u32 s75, s38
	v_mov_b32_e32 v29, 0
	s_cbranch_scc1 .LBB0_293
	s_add_i32 s5, s75, s39
	s_mul_hi_i32 s47, s5, 0x3a00
	s_mulk_i32 s5, 0x3a00
	s_add_u32 s46, s16, s5
	s_addc_u32 s47, s17, s47
	v_lshl_add_u64 v[6:7], s[46:47], 0, v[0:1]
	v_add_co_u32_e32 v6, vcc, 0x1000, v6
	s_nop 1
	v_addc_co_u32_e32 v7, vcc, 0, v7, vcc
	global_load_ushort v64, v[6:7], off nt
	s_nop 0
	global_load_ushort v29, v[6:7], off offset:1024 nt
.LBB0_293:
	s_or_b32 s74, s4, 10
	v_mov_b32_e32 v62, 0
	s_cmp_ge_u32 s74, s38
	v_mov_b32_e32 v63, 0
	s_waitcnt lgkmcnt(0)
	v_mov_b32_e32 v26, 0
	s_cbranch_scc1 .LBB0_295
	s_add_i32 s5, s74, s39
	s_mul_hi_i32 s47, s5, 0x3a00
	s_mulk_i32 s5, 0x3a00
	s_add_u32 s46, s16, s5
	s_addc_u32 s47, s17, s47
	v_lshl_add_u64 v[6:7], s[46:47], 0, v[0:1]
	v_add_co_u32_e32 v6, vcc, 0x1000, v6
	s_nop 1
	v_addc_co_u32_e32 v7, vcc, 0, v7, vcc
	global_load_ushort v63, v[6:7], off nt
	s_nop 0
	global_load_ushort v26, v[6:7], off offset:1024 nt
.LBB0_295:
	s_or_b32 s73, s4, 11
	s_cmp_ge_u32 s73, s38
	v_mov_b32_e32 v27, 0
	s_cbranch_scc1 .LBB0_297
	s_add_i32 s5, s73, s39
	s_mul_hi_i32 s47, s5, 0x3a00
	s_mulk_i32 s5, 0x3a00
	s_add_u32 s46, s16, s5
	s_addc_u32 s47, s17, s47
	v_lshl_add_u64 v[6:7], s[46:47], 0, v[0:1]
	v_add_co_u32_e32 v6, vcc, 0x1000, v6
	s_nop 1
	v_addc_co_u32_e32 v7, vcc, 0, v7, vcc
	global_load_ushort v62, v[6:7], off nt
	s_nop 0
	global_load_ushort v27, v[6:7], off offset:1024 nt
; __device__ __forceinline__ void gla_qk_item(const Ctx& P, int l, int wi, LAS unsigned char* wl, int lane) {
;     ...
;     for (int hf = 0; hf < 2; ++hf) { unsigned qr[32], kr[32];
; #pragma unroll
;         for (int i = 0; i < 32; ++i) { const int t = hf * 32 + i; qr[i] = 0u; kr[i] = 0u;
;             if (t < L) { qr[i] = Z[(size_t)(row0 + t) * NZ + ZC_Q + col]; kr[i] = Z[(size_t)(row0 + t) * NZ + ZC_K + col]; } }
.LBB0_297:
	s_or_b32 s72, s4, 12
	v_mov_b32_e32 v60, 0
	s_cmp_ge_u32 s72, s38
	v_mov_b32_e32 v61, 0
	v_mov_b32_e32 v24, 0
	s_cbranch_scc1 .LBB0_299
	s_add_i32 s5, s72, s39
	s_mul_hi_i32 s47, s5, 0x3a00
	s_mulk_i32 s5, 0x3a00
	s_add_u32 s46, s16, s5
	s_addc_u32 s47, s17, s47
	v_lshl_add_u64 v[6:7], s[46:47], 0, v[0:1]
	v_add_co_u32_e32 v6, vcc, 0x1000, v6
	s_nop 1
	v_addc_co_u32_e32 v7, vcc, 0, v7, vcc
	global_load_ushort v61, v[6:7], off nt
	s_nop 0
	global_load_ushort v24, v[6:7], off offset:1024 nt
.LBB0_299:
	s_or_b32 s71, s4, 13
	s_cmp_ge_u32 s71, s38
	v_mov_b32_e32 v25, 0
	s_cbranch_scc1 .LBB0_301
	s_add_i32 s5, s71, s39
	s_mul_hi_i32 s47, s5, 0x3a00
	s_mulk_i32 s5, 0x3a00
	s_add_u32 s46, s16, s5
	s_addc_u32 s47, s17, s47
	v_lshl_add_u64 v[6:7], s[46:47], 0, v[0:1]
	v_add_co_u32_e32 v6, vcc, 0x1000, v6
	s_nop 1
	v_addc_co_u32_e32 v7, vcc, 0, v7, vcc
	global_load_ushort v60, v[6:7], off nt
	s_nop 0
	global_load_ushort v25, v[6:7], off offset:1024 nt
.LBB0_301:
	s_or_b32 s70, s4, 14
	v_mov_b32_e32 v57, 0
	s_cmp_ge_u32 s70, s38
	v_mov_b32_e32 v59, 0
	v_mov_b32_e32 v22, 0
	s_cbranch_scc1 .LBB0_303
	s_add_i32 s5, s70, s39
	s_mul_hi_i32 s47, s5, 0x3a00
	s_mulk_i32 s5, 0x3a00
	s_add_u32 s46, s16, s5
	s_addc_u32 s47, s17, s47
	v_lshl_add_u64 v[6:7], s[46:47], 0, v[0:1]
	v_add_co_u32_e32 v6, vcc, 0x1000, v6
	s_nop 1
	v_addc_co_u32_e32 v7, vcc, 0, v7, vcc
	global_load_ushort v59, v[6:7], off nt
	s_nop 0
	global_load_ushort v22, v[6:7], off offset:1024 nt
.LBB0_303:
	s_or_b32 s69, s4, 15
	s_cmp_ge_u32 s69, s38
	v_mov_b32_e32 v23, 0
	s_cbranch_scc1 .LBB0_305
	s_add_i32 s5, s69, s39
	s_mul_hi_i32 s47, s5, 0x3a00
	s_mulk_i32 s5, 0x3a00
	s_add_u32 s46, s16, s5
	s_addc_u32 s47, s17, s47
	v_lshl_add_u64 v[6:7], s[46:47], 0, v[0:1]
	v_add_co_u32_e32 v6, vcc, 0x1000, v6
	s_nop 1
	v_addc_co_u32_e32 v7, vcc, 0, v7, vcc
	global_load_ushort v57, v[6:7], off nt
	s_nop 0
	global_load_ushort v23, v[6:7], off offset:1024 nt
.LBB0_305:
	s_or_b32 s68, s4, 16
	v_mov_b32_e32 v56, 0
	s_cmp_ge_u32 s68, s38
	v_mov_b32_e32 v58, 0
	v_mov_b32_e32 v20, 0
	s_cbranch_scc1 .LBB0_307
	s_add_i32 s5, s68, s39
	s_mul_hi_i32 s47, s5, 0x3a00
	s_mulk_i32 s5, 0x3a00
	s_add_u32 s46, s16, s5
	s_addc_u32 s47, s17, s47
	v_lshl_add_u64 v[6:7], s[46:47], 0, v[0:1]
	v_add_co_u32_e32 v6, vcc, 0x1000, v6
	s_nop 1
	v_addc_co_u32_e32 v7, vcc, 0, v7, vcc
	global_load_ushort v58, v[6:7], off nt
	s_nop 0
	global_load_ushort v20, v[6:7], off offset:1024 nt
.LBB0_307:
	s_or_b32 s63, s4, 17
	s_cmp_ge_u32 s63, s38
	v_mov_b32_e32 v21, 0
	s_cbranch_scc1 .LBB0_309
	s_add_i32 s5, s63, s39
	s_mul_hi_i32 s47, s5, 0x3a00
	s_mulk_i32 s5, 0x3a00
	s_add_u32 s46, s16, s5
	s_addc_u32 s47, s17, s47
	v_lshl_add_u64 v[6:7], s[46:47], 0, v[0:1]
	v_add_co_u32_e32 v6, vcc, 0x1000, v6
	s_nop 1
	v_addc_co_u32_e32 v7, vcc, 0, v7, vcc
	global_load_ushort v56, v[6:7], off nt
	s_nop 0
	global_load_ushort v21, v[6:7], off offset:1024 nt
.LBB0_309:
	s_or_b32 s61, s4, 18
	v_mov_b32_e32 v54, 0
	s_cmp_ge_u32 s61, s38
	v_mov_b32_e32 v55, 0
	v_mov_b32_e32 v18, 0
	s_cbranch_scc1 .LBB0_311
	s_add_i32 s5, s61, s39
	s_mul_hi_i32 s47, s5, 0x3a00
	s_mulk_i32 s5, 0x3a00
	s_add_u32 s46, s16, s5
	s_addc_u32 s47, s17, s47
	v_lshl_add_u64 v[6:7], s[46:47], 0, v[0:1]
	v_add_co_u32_e32 v6, vcc, 0x1000, v6
	s_nop 1
	v_addc_co_u32_e32 v7, vcc, 0, v7, vcc
	global_load_ushort v55, v[6:7], off nt
	s_nop 0
	global_load_ushort v18, v[6:7], off offset:1024 nt
.LBB0_311:
	s_or_b32 s60, s4, 19
	s_cmp_ge_u32 s60, s38
	v_mov_b32_e32 v19, 0
	s_cbranch_scc1 .LBB0_313
	s_add_i32 s5, s60, s39
	s_mul_hi_i32 s47, s5, 0x3a00
	s_mulk_i32 s5, 0x3a00
	s_add_u32 s46, s16, s5
	s_addc_u32 s47, s17, s47
	v_lshl_add_u64 v[6:7], s[46:47], 0, v[0:1]
	v_add_co_u32_e32 v6, vcc, 0x1000, v6
	s_nop 1
	v_addc_co_u32_e32 v7, vcc, 0, v7, vcc
	global_load_ushort v54, v[6:7], off nt
	s_nop 0
	global_load_ushort v19, v[6:7], off offset:1024 nt
.LBB0_313:
	s_or_b32 s57, s4, 20
	v_mov_b32_e32 v52, 0
	s_cmp_ge_u32 s57, s38
	v_mov_b32_e32 v53, 0
	v_mov_b32_e32 v16, 0
	s_cbranch_scc1 .LBB0_315
	s_add_i32 s5, s57, s39
	s_mul_hi_i32 s47, s5, 0x3a00
	s_mulk_i32 s5, 0x3a00
	s_add_u32 s46, s16, s5
	s_addc_u32 s47, s17, s47
	v_lshl_add_u64 v[6:7], s[46:47], 0, v[0:1]
	v_add_co_u32_e32 v6, vcc, 0x1000, v6
	s_nop 1
	v_addc_co_u32_e32 v7, vcc, 0, v7, vcc
	global_load_ushort v53, v[6:7], off nt
	s_nop 0
	global_load_ushort v16, v[6:7], off offset:1024 nt
.LBB0_315:
	s_or_b32 s56, s4, 21
	s_cmp_ge_u32 s56, s38
	v_mov_b32_e32 v17, 0
	s_cbranch_scc1 .LBB0_317
	s_add_i32 s5, s56, s39
	s_mul_hi_i32 s47, s5, 0x3a00
	s_mulk_i32 s5, 0x3a00
	s_add_u32 s46, s16, s5
	s_addc_u32 s47, s17, s47
	v_lshl_add_u64 v[6:7], s[46:47], 0, v[0:1]
	v_add_co_u32_e32 v6, vcc, 0x1000, v6
	s_nop 1
	v_addc_co_u32_e32 v7, vcc, 0, v7, vcc
	global_load_ushort v52, v[6:7], off nt
	s_nop 0
	global_load_ushort v17, v[6:7], off offset:1024 nt
; __device__ __forceinline__ void gla_qk_item(const Ctx& P, int l, int wi, LAS unsigned char* wl, int lane) {
;     ...
;     for (int hf = 0; hf < 2; ++hf) { unsigned qr[32], kr[32];
; #pragma unroll
;         for (int i = 0; i < 32; ++i) { const int t = hf * 32 + i; qr[i] = 0u; kr[i] = 0u;
;             if (t < L) { qr[i] = Z[(size_t)(row0 + t) * NZ + ZC_Q + col]; kr[i] = Z[(size_t)(row0 + t) * NZ + ZC_K + col]; } }
.LBB0_317:
	s_or_b32 s55, s4, 22
	v_mov_b32_e32 v49, 0
	s_cmp_ge_u32 s55, s38
	v_mov_b32_e32 v51, 0
	v_mov_b32_e32 v14, 0
	s_cbranch_scc1 .LBB0_319
	s_add_i32 s5, s55, s39
	s_mul_hi_i32 s47, s5, 0x3a00
	s_mulk_i32 s5, 0x3a00
	s_add_u32 s46, s16, s5
	s_addc_u32 s47, s17, s47
	v_lshl_add_u64 v[6:7], s[46:47], 0, v[0:1]
	v_add_co_u32_e32 v6, vcc, 0x1000, v6
	s_nop 1
	v_addc_co_u32_e32 v7, vcc, 0, v7, vcc
	global_load_ushort v51, v[6:7], off nt
	s_nop 0
	global_load_ushort v14, v[6:7], off offset:1024 nt
.LBB0_319:
	s_or_b32 s54, s4, 23
	s_cmp_ge_u32 s54, s38
	v_mov_b32_e32 v15, 0
	s_cbranch_scc1 .LBB0_321
	s_add_i32 s5, s54, s39
	s_mul_hi_i32 s47, s5, 0x3a00
	s_mulk_i32 s5, 0x3a00
	s_add_u32 s46, s16, s5
	s_addc_u32 s47, s17, s47
	v_lshl_add_u64 v[6:7], s[46:47], 0, v[0:1]
	v_add_co_u32_e32 v6, vcc, 0x1000, v6
	s_nop 1
	v_addc_co_u32_e32 v7, vcc, 0, v7, vcc
	global_load_ushort v49, v[6:7], off nt
	s_nop 0
	global_load_ushort v15, v[6:7], off offset:1024 nt
.LBB0_321:
	s_or_b32 s53, s4, 24
	v_mov_b32_e32 v48, 0
	s_cmp_ge_u32 s53, s38
	v_mov_b32_e32 v50, 0
	v_mov_b32_e32 v12, 0
	s_cbranch_scc1 .LBB0_323
	s_add_i32 s5, s53, s39
	s_mul_hi_i32 s47, s5, 0x3a00
	s_mulk_i32 s5, 0x3a00
	s_add_u32 s46, s16, s5
	s_addc_u32 s47, s17, s47
	v_lshl_add_u64 v[6:7], s[46:47], 0, v[0:1]
	v_add_co_u32_e32 v6, vcc, 0x1000, v6
	s_nop 1
	v_addc_co_u32_e32 v7, vcc, 0, v7, vcc
	global_load_ushort v50, v[6:7], off nt
	s_nop 0
	global_load_ushort v12, v[6:7], off offset:1024 nt
.LBB0_323:
	s_or_b32 s52, s4, 25
	s_cmp_ge_u32 s52, s38
	v_mov_b32_e32 v13, 0
	s_cbranch_scc1 .LBB0_325
	s_add_i32 s5, s52, s39
	s_mul_hi_i32 s47, s5, 0x3a00
	s_mulk_i32 s5, 0x3a00
	s_add_u32 s46, s16, s5
	s_addc_u32 s47, s17, s47
	v_lshl_add_u64 v[6:7], s[46:47], 0, v[0:1]
	v_add_co_u32_e32 v6, vcc, 0x1000, v6
	s_nop 1
	v_addc_co_u32_e32 v7, vcc, 0, v7, vcc
	global_load_ushort v48, v[6:7], off nt
	s_nop 0
	global_load_ushort v13, v[6:7], off offset:1024 nt
.LBB0_325:
	s_or_b32 s51, s4, 26
	v_mov_b32_e32 v46, 0
	s_cmp_ge_u32 s51, s38
	v_mov_b32_e32 v47, 0
	v_mov_b32_e32 v10, 0
	s_cbranch_scc1 .LBB0_327
	s_add_i32 s5, s51, s39
	s_mul_hi_i32 s47, s5, 0x3a00
	s_mulk_i32 s5, 0x3a00
	s_add_u32 s46, s16, s5
	s_addc_u32 s47, s17, s47
	v_lshl_add_u64 v[6:7], s[46:47], 0, v[0:1]
	v_add_co_u32_e32 v6, vcc, 0x1000, v6
	s_nop 1
	v_addc_co_u32_e32 v7, vcc, 0, v7, vcc
	global_load_ushort v47, v[6:7], off nt
	s_nop 0
	global_load_ushort v10, v[6:7], off offset:1024 nt
.LBB0_327:
	s_or_b32 s50, s4, 27
	s_cmp_ge_u32 s50, s38
	v_mov_b32_e32 v11, 0
	s_cbranch_scc1 .LBB0_329
	s_add_i32 s5, s50, s39
	s_mul_hi_i32 s47, s5, 0x3a00
	s_mulk_i32 s5, 0x3a00
	s_add_u32 s46, s16, s5
	s_addc_u32 s47, s17, s47
	v_lshl_add_u64 v[6:7], s[46:47], 0, v[0:1]
	v_add_co_u32_e32 v6, vcc, 0x1000, v6
	s_nop 1
	v_addc_co_u32_e32 v7, vcc, 0, v7, vcc
	global_load_ushort v46, v[6:7], off nt
	s_nop 0
	global_load_ushort v11, v[6:7], off offset:1024 nt
.LBB0_329:
	s_or_b32 s49, s4, 28
	v_mov_b32_e32 v44, 0
	s_cmp_ge_u32 s49, s38
	v_mov_b32_e32 v45, 0
	v_mov_b32_e32 v8, 0
	s_cbranch_scc1 .LBB0_331
	s_add_i32 s5, s49, s39
	s_mul_hi_i32 s47, s5, 0x3a00
	s_mulk_i32 s5, 0x3a00
	s_add_u32 s46, s16, s5
	s_addc_u32 s47, s17, s47
	v_lshl_add_u64 v[6:7], s[46:47], 0, v[0:1]
	v_add_co_u32_e32 v6, vcc, 0x1000, v6
	s_nop 1
	v_addc_co_u32_e32 v7, vcc, 0, v7, vcc
	global_load_ushort v45, v[6:7], off nt
	s_nop 0
	global_load_ushort v8, v[6:7], off offset:1024 nt
.LBB0_331:
	s_or_b32 s48, s4, 29
	s_cmp_ge_u32 s48, s38
	v_mov_b32_e32 v9, 0
	s_cbranch_scc1 .LBB0_333
	s_add_i32 s5, s48, s39
	s_mul_hi_i32 s47, s5, 0x3a00
	s_mulk_i32 s5, 0x3a00
	s_add_u32 s46, s16, s5
	s_addc_u32 s47, s17, s47
	v_lshl_add_u64 v[6:7], s[46:47], 0, v[0:1]
	v_add_co_u32_e32 v6, vcc, 0x1000, v6
	s_nop 1
	v_addc_co_u32_e32 v7, vcc, 0, v7, vcc
	global_load_ushort v44, v[6:7], off nt
	s_nop 0
	global_load_ushort v9, v[6:7], off offset:1024 nt
.LBB0_333:
	s_or_b32 s47, s4, 30
	v_mov_b32_e32 v42, 0
	s_cmp_ge_u32 s47, s38
	v_mov_b32_e32 v43, 0
	v_mov_b32_e32 v6, 0
	s_cbranch_scc1 .LBB0_335
	s_add_i32 s5, s47, s39
	s_mul_hi_i32 s46, s5, 0x3a00
	s_mulk_i32 s5, 0x3a00
	s_add_u32 s84, s16, s5
	s_addc_u32 s85, s17, s46
	v_lshl_add_u64 v[6:7], s[84:85], 0, v[0:1]
	v_add_co_u32_e32 v6, vcc, 0x1000, v6
	v_readlane_b32 s84, v250, 44
	s_nop 0
	v_addc_co_u32_e32 v7, vcc, 0, v7, vcc
	global_load_ushort v43, v[6:7], off nt
	s_nop 0
	global_load_ushort v6, v[6:7], off offset:1024 nt
.LBB0_335:
	s_or_b32 s46, s4, 31
	s_cmp_ge_u32 s46, s38
	v_mov_b32_e32 v7, 0
	s_cbranch_scc1 .LBB0_272
	s_add_i32 s4, s46, s39
	s_mul_hi_i32 s5, s4, 0x3a00
	s_mulk_i32 s4, 0x3a00
	s_add_u32 s4, s16, s4
	s_addc_u32 s5, s17, s5
	v_lshl_add_u64 v[72:73], s[4:5], 0, v[0:1]
	v_add_co_u32_e32 v72, vcc, 0x1000, v72
	s_nop 1
	v_addc_co_u32_e32 v73, vcc, 0, v73, vcc
	global_load_ushort v42, v[72:73], off nt
	s_nop 0
	global_load_ushort v7, v[72:73], off offset:1024 nt
	s_branch .LBB0_272

; #define LAS __attribute__((address_space(3)))
; __device__ __forceinline__ float bf2f(unsigned b) { return __uint_as_float(b << 16); }
; __device__ __forceinline__ float softplus_(float x) { return fmaxf(x, 0.f) + __logf(1.f + __expf(-fabsf(x))); }
; __device__ __forceinline__ void rg_load_const(const Ctx& P, int l, int ch, int nb, int lane, RgConst& c, bf16x8 (&bw)[2][4][2]) {
;     const float* p_cw = INP(P, 9);
;     c.cw0 = p_cw[(size_t)(l * 4 + 0) * D + ch]; c.cw1 = p_cw[(size_t)(l * 4 + 1) * D + ch]; c.cw2 = p_cw[(size_t)(l * 4 + 2) * D + ch]; c.cw3 = p_cw[(size_t)(l * 4 + 3) * D + ch];
;     c.cb = INP(P, 10)[l * D + ch]; c.ba = INP(P, 12)[l * D + ch]; c.bx = INP(P, 14)[l * D + ch]; c.sp8 = 8.f * softplus_(-INP(P, 15)[l * D + ch]);
;     const bf16_t* RGW = (const bf16_t*)(P.ws + WS_RGW);
;     const int fr = lane & 15, fq = lane >> 4;
; #pragma unroll
;     for (int g = 0; g < 2; ++g)
; #pragma unroll
;         for (int ct = 0; ct < 4; ++ct)
; #pragma unroll
;             for (int ks = 0; ks < 2; ++ks) bw[g][ct][ks] = *(const bf16x8*)(RGW + ((((size_t)l * 2 + g) * 16 + nb) * 64 + 16 * ct + fr) * 64 + ks * 32 + fq * 8);
; }
; __device__ __forceinline__ void rg_prompt_item(const Ctx& P, int l, int wi, LAS unsigned char* wl, int lane) {
;     const int nb = wi & 15, c = wi < 4096 ? 1 + ((wi >> 4) & 31) : 0, b = wi < 4096 ? wi >> 9 : (wi - 4096) >> 4;
;     const int L = c == 0 ? 16 : 64, t0 = c == 0 ? 0 : 16 + 64 * (c - 1), row0 = b * TP + t0, ch = nb * 64 + lane;
;     const bf16_t* Z = (const bf16_t*)(P.ws + WS_Z); bf16_t* HG = (bf16_t*)(P.ws + WS_HG); bf16_t* A2 = (bf16_t*)(P.ws + WS_T); float* CAR = (float*)(P.ws + WS_CARRY);
;     RgConst k; bf16x8 bw[2][4][2]; rg_load_const(P, l, ch, nb, lane, k, bw);
;     float xm3 = 0.f, xm2 = 0.f, xm1 = 0.f;
;     if (t0 > 0) { xm3 = bf2f(Z[(size_t)(row0 - 3) * NZ + ch]); xm2 = bf2f(Z[(size_t)(row0 - 2) * NZ + ch]); xm1 = bf2f(Z[(size_t)(row0 - 1) * NZ + ch]); }
.LBB0_338:
	s_andn2_b64 vcc, exec, s[0:1]
	s_cbranch_vccnz .LBB0_210
	s_bfe_u32 s0, s45, 0x50004
	s_add_i32 s4, s0, 1
	s_cmpk_gt_i32 s45, 0xfff
	s_cselect_b64 s[0:1], -1, 0
	s_and_b64 s[0:1], s[0:1], exec
	s_cselect_b32 s4, 0, s4
	s_lshl_b32 s0, s4, 6
	s_sub_i32 s5, s0, 48
	s_cmpk_gt_i32 s45, 0xfff
	s_cselect_b64 s[0:1], -1, 0
	s_and_b64 s[0:1], s[0:1], exec
	s_cselect_b32 s23, 0, s5
	s_add_i32 s0, s45, 0xfffff000
	s_ashr_i32 s5, s45, 9
	s_lshr_b32 s22, s0, 4
	s_cmpk_gt_i32 s45, 0xfff
	s_cselect_b64 s[0:1], -1, 0
	s_and_b64 s[14:15], s[0:1], exec
	v_readlane_b32 s15, v250, 15
	s_cselect_b32 s5, s22, s5
	s_mul_i32 s14, s5, 0x810
	v_mov_b32_e32 v0, s15
	ds_read2_b64 v[2:5], v0 offset1:1
	s_add_i32 s22, s23, s14
	s_lshl_b32 s14, s45, 6
	s_and_b32 s30, s14, 0x3c0
	v_readlane_b32 s14, v250, 16
	v_or_b32_e32 v110, s30, v83
	s_waitcnt lgkmcnt(0)
	v_readfirstlane_b32 s15, v3
	v_mov_b32_e32 v0, s14
	v_readfirstlane_b32 s14, v2
	s_add_u32 s14, s14, s40
	ds_read_b64 v[6:7], v0
	s_addc_u32 s15, s15, 0
	v_lshlrev_b32_e32 v0, 2, v110
	v_lshl_add_u64 v[2:3], s[14:15], 0, v[0:1]
	s_movk_i32 s38, 0x1000
	v_add_co_u32_e32 v8, vcc, s38, v2
	v_readfirstlane_b32 s15, v5
	s_nop 0
	v_addc_co_u32_e32 v9, vcc, 0, v3, vcc
	v_add_co_u32_e32 v10, vcc, s7, v2
	v_readfirstlane_b32 s14, v4
	s_nop 0
	v_addc_co_u32_e32 v11, vcc, 0, v3, vcc
	v_add_co_u32_e32 v12, vcc, s2, v2
	s_cmp_lt_i32 s23, 1
	s_nop 0
	v_addc_co_u32_e32 v13, vcc, 0, v3, vcc
	flat_load_dword v87, v[2:3]
	flat_load_dword v111, v[8:9]
	flat_load_dword v112, v[10:11]
	flat_load_dword v113, v[12:13]
	v_or_b32_e32 v2, s41, v110
	v_mov_b32_e32 v3, v1
	v_lshlrev_b64 v[8:9], 2, v[2:3]
	v_lshl_add_u64 v[2:3], s[14:15], 0, v[8:9]
	v_readlane_b32 s14, v250, 17
	flat_load_dword v114, v[2:3]
	s_waitcnt lgkmcnt(0)
	v_readfirstlane_b32 s15, v7
	v_mov_b32_e32 v2, s14
	ds_read_b128 v[2:5], v2
	v_readfirstlane_b32 s14, v6
	s_mul_i32 s23, s22, 0x3a00
	v_lshlrev_b32_e32 v84, 1, v110
	v_lshl_add_u64 v[6:7], s[14:15], 0, v[8:9]
	s_waitcnt lgkmcnt(0)
	v_readfirstlane_b32 s15, v3
	v_readfirstlane_b32 s14, v2
	flat_load_dword v115, v[6:7]
	s_nop 0
	v_lshl_add_u64 v[2:3], s[14:15], 0, v[8:9]
	v_readfirstlane_b32 s15, v5
	v_readfirstlane_b32 s14, v4
	flat_load_dword v116, v[2:3]
	s_nop 0
	v_lshl_add_u64 v[2:3], s[14:15], 0, v[8:9]
	flat_load_dword v66, v[2:3]
	v_or_b32_e32 v2, s30, v82
	v_mov_b32_e32 v3, v79
	v_lshlrev_b64 v[2:3], 7, v[2:3]
	v_lshl_add_u64 v[50:51], v[80:81], 0, v[2:3]
	v_add_co_u32_e32 v30, vcc, s38, v50
	s_mov_b32 s14, 0x20000
	s_nop 0
	v_addc_co_u32_e32 v31, vcc, 0, v51, vcc
	v_add_co_u32_e32 v46, vcc, s14, v50
	global_load_dwordx4 v[2:5], v[50:51], off
	global_load_dwordx4 v[6:9], v[50:51], off offset:64
	global_load_dwordx4 v[10:13], v[50:51], off offset:2048
	global_load_dwordx4 v[14:17], v[50:51], off offset:2112
	v_addc_co_u32_e32 v47, vcc, 0, v51, vcc
	v_add_co_u32_e32 v62, vcc, 0x21000, v50
	global_load_dwordx4 v[18:21], v[30:31], off
	global_load_dwordx4 v[22:25], v[30:31], off offset:64
	global_load_dwordx4 v[26:29], v[30:31], off offset:2048
	s_nop 0
	global_load_dwordx4 v[30:33], v[30:31], off offset:2112
	v_addc_co_u32_e32 v63, vcc, 0, v51, vcc
	global_load_dwordx4 v[34:37], v[46:47], off
	global_load_dwordx4 v[38:41], v[46:47], off offset:64
	global_load_dwordx4 v[42:45], v[46:47], off offset:2048
	s_nop 0
	global_load_dwordx4 v[46:49], v[46:47], off offset:2112
	s_nop 0
	global_load_dwordx4 v[50:53], v[62:63], off
	global_load_dwordx4 v[54:57], v[62:63], off offset:64
	global_load_dwordx4 v[58:61], v[62:63], off offset:2048
	s_nop 0
	global_load_dwordx4 v[62:65], v[62:63], off offset:2112
	s_mov_b32 s14, 0
	s_cbranch_scc1 .LBB0_341
	s_add_i32 s15, s22, -3
	s_add_i32 s30, s23, 0xffff5200
	s_mul_hi_i32 s15, s15, 0x3a00
	s_add_u32 s38, s16, s30
	s_addc_u32 s39, s17, s15
	s_add_i32 s15, s22, -2
	s_add_i32 s30, s23, 0xffff8c00
	s_mul_hi_i32 s15, s15, 0x3a00
	s_add_u32 s46, s16, s30
	s_addc_u32 s47, s17, s15
	global_load_ushort v67, v84, s[38:39] nt
	global_load_ushort v68, v84, s[46:47] nt
	s_add_i32 s15, s22, -1
	s_add_i32 s30, s23, 0xffffc600
	s_mul_hi_i32 s15, s15, 0x3a00
	s_add_u32 s38, s16, s30
	s_addc_u32 s39, s17, s15
	s_waitcnt vmcnt(0)
	v_lshlrev_b32_e32 v92, 16, v67
	global_load_ushort v67, v84, s[38:39] nt
	v_lshlrev_b32_e32 v93, 16, v68
	s_waitcnt vmcnt(0)
	v_lshlrev_b32_e32 v94, 16, v67
	s_branch .LBB0_342

; #define LAS __attribute__((address_space(3)))
; __device__ __forceinline__ float bf2f(unsigned b) { return __uint_as_float(b << 16); }
; __device__ __forceinline__ float softplus_(float x) { return fmaxf(x, 0.f) + __logf(1.f + __expf(-fabsf(x))); }
; __device__ __forceinline__ void rg_load_const(const Ctx& P, int l, int ch, int nb, int lane, RgConst& c, bf16x8 (&bw)[2][4][2]) {
;     ...
;     c.cb = INP(P, 10)[l * D + ch]; c.ba = INP(P, 12)[l * D + ch]; c.bx = INP(P, 14)[l * D + ch]; c.sp8 = 8.f * softplus_(-INP(P, 15)[l * D + ch]);
;     const bf16_t* RGW = (const bf16_t*)(P.ws + WS_RGW);
;     const int fr = lane & 15, fq = lane >> 4;
; #pragma unroll
;     for (int g = 0; g < 2; ++g)
; #pragma unroll
;         for (int ct = 0; ct < 4; ++ct)
; #pragma unroll
;             for (int ks = 0; ks < 2; ++ks) bw[g][ct][ks] = *(const bf16x8*)(RGW + ((((size_t)l * 2 + g) * 16 + nb) * 64 + 16 * ct + fr) * 64 + ks * 32 + fq * 8);
; }
; __device__ __forceinline__ void rg_prompt_item(const Ctx& P, int l, int wi, LAS unsigned char* wl, int lane) {
;     const int nb = wi & 15, c = wi < 4096 ? 1 + ((wi >> 4) & 31) : 0, b = wi < 4096 ? wi >> 9 : (wi - 4096) >> 4;
;     const int L = c == 0 ? 16 : 64, t0 = c == 0 ? 0 : 16 + 64 * (c - 1), row0 = b * TP + t0, ch = nb * 64 + lane;
;     const bf16_t* Z = (const bf16_t*)(P.ws + WS_Z); bf16_t* HG = (bf16_t*)(P.ws + WS_HG); bf16_t* A2 = (bf16_t*)(P.ws + WS_T); float* CAR = (float*)(P.ws + WS_CARRY);
;     RgConst k; bf16x8 bw[2][4][2]; rg_load_const(P, l, ch, nb, lane, k, bw);
;     float xm3 = 0.f, xm2 = 0.f, xm1 = 0.f;
;     if (t0 > 0) { xm3 = bf2f(Z[(size_t)(row0 - 3) * NZ + ch]); xm2 = bf2f(Z[(size_t)(row0 - 2) * NZ + ch]); xm1 = bf2f(Z[(size_t)(row0 - 1) * NZ + ch]); }
;     float h = 0.f, pacc = 1.f;
;     unsigned xr[16], yr[16];
; #pragma unroll
;     for (int i = 0; i < 16; ++i) { xr[i] = Z[(size_t)(row0 + i) * NZ + ch]; yr[i] = Z[(size_t)(row0 + i) * NZ + ZC_RGY + ch]; }
.LBB0_342:
	s_and_b64 s[0:1], s[0:1], exec
	s_mov_b32 s0, 0xbfb8aa3b
	s_waitcnt vmcnt(0) lgkmcnt(0)
	v_max_f32_e64 v67, -v66, -v66
	v_mul_f32_e64 v66, |v66|, s0
	v_exp_f32_e32 v66, v66
	s_mov_b32 s0, 0x3f317217
	s_cselect_b32 s15, 1, 4
	v_max_f32_e32 v67, 0, v67
	v_add_f32_e32 v66, 1.0, v66
	v_cmp_gt_f32_e32 vcc, s66, v66
	v_mov_b32_e32 v85, v1
	v_mov_b32_e32 v88, 0
	v_cndmask_b32_e64 v68, 0, 32, vcc
	v_ldexp_f32 v66, v66, v68
	v_log_f32_e32 v66, v66
	v_mov_b32_e32 v86, 1.0
	v_mul_f32_e32 v68, 0x3f317217, v66
	v_fma_f32 v68, v66, s0, -v68
	v_fmac_f32_e32 v68, 0x3377d1cf, v66
	s_mov_b32 s0, 0x7f800000
	v_fmac_f32_e32 v68, 0x3f317217, v66
	v_cmp_lt_f32_e64 s[0:1], |v66|, s0
	s_nop 1
	v_cndmask_b32_e64 v66, v66, v68, s[0:1]
	s_mul_hi_i32 s1, s22, 0x3a00
	s_add_u32 s0, s16, s23
	s_addc_u32 s1, s17, s1
	global_load_ushort v165, v84, s[0:1] nt
	global_load_ushort v89, v84, s[0:1] offset:2048 nt
	s_or_b32 s0, s22, 1
	s_mul_hi_i32 s1, s0, 0x3a00
	s_mulk_i32 s0, 0x3a00
	s_add_u32 s0, s16, s0
	s_addc_u32 s1, s17, s1
	global_load_ushort v168, v84, s[0:1] nt
	global_load_ushort v158, v84, s[0:1] offset:2048 nt
	s_or_b32 s0, s22, 2
	s_mul_hi_i32 s1, s0, 0x3a00
	s_mulk_i32 s0, 0x3a00
	s_add_u32 s0, s16, s0
	s_addc_u32 s1, s17, s1
	global_load_ushort v170, v84, s[0:1] nt
	global_load_ushort v159, v84, s[0:1] offset:2048 nt
	s_or_b32 s0, s22, 3
	s_mul_hi_i32 s1, s0, 0x3a00
	s_mulk_i32 s0, 0x3a00
	s_add_u32 s0, s16, s0
	s_addc_u32 s1, s17, s1
	global_load_ushort v174, v84, s[0:1] nt
	global_load_ushort v160, v84, s[0:1] offset:2048 nt
	s_or_b32 s0, s22, 4
	s_mul_hi_i32 s1, s0, 0x3a00
	s_mulk_i32 s0, 0x3a00
	s_add_u32 s0, s16, s0
	s_addc_u32 s1, s17, s1
	global_load_ushort v173, v84, s[0:1] nt
	global_load_ushort v161, v84, s[0:1] offset:2048 nt
	s_or_b32 s0, s22, 5
	s_mul_hi_i32 s1, s0, 0x3a00
	s_mulk_i32 s0, 0x3a00
	s_add_u32 s0, s16, s0
	s_addc_u32 s1, s17, s1
	global_load_ushort v172, v84, s[0:1] nt
	global_load_ushort v162, v84, s[0:1] offset:2048 nt
	s_or_b32 s0, s22, 6
	s_mul_hi_i32 s1, s0, 0x3a00
	s_mulk_i32 s0, 0x3a00
	s_add_u32 s0, s16, s0
	s_addc_u32 s1, s17, s1
	global_load_ushort v171, v84, s[0:1] nt
	global_load_ushort v163, v84, s[0:1] offset:2048 nt
	s_or_b32 s0, s22, 7
	s_mul_hi_i32 s1, s0, 0x3a00
	s_mulk_i32 s0, 0x3a00
	s_add_u32 s0, s16, s0
	s_addc_u32 s1, s17, s1
	global_load_ushort v169, v84, s[0:1] nt
	global_load_ushort v164, v84, s[0:1] offset:2048 nt
	s_or_b32 s0, s22, 8
	s_mul_hi_i32 s1, s0, 0x3a00
	s_mulk_i32 s0, 0x3a00
	s_add_u32 s0, s16, s0
	s_addc_u32 s1, s17, s1
	global_load_ushort v167, v84, s[0:1] nt
	global_load_ushort v166, v84, s[0:1] offset:2048 nt
	s_or_b32 s0, s22, 9
	s_mul_hi_i32 s1, s0, 0x3a00
	s_mulk_i32 s0, 0x3a00
	s_add_u32 s0, s16, s0
	s_addc_u32 s1, s17, s1
	global_load_ushort v103, v84, s[0:1] nt
	global_load_ushort v101, v84, s[0:1] offset:2048 nt
	s_or_b32 s0, s22, 10
	s_mul_hi_i32 s1, s0, 0x3a00
	s_mulk_i32 s0, 0x3a00
	s_add_u32 s0, s16, s0
	s_addc_u32 s1, s17, s1
	global_load_ushort v102, v84, s[0:1] nt
	global_load_ushort v100, v84, s[0:1] offset:2048 nt
	s_or_b32 s0, s22, 11
	s_mul_hi_i32 s1, s0, 0x3a00
	s_mulk_i32 s0, 0x3a00
	s_add_u32 s0, s16, s0
	s_addc_u32 s1, s17, s1
	global_load_ushort v99, v84, s[0:1] nt
	global_load_ushort v98, v84, s[0:1] offset:2048 nt
	s_or_b32 s0, s22, 12
	s_mul_hi_i32 s1, s0, 0x3a00
	s_mulk_i32 s0, 0x3a00
	s_add_u32 s0, s16, s0
	s_addc_u32 s1, s17, s1
	global_load_ushort v73, v84, s[0:1] nt
	global_load_ushort v72, v84, s[0:1] offset:2048 nt
	s_or_b32 s0, s22, 13
	s_mul_hi_i32 s1, s0, 0x3a00
	s_mulk_i32 s0, 0x3a00
	v_cndmask_b32_e32 v68, 0, v195, vcc
	s_add_u32 s0, s16, s0
	v_sub_f32_e32 v66, v66, v68
	s_addc_u32 s1, s17, s1
	v_add_f32_e32 v90, v67, v66
	global_load_ushort v66, v84, s[0:1] nt
	global_load_ushort v71, v84, s[0:1] offset:2048 nt
	s_or_b32 s0, s22, 14
	s_mul_hi_i32 s1, s0, 0x3a00
	s_mulk_i32 s0, 0x3a00
	s_add_u32 s0, s16, s0
	s_addc_u32 s1, s17, s1
	global_load_ushort v67, v84, s[0:1] nt
	global_load_ushort v70, v84, s[0:1] offset:2048 nt
	s_or_b32 s0, s22, 15
	s_mul_hi_i32 s1, s0, 0x3a00
	s_mulk_i32 s0, 0x3a00
	s_add_u32 s0, s16, s0
	s_addc_u32 s1, s17, s1
	global_load_ushort v69, v84, s[0:1] nt
	global_load_ushort v68, v84, s[0:1] offset:2048 nt
	v_mul_f32_e32 v95, 0xc1000000, v90
	v_lshl_add_u64 v[90:91], s[16:17], 0, v[84:85]
	s_add_i32 s22, s22, 31
	s_waitcnt vmcnt(30)
	v_mov_b32_e32 v85, v89
	s_waitcnt vmcnt(28)
	v_mov_b32_e32 v117, v158
	s_waitcnt vmcnt(26)
	v_mov_b32_e32 v119, v159
	s_waitcnt vmcnt(24)
	v_mov_b32_e32 v122, v160
	v_mov_b32_e32 v118, v165
	v_mov_b32_e32 v120, v168
	v_mov_b32_e32 v121, v170
	s_waitcnt vmcnt(22)
	v_mov_b32_e32 v123, v161
	v_mov_b32_e32 v124, v174
	v_mov_b32_e32 v126, v173
	s_waitcnt vmcnt(21)
	v_mov_b32_e32 v128, v172
	s_waitcnt vmcnt(20)
	v_mov_b32_e32 v125, v162
	s_waitcnt vmcnt(19)
	v_mov_b32_e32 v129, v171
	s_waitcnt vmcnt(18)
	v_mov_b32_e32 v127, v163
	s_waitcnt vmcnt(17)
	v_mov_b32_e32 v144, v169
	s_waitcnt vmcnt(16)
	v_mov_b32_e32 v142, v164
	s_waitcnt vmcnt(15)
	v_mov_b32_e32 v146, v167
	s_waitcnt vmcnt(14)
	v_mov_b32_e32 v143, v166
	s_waitcnt vmcnt(13)
	v_mov_b32_e32 v148, v103
	s_waitcnt vmcnt(12)
	v_mov_b32_e32 v145, v101
	s_waitcnt vmcnt(11)
	v_mov_b32_e32 v149, v102
	s_waitcnt vmcnt(10)
	v_mov_b32_e32 v147, v100
	s_waitcnt vmcnt(9)
	v_mov_b32_e32 v152, v99
	s_waitcnt vmcnt(8)
	v_mov_b32_e32 v150, v98
	s_waitcnt vmcnt(7)
	v_mov_b32_e32 v154, v73
	s_waitcnt vmcnt(6)
	v_mov_b32_e32 v151, v72
	s_waitcnt vmcnt(4)
	v_mov_b32_e32 v153, v71
	s_waitcnt vmcnt(3)
	v_mov_b64_e32 v[96:97], v[66:67]
	s_waitcnt vmcnt(2)
	v_mov_b32_e32 v155, v70
	s_waitcnt vmcnt(1)
	v_mov_b32_e32 v157, v69
	s_waitcnt vmcnt(0)
	v_mov_b32_e32 v156, v68
	s_add_i32 s14, s14, 1
	s_cmp_ge_u32 s14, s15
	s_cbranch_scc1 .LBB0_344
; __device__ __forceinline__ void rg_prompt_item(const Ctx& P, int l, int wi, LAS unsigned char* wl, int lane) {
;     ...
;         if (sub + 1 < L / 16) {
; #pragma unroll
;             for (int i = 0; i < 16; ++i) { xr[i] = Z[(size_t)(r0 + 16 + i) * NZ + ch]; yr[i] = Z[(size_t)(r0 + 16 + i) * NZ + ZC_RGY + ch]; } }
.LBB0_343:
	s_add_i32 s0, s22, -15
	v_mad_i64_i32 v[96:97], s[0:1], s0, v194, v[90:91]
	s_add_i32 s0, s22, -14
	global_load_ushort v118, v[96:97], off nt
	global_load_ushort v85, v[96:97], off offset:2048 nt
	v_mad_i64_i32 v[96:97], s[0:1], s0, v194, v[90:91]
	s_add_i32 s0, s22, -13
	global_load_ushort v120, v[96:97], off nt
	global_load_ushort v117, v[96:97], off offset:2048 nt
	v_mad_i64_i32 v[96:97], s[0:1], s0, v194, v[90:91]
	s_add_i32 s0, s22, -12
	global_load_ushort v121, v[96:97], off nt
	global_load_ushort v119, v[96:97], off offset:2048 nt
	v_mad_i64_i32 v[96:97], s[0:1], s0, v194, v[90:91]
	s_add_i32 s0, s22, -11
	global_load_ushort v124, v[96:97], off nt
	global_load_ushort v122, v[96:97], off offset:2048 nt
	v_mad_i64_i32 v[96:97], s[0:1], s0, v194, v[90:91]
	s_add_i32 s0, s22, -10
	global_load_ushort v126, v[96:97], off nt
	global_load_ushort v123, v[96:97], off offset:2048 nt
	v_mad_i64_i32 v[96:97], s[0:1], s0, v194, v[90:91]
	s_add_i32 s0, s22, -9
	global_load_ushort v128, v[96:97], off nt
	global_load_ushort v125, v[96:97], off offset:2048 nt
	v_mad_i64_i32 v[96:97], s[0:1], s0, v194, v[90:91]
	s_add_i32 s0, s22, -8
	global_load_ushort v129, v[96:97], off nt
	global_load_ushort v127, v[96:97], off offset:2048 nt
	v_mad_i64_i32 v[96:97], s[0:1], s0, v194, v[90:91]
	s_add_i32 s0, s22, -7
	global_load_ushort v144, v[96:97], off nt
	global_load_ushort v142, v[96:97], off offset:2048 nt
	v_mad_i64_i32 v[96:97], s[0:1], s0, v194, v[90:91]
	s_add_i32 s0, s22, -6
	global_load_ushort v146, v[96:97], off nt
	global_load_ushort v143, v[96:97], off offset:2048 nt
	v_mad_i64_i32 v[96:97], s[0:1], s0, v194, v[90:91]
	s_add_i32 s0, s22, -5
	global_load_ushort v148, v[96:97], off nt
	global_load_ushort v145, v[96:97], off offset:2048 nt
	v_mad_i64_i32 v[96:97], s[0:1], s0, v194, v[90:91]
	s_add_i32 s0, s22, -4
	global_load_ushort v149, v[96:97], off nt
	global_load_ushort v147, v[96:97], off offset:2048 nt
	v_mad_i64_i32 v[96:97], s[0:1], s0, v194, v[90:91]
	s_add_i32 s0, s22, -3
	global_load_ushort v152, v[96:97], off nt
	global_load_ushort v150, v[96:97], off offset:2048 nt
	v_mad_i64_i32 v[96:97], s[0:1], s0, v194, v[90:91]
	s_add_i32 s0, s22, -2
	s_nop 0
	v_mad_i64_i32 v[156:157], s[0:1], s0, v194, v[90:91]
	s_add_i32 s0, s22, -1
	global_load_ushort v154, v[96:97], off nt
	global_load_ushort v151, v[96:97], off offset:2048 nt
	s_nop 0
	global_load_ushort v96, v[156:157], off nt
	global_load_ushort v153, v[156:157], off offset:2048 nt
	v_mad_i64_i32 v[156:157], s[0:1], s0, v194, v[90:91]
	v_mad_i64_i32 v[176:177], s[0:1], s22, v194, v[90:91]
	global_load_ushort v97, v[156:157], off nt
	global_load_ushort v155, v[156:157], off offset:2048 nt
	s_nop 0
	global_load_ushort v157, v[176:177], off nt
	global_load_ushort v156, v[176:177], off offset:2048 nt

; __device__ __forceinline__ void gla_vt_item(const Ctx& P, int wi, int lane) {
;     ...
;     const int L = c == 0 ? 16 : 64, t0 = c == 0 ? 0 : 16 + 64 * (c - 1), row0 = b * TP + t0, e = eg * 64 + lane;
;     const bf16_t* Z = (const bf16_t*)(P.ws + WS_Z);
;     bf16_t* VT = (bf16_t*)(P.ws + WS_VT) + (((size_t)b * NCH + c) * 4 + h) * 16384;
;     unsigned v[64];
; #pragma unroll
;     for (int t = 0; t < 64; ++t) v[t] = t < L ? (unsigned)Z[(size_t)(row0 + t) * NZ + ZC_V + h * 256 + e] : 0u;
.LBB0_348:
	s_add_i32 s0, s15, 17
	v_mad_i64_i32 v[22:23], s[0:1], s0, v194, v[2:3]
	global_load_ushort v21, v[22:23], off nt
	s_and_b64 vcc, exec, s[38:39]
	s_cbranch_vccnz .LBB0_217
.LBB0_349:
	s_add_i32 s0, s15, 18
	v_mad_i64_i32 v[22:23], s[0:1], s0, v194, v[2:3]
	global_load_ushort v18, v[22:23], off nt
	v_mov_b32_e32 v22, 0
	s_and_b64 vcc, exec, s[38:39]
	v_mov_b32_e32 v23, 0
	s_cbranch_vccnz .LBB0_218
.LBB0_350:
	s_add_i32 s0, s15, 19
	v_mad_i64_i32 v[24:25], s[0:1], s0, v194, v[2:3]
	global_load_ushort v23, v[24:25], off nt
	s_and_b64 vcc, exec, s[38:39]
	s_cbranch_vccnz .LBB0_219
.LBB0_351:
	s_add_i32 s0, s15, 20
	v_mad_i64_i32 v[24:25], s[0:1], s0, v194, v[2:3]
	global_load_ushort v22, v[24:25], off nt
	v_mov_b32_e32 v24, 0
	s_and_b64 vcc, exec, s[38:39]
	v_mov_b32_e32 v25, 0
	s_cbranch_vccnz .LBB0_220
.LBB0_352:
	s_add_i32 s0, s15, 21
	v_mad_i64_i32 v[26:27], s[0:1], s0, v194, v[2:3]
	global_load_ushort v25, v[26:27], off nt
	s_and_b64 vcc, exec, s[38:39]
	s_cbranch_vccnz .LBB0_221
.LBB0_353:
	s_add_i32 s0, s15, 22
	v_mad_i64_i32 v[26:27], s[0:1], s0, v194, v[2:3]
	global_load_ushort v24, v[26:27], off nt
	v_mov_b32_e32 v26, 0
	s_and_b64 vcc, exec, s[38:39]
	v_mov_b32_e32 v27, 0
	s_cbranch_vccnz .LBB0_222
.LBB0_354:
	s_add_i32 s0, s15, 23
	v_mad_i64_i32 v[28:29], s[0:1], s0, v194, v[2:3]
	global_load_ushort v27, v[28:29], off nt
	s_and_b64 vcc, exec, s[38:39]
	s_cbranch_vccnz .LBB0_223
.LBB0_355:
	s_add_i32 s0, s15, 24
	v_mad_i64_i32 v[28:29], s[0:1], s0, v194, v[2:3]
	global_load_ushort v26, v[28:29], off nt
	v_mov_b32_e32 v28, 0
	s_and_b64 vcc, exec, s[38:39]
	v_mov_b32_e32 v29, 0
	s_cbranch_vccnz .LBB0_224
.LBB0_356:
	s_add_i32 s0, s15, 25
	v_mad_i64_i32 v[30:31], s[0:1], s0, v194, v[2:3]
	global_load_ushort v29, v[30:31], off nt
	s_and_b64 vcc, exec, s[38:39]
	s_cbranch_vccnz .LBB0_225
.LBB0_357:
	s_add_i32 s0, s15, 26
	v_mad_i64_i32 v[30:31], s[0:1], s0, v194, v[2:3]
	global_load_ushort v28, v[30:31], off nt
	v_mov_b32_e32 v30, 0
	s_and_b64 vcc, exec, s[38:39]
	v_mov_b32_e32 v31, 0
	s_cbranch_vccnz .LBB0_226
.LBB0_358:
	s_add_i32 s0, s15, 27
	v_mad_i64_i32 v[32:33], s[0:1], s0, v194, v[2:3]
	global_load_ushort v31, v[32:33], off nt
	s_and_b64 vcc, exec, s[38:39]
	s_cbranch_vccnz .LBB0_227
.LBB0_359:
	s_add_i32 s0, s15, 28
	v_mad_i64_i32 v[32:33], s[0:1], s0, v194, v[2:3]
	global_load_ushort v30, v[32:33], off nt
	v_mov_b32_e32 v32, 0
	s_and_b64 vcc, exec, s[38:39]
	v_mov_b32_e32 v33, 0
	s_cbranch_vccnz .LBB0_228
.LBB0_360:
	s_add_i32 s0, s15, 29
	v_mad_i64_i32 v[34:35], s[0:1], s0, v194, v[2:3]
	global_load_ushort v33, v[34:35], off nt
	s_and_b64 vcc, exec, s[38:39]
	s_cbranch_vccnz .LBB0_229
.LBB0_361:
	s_add_i32 s0, s15, 30
	v_mad_i64_i32 v[34:35], s[0:1], s0, v194, v[2:3]
	global_load_ushort v32, v[34:35], off nt
	v_mov_b32_e32 v34, 0
	s_and_b64 vcc, exec, s[38:39]
	v_mov_b32_e32 v35, 0
	s_cbranch_vccnz .LBB0_230
.LBB0_362:
	s_add_i32 s0, s15, 31
	v_mad_i64_i32 v[36:37], s[0:1], s0, v194, v[2:3]
	global_load_ushort v35, v[36:37], off nt
	s_and_b64 vcc, exec, s[38:39]
	s_cbranch_vccnz .LBB0_231
.LBB0_363:
	s_add_i32 s0, s15, 32
	v_mad_i64_i32 v[36:37], s[0:1], s0, v194, v[2:3]
	global_load_ushort v34, v[36:37], off nt
	v_mov_b32_e32 v36, 0
	s_and_b64 vcc, exec, s[38:39]
	v_mov_b32_e32 v37, 0
	s_cbranch_vccnz .LBB0_232
.LBB0_364:
	s_add_i32 s0, s15, 33
	v_mad_i64_i32 v[38:39], s[0:1], s0, v194, v[2:3]
	global_load_ushort v37, v[38:39], off nt
	s_and_b64 vcc, exec, s[38:39]
	s_cbranch_vccnz .LBB0_233
.LBB0_365:
	s_add_i32 s0, s15, 34
	v_mad_i64_i32 v[38:39], s[0:1], s0, v194, v[2:3]
	global_load_ushort v36, v[38:39], off nt
	v_mov_b32_e32 v38, 0
	s_and_b64 vcc, exec, s[38:39]
	v_mov_b32_e32 v39, 0
	s_cbranch_vccnz .LBB0_234
.LBB0_366:
	s_add_i32 s0, s15, 35
	v_mad_i64_i32 v[40:41], s[0:1], s0, v194, v[2:3]
	global_load_ushort v39, v[40:41], off nt
	s_and_b64 vcc, exec, s[38:39]
	s_cbranch_vccnz .LBB0_235
.LBB0_367:
	s_add_i32 s0, s15, 36
	v_mad_i64_i32 v[40:41], s[0:1], s0, v194, v[2:3]
	global_load_ushort v38, v[40:41], off nt
	v_mov_b32_e32 v40, 0
	s_and_b64 vcc, exec, s[38:39]
	v_mov_b32_e32 v41, 0
	s_cbranch_vccnz .LBB0_236
.LBB0_368:
	s_add_i32 s0, s15, 37
	v_mad_i64_i32 v[42:43], s[0:1], s0, v194, v[2:3]
	global_load_ushort v41, v[42:43], off nt
	s_and_b64 vcc, exec, s[38:39]
	s_cbranch_vccnz .LBB0_237
.LBB0_369:
	s_add_i32 s0, s15, 38
	v_mad_i64_i32 v[42:43], s[0:1], s0, v194, v[2:3]
	global_load_ushort v40, v[42:43], off nt
	v_mov_b32_e32 v42, 0
	s_and_b64 vcc, exec, s[38:39]
	v_mov_b32_e32 v43, 0
	s_cbranch_vccnz .LBB0_238
.LBB0_370:
	s_add_i32 s0, s15, 39
	v_mad_i64_i32 v[44:45], s[0:1], s0, v194, v[2:3]
	global_load_ushort v43, v[44:45], off nt
	s_and_b64 vcc, exec, s[38:39]
	s_cbranch_vccnz .LBB0_239
; __device__ __forceinline__ void gla_vt_item(const Ctx& P, int wi, int lane) {
;     ...
;     const int L = c == 0 ? 16 : 64, t0 = c == 0 ? 0 : 16 + 64 * (c - 1), row0 = b * TP + t0, e = eg * 64 + lane;
;     const bf16_t* Z = (const bf16_t*)(P.ws + WS_Z);
;     bf16_t* VT = (bf16_t*)(P.ws + WS_VT) + (((size_t)b * NCH + c) * 4 + h) * 16384;
;     unsigned v[64];
; #pragma unroll
;     for (int t = 0; t < 64; ++t) v[t] = t < L ? (unsigned)Z[(size_t)(row0 + t) * NZ + ZC_V + h * 256 + e] : 0u;
.LBB0_371:
	s_add_i32 s0, s15, 40
	v_mad_i64_i32 v[44:45], s[0:1], s0, v194, v[2:3]
	global_load_ushort v42, v[44:45], off nt
	v_mov_b32_e32 v44, 0
	s_and_b64 vcc, exec, s[38:39]
	v_mov_b32_e32 v45, 0
	s_cbranch_vccnz .LBB0_240
.LBB0_372:
	s_add_i32 s0, s15, 41
	v_mad_i64_i32 v[46:47], s[0:1], s0, v194, v[2:3]
	global_load_ushort v45, v[46:47], off nt
	s_and_b64 vcc, exec, s[38:39]
	s_cbranch_vccnz .LBB0_241
.LBB0_373:
	s_add_i32 s0, s15, 42
	v_mad_i64_i32 v[46:47], s[0:1], s0, v194, v[2:3]
	global_load_ushort v44, v[46:47], off nt
	v_mov_b32_e32 v46, 0
	s_and_b64 vcc, exec, s[38:39]
	v_mov_b32_e32 v47, 0
	s_cbranch_vccnz .LBB0_242
.LBB0_374:
	s_add_i32 s0, s15, 43
	v_mad_i64_i32 v[48:49], s[0:1], s0, v194, v[2:3]
	global_load_ushort v47, v[48:49], off nt
	s_and_b64 vcc, exec, s[38:39]
	s_cbranch_vccnz .LBB0_243
.LBB0_375:
	s_add_i32 s0, s15, 44
	v_mad_i64_i32 v[48:49], s[0:1], s0, v194, v[2:3]
	global_load_ushort v46, v[48:49], off nt
	v_mov_b32_e32 v48, 0
	s_and_b64 vcc, exec, s[38:39]
	v_mov_b32_e32 v49, 0
	s_cbranch_vccnz .LBB0_244
.LBB0_376:
	s_add_i32 s0, s15, 45
	v_mad_i64_i32 v[50:51], s[0:1], s0, v194, v[2:3]
	global_load_ushort v49, v[50:51], off nt
	s_and_b64 vcc, exec, s[38:39]
	s_cbranch_vccnz .LBB0_245
.LBB0_377:
	s_add_i32 s0, s15, 46
	v_mad_i64_i32 v[50:51], s[0:1], s0, v194, v[2:3]
	global_load_ushort v48, v[50:51], off nt
	v_mov_b32_e32 v50, 0
	s_and_b64 vcc, exec, s[38:39]
	v_mov_b32_e32 v51, 0
	s_cbranch_vccnz .LBB0_246
.LBB0_378:
	s_add_i32 s0, s15, 47
	v_mad_i64_i32 v[52:53], s[0:1], s0, v194, v[2:3]
	global_load_ushort v51, v[52:53], off nt
	s_and_b64 vcc, exec, s[38:39]
	s_cbranch_vccnz .LBB0_247
.LBB0_379:
	s_add_i32 s0, s15, 48
	v_mad_u64_u32 v[52:53], s[0:1], s0, v194, v[2:3]
	global_load_ushort v50, v[52:53], off nt
	v_mov_b32_e32 v52, 0
	s_and_b64 vcc, exec, s[38:39]
	v_mov_b32_e32 v53, 0
	s_cbranch_vccnz .LBB0_248
.LBB0_380:
	s_add_i32 s0, s15, 49
	v_mad_u64_u32 v[54:55], s[0:1], s0, v194, v[2:3]
	global_load_ushort v53, v[54:55], off nt
	s_and_b64 vcc, exec, s[38:39]
	s_cbranch_vccnz .LBB0_249
.LBB0_381:
	s_add_i32 s0, s15, 50
	v_mad_u64_u32 v[54:55], s[0:1], s0, v194, v[2:3]
	global_load_ushort v52, v[54:55], off nt
	v_mov_b32_e32 v54, 0
	s_and_b64 vcc, exec, s[38:39]
	v_mov_b32_e32 v55, 0
	s_cbranch_vccnz .LBB0_250
.LBB0_382:
	s_add_i32 s0, s15, 51
	v_mad_u64_u32 v[56:57], s[0:1], s0, v194, v[2:3]
	global_load_ushort v55, v[56:57], off nt
	s_and_b64 vcc, exec, s[38:39]
	s_cbranch_vccnz .LBB0_251
.LBB0_383:
	s_add_i32 s0, s15, 52
	v_mad_u64_u32 v[56:57], s[0:1], s0, v194, v[2:3]
	global_load_ushort v54, v[56:57], off nt
	v_mov_b32_e32 v56, 0
	s_and_b64 vcc, exec, s[38:39]
	v_mov_b32_e32 v57, 0
	s_cbranch_vccnz .LBB0_252
.LBB0_384:
	s_add_i32 s0, s15, 53
	v_mad_u64_u32 v[58:59], s[0:1], s0, v194, v[2:3]
	global_load_ushort v57, v[58:59], off nt
	s_and_b64 vcc, exec, s[38:39]
	s_cbranch_vccnz .LBB0_253
.LBB0_385:
	s_add_i32 s0, s15, 54
	v_mad_u64_u32 v[58:59], s[0:1], s0, v194, v[2:3]
	global_load_ushort v56, v[58:59], off nt
	v_mov_b32_e32 v58, 0
	s_and_b64 vcc, exec, s[38:39]
	v_mov_b32_e32 v59, 0
	s_cbranch_vccnz .LBB0_254
.LBB0_386:
	s_add_i32 s0, s15, 55
	v_mad_u64_u32 v[60:61], s[0:1], s0, v194, v[2:3]
	global_load_ushort v59, v[60:61], off nt
	s_and_b64 vcc, exec, s[38:39]
	s_cbranch_vccnz .LBB0_255
.LBB0_387:
	s_add_i32 s0, s15, 56
	v_mad_u64_u32 v[60:61], s[0:1], s0, v194, v[2:3]
	global_load_ushort v58, v[60:61], off nt
	v_mov_b32_e32 v60, 0
	s_and_b64 vcc, exec, s[38:39]
	v_mov_b32_e32 v61, 0
	s_cbranch_vccnz .LBB0_256
.LBB0_388:
	s_add_i32 s0, s15, 57
	v_mad_u64_u32 v[62:63], s[0:1], s0, v194, v[2:3]
	global_load_ushort v61, v[62:63], off nt
	s_and_b64 vcc, exec, s[38:39]
	s_cbranch_vccnz .LBB0_257
.LBB0_389:
	s_add_i32 s0, s15, 58
	v_mad_u64_u32 v[62:63], s[0:1], s0, v194, v[2:3]
	global_load_ushort v60, v[62:63], off nt
	v_mov_b32_e32 v62, 0
	s_and_b64 vcc, exec, s[38:39]
	v_mov_b32_e32 v63, 0
	s_cbranch_vccnz .LBB0_258
.LBB0_390:
	s_add_i32 s0, s15, 59
	v_mad_u64_u32 v[64:65], s[0:1], s0, v194, v[2:3]
	global_load_ushort v63, v[64:65], off nt
	s_and_b64 vcc, exec, s[38:39]
	s_cbranch_vccnz .LBB0_259
.LBB0_391:
	s_add_i32 s0, s15, 60
	v_mad_u64_u32 v[64:65], s[0:1], s0, v194, v[2:3]
	global_load_ushort v62, v[64:65], off nt
	v_mov_b32_e32 v64, 0
	s_and_b64 vcc, exec, s[38:39]
	v_mov_b32_e32 v65, 0
	s_cbranch_vccnz .LBB0_260
.LBB0_392:
	s_add_i32 s0, s15, 61
	v_mad_u64_u32 v[66:67], s[0:1], s0, v194, v[2:3]
	global_load_ushort v65, v[66:67], off nt
	s_and_b64 vcc, exec, s[38:39]
	s_cbranch_vccnz .LBB0_261
.LBB0_393:
	s_add_i32 s0, s15, 62
	v_mad_u64_u32 v[66:67], s[0:1], s0, v194, v[2:3]
	global_load_ushort v64, v[66:67], off nt
	s_and_b64 vcc, exec, s[38:39]
	v_mov_b32_e32 v66, 0
	s_cbranch_vccz .LBB0_262
	s_branch .LBB0_263

; #define LAS __attribute__((address_space(3)))
; __device__ __forceinline__ unsigned pk2(float lo, float hi) { f32x2 v = {lo, hi}; bf16x2_t b = __builtin_convertvector(v, bf16x2_t); return __builtin_bit_cast(unsigned, b); }
; #define WAVE_LDS_FENCE() asm volatile("s_waitcnt lgkmcnt(0)" ::: "memory")
; template <int MODE>
; __device__ __forceinline__ void transpose_item(const float* W, int K, int Nsrc, const float* g, bf16_t* WT, LAS float* scr, int kb, int nb, int lane) {
;     const int k0 = 64 * kb, n0 = 32 * nb, nd = n0 + (lane & 7) * 4;
;     int src = nd;
;     if (MODE == 1) src = nd < 4096 ? nd : (nd < 7168 ? nd + 16 : (nd < 7184 ? nd - 7168 + 4096 : -1));
; #pragma unroll
;     for (int i = 0; i < 8; ++i) { const int kk = 8 * i + (lane >> 3); f32x4 v = {0.f, 0.f, 0.f, 0.f};
;         if (src >= 0) { v = *(const f32x4*)(W + (size_t)(k0 + kk) * Nsrc + src); if (g) v = v * g[k0 + kk]; }
;         LAS float* d = scr + kk * 33 + (lane & 7) * 4; d[0] = v[0]; d[1] = v[1]; d[2] = v[2]; d[3] = v[3]; }
;     WAVE_LDS_FENCE();
;     const int c = lane & 7;
; #pragma unroll
;     for (int j = 0; j < 4; ++j) { const int n = (lane >> 3) + 8 * j; const LAS float* s = scr + (8 * c) * 33 + n;
;         u32x4 o; o.x = pk2(s[0 * 33], s[1 * 33]); o.y = pk2(s[2 * 33], s[3 * 33]); o.z = pk2(s[4 * 33], s[5 * 33]); o.w = pk2(s[6 * 33], s[7 * 33]);
;         *(u32x4*)(WT + (size_t)(n0 + n) * K + k0 + 8 * c) = o; }
;     WAVE_LDS_FENCE();
; }
; __device__ __forceinline__ void prep_weights(const Ctx& P, LAS unsigned char* lds, int l, int gw, int NGW) {
;     ...
;         transpose_item<0>(p_wdn + (size_t)l * DFF * D, DFF, D, nullptr, (bf16_t*)(ws + WS_WDN) + (size_t)l * D * DFF, scr, r / 32, r % 32, lane);
.LBB0_482:
	s_cmpk_gt_i32 s55, 0xe7f
	s_mov_b64 s[38:39], -1
	s_cbranch_scc0 .LBB0_516
	s_cmpk_gt_u32 s55, 0x107f
	s_cbranch_scc0 .LBB0_513
	s_cmpk_gt_u32 s55, 0x127f
	s_cbranch_scc0 .LBB0_510
	s_cmpk_gt_u32 s55, 0x147f
	s_cbranch_scc0 .LBB0_507
	s_cmpk_gt_u32 s55, 0x207f
	s_cbranch_scc0 .LBB0_488
	s_and_b32 s38, s1, 0x3e0
	s_and_b32 s30, s53, 0x7fffffc0
	v_or_b32_e32 v0, s38, v25
	s_addk_i32 s30, 0xbf00
	v_lshlrev_b32_e32 v0, 2, v0
	v_lshl_add_u64 v[20:21], s[4:5], 0, v[0:1]
	v_or_b32_e32 v0, s30, v6
	v_lshlrev_b32_e32 v0, 10, v0
	v_lshl_add_u64 v[2:3], v[0:1], 2, v[20:21]
	flat_load_dwordx4 v[2:5], v[2:3] nt
	v_or_b32_e32 v0, s30, v28
	v_add_u32_e32 v22, v26, v27
	v_lshlrev_b32_e32 v0, 10, v0
	s_waitcnt vmcnt(0) lgkmcnt(0)
	ds_write2_b32 v22, v2, v3 offset1:1
	ds_write2_b32 v22, v4, v5 offset0:2 offset1:3
	v_lshl_add_u64 v[2:3], v[0:1], 2, v[20:21]
	flat_load_dwordx4 v[2:5], v[2:3] nt
	v_add_u32_e32 v0, 0x420, v22
	s_waitcnt vmcnt(0) lgkmcnt(0)
	ds_write2_b32 v0, v2, v3 offset1:1
	v_add_u32_e32 v0, 0x428, v22
	ds_write2_b32 v0, v4, v5 offset1:1
	v_or_b32_e32 v0, s30, v29
	v_lshlrev_b32_e32 v0, 10, v0
	v_lshl_add_u64 v[2:3], v[0:1], 2, v[20:21]
	flat_load_dwordx4 v[2:5], v[2:3] nt
	v_add_u32_e32 v0, 0x840, v22
	s_waitcnt vmcnt(0) lgkmcnt(0)
	ds_write2_b32 v0, v2, v3 offset1:1
	v_add_u32_e32 v0, 0x848, v22
	ds_write2_b32 v0, v4, v5 offset1:1
	v_or_b32_e32 v0, s30, v30
	v_lshlrev_b32_e32 v0, 10, v0
	v_lshl_add_u64 v[2:3], v[0:1], 2, v[20:21]
	flat_load_dwordx4 v[2:5], v[2:3] nt
	v_add_u32_e32 v0, 0xc60, v22
	s_waitcnt vmcnt(0) lgkmcnt(0)
	ds_write2_b32 v0, v2, v3 offset1:1
	v_add_u32_e32 v0, 0xc68, v22
	ds_write2_b32 v0, v4, v5 offset1:1
	v_or_b32_e32 v0, s30, v31
	v_lshlrev_b32_e32 v0, 10, v0
	v_lshl_add_u64 v[2:3], v[0:1], 2, v[20:21]
	flat_load_dwordx4 v[2:5], v[2:3] nt
	v_add_u32_e32 v0, 0x1080, v22
	s_waitcnt vmcnt(0) lgkmcnt(0)
	ds_write2_b32 v0, v2, v3 offset1:1
	v_add_u32_e32 v0, 0x1088, v22
	ds_write2_b32 v0, v4, v5 offset1:1
	v_or_b32_e32 v0, s30, v32
	v_lshlrev_b32_e32 v0, 10, v0
	v_lshl_add_u64 v[2:3], v[0:1], 2, v[20:21]
	flat_load_dwordx4 v[2:5], v[2:3] nt
	v_add_u32_e32 v0, 0x14a0, v22
	s_waitcnt vmcnt(0) lgkmcnt(0)
	ds_write2_b32 v0, v2, v3 offset1:1
	v_add_u32_e32 v0, 0x14a8, v22
	ds_write2_b32 v0, v4, v5 offset1:1
	v_or_b32_e32 v0, s30, v33
	v_lshlrev_b32_e32 v0, 10, v0
	v_lshl_add_u64 v[2:3], v[0:1], 2, v[20:21]
	flat_load_dwordx4 v[2:5], v[2:3] nt
	v_add_u32_e32 v0, 0x18c0, v22
	s_waitcnt vmcnt(0) lgkmcnt(0)
	ds_write2_b32 v0, v2, v3 offset1:1
	v_add_u32_e32 v0, 0x18c8, v22
	ds_write2_b32 v0, v4, v5 offset1:1
	v_or_b32_e32 v0, s30, v34
	v_lshlrev_b32_e32 v0, 10, v0
	v_lshl_add_u64 v[2:3], v[0:1], 2, v[20:21]
	flat_load_dwordx4 v[2:5], v[2:3] nt
	v_add_u32_e32 v0, 0x1ce0, v22
	s_waitcnt vmcnt(0) lgkmcnt(0)
	ds_write2_b32 v0, v2, v3 offset1:1
	v_add_u32_e32 v0, 0x1ce8, v22
	ds_write2_b32 v0, v4, v5 offset1:1
	s_waitcnt lgkmcnt(0)
	ds_read2_b32 v[4:5], v35 offset0:33 offset1:41
	ds_read2_b32 v[36:37], v35 offset1:8
	ds_read2_b32 v[38:39], v35 offset0:66 offset1:74
	ds_read2_b32 v[40:41], v35 offset0:99 offset1:107
	ds_read2_b32 v[42:43], v35 offset0:132 offset1:140
	ds_read2_b32 v[44:45], v35 offset0:165 offset1:173
	ds_read2_b32 v[46:47], v35 offset0:198 offset1:206
	ds_read2_b32 v[48:49], v35 offset0:231 offset1:239
	v_or_b32_e32 v0, s38, v6
	v_mul_u32_u24_e32 v0, 0xc00, v0
	v_lshl_add_u64 v[2:3], s[30:31], 1, v[8:9]
	v_lshlrev_b32_e32 v0, 1, v0
	v_lshl_add_u64 v[50:51], v[2:3], 0, v[0:1]
	v_or_b32_e32 v0, s38, v28
	v_mul_u32_u24_e32 v0, 0xc00, v0
	s_waitcnt lgkmcnt(6)
	v_cvt_pk_bf16_f32 v20, v36, v4
	s_waitcnt lgkmcnt(4)
	v_cvt_pk_bf16_f32 v21, v38, v40
	s_waitcnt lgkmcnt(2)
	v_cvt_pk_bf16_f32 v22, v42, v44
	s_waitcnt lgkmcnt(0)
	v_cvt_pk_bf16_f32 v23, v46, v48
	v_lshlrev_b32_e32 v0, 1, v0
	global_store_dwordx4 v[50:51], v[20:23], off
	s_nop 1
	v_cvt_pk_bf16_f32 v20, v37, v5
	v_cvt_pk_bf16_f32 v21, v39, v41
	v_cvt_pk_bf16_f32 v22, v43, v45
	v_cvt_pk_bf16_f32 v23, v47, v49
	v_lshl_add_u64 v[4:5], v[2:3], 0, v[0:1]
	global_store_dwordx4 v[4:5], v[20:23], off
	ds_read2_b32 v[4:5], v35 offset0:16 offset1:24
	ds_read2_b32 v[36:37], v35 offset0:49 offset1:57
	ds_read2_b32 v[38:39], v35 offset0:82 offset1:90
	ds_read2_b32 v[40:41], v35 offset0:115 offset1:123
	ds_read2_b32 v[42:43], v35 offset0:148 offset1:156
	ds_read2_b32 v[44:45], v35 offset0:181 offset1:189
	ds_read2_b32 v[46:47], v35 offset0:214 offset1:222
	ds_read2_b32 v[48:49], v35 offset0:247 offset1:255
	v_or_b32_e32 v0, s38, v29
	v_mul_u32_u24_e32 v0, 0xc00, v0
	v_lshlrev_b32_e32 v0, 1, v0
	v_lshl_add_u64 v[50:51], v[2:3], 0, v[0:1]
	v_or_b32_e32 v0, s38, v30
	v_mul_u32_u24_e32 v0, 0xc00, v0
	s_waitcnt lgkmcnt(6)
	v_cvt_pk_bf16_f32 v20, v4, v36
	s_waitcnt lgkmcnt(4)
	v_cvt_pk_bf16_f32 v21, v38, v40
	s_waitcnt lgkmcnt(2)
	v_cvt_pk_bf16_f32 v22, v42, v44
	s_waitcnt lgkmcnt(0)
	v_cvt_pk_bf16_f32 v23, v46, v48
	v_lshlrev_b32_e32 v0, 1, v0
	global_store_dwordx4 v[50:51], v[20:23], off
	v_lshl_add_u64 v[2:3], v[2:3], 0, v[0:1]
	s_mov_b64 s[38:39], 0
	v_cvt_pk_bf16_f32 v20, v5, v37
	v_cvt_pk_bf16_f32 v21, v39, v41
	v_cvt_pk_bf16_f32 v22, v43, v45
	v_cvt_pk_bf16_f32 v23, v47, v49
	global_store_dwordx4 v[2:3], v[20:23], off
	s_waitcnt lgkmcnt(0)
; #define LAS __attribute__((address_space(3)))
; template <int MODE>
; __device__ __forceinline__ void transpose_item(const float* W, int K, int Nsrc, const float* g, bf16_t* WT, LAS float* scr, int kb, int nb, int lane) {
;     const int k0 = 64 * kb, n0 = 32 * nb, nd = n0 + (lane & 7) * 4;
;     int src = nd;
;     if (MODE == 1) src = nd < 4096 ? nd : (nd < 7168 ? nd + 16 : (nd < 7184 ? nd - 7168 + 4096 : -1));
; #pragma unroll
;     for (int i = 0; i < 8; ++i) { const int kk = 8 * i + (lane >> 3); f32x4 v = {0.f, 0.f, 0.f, 0.f};
;         if (src >= 0) { v = *(const f32x4*)(W + (size_t)(k0 + kk) * Nsrc + src); if (g) v = v * g[k0 + kk]; }
;         LAS float* d = scr + kk * 33 + (lane & 7) * 4; d[0] = v[0]; d[1] = v[1]; d[2] = v[2]; d[3] = v[3]; }
; __device__ __forceinline__ void prep_weights(const Ctx& P, LAS unsigned char* lds, int l, int gw, int NGW) {
;     ...
;         if (r < I_UP) { transpose_item<0>(p_wup + (size_t)l * D * DUP, D, DUP, p_g2 + l * D, (bf16_t*)(ws + WS_WUP) + (size_t)l * DUP * D, scr, r / 192, r % 192, lane); continue; } r -= I_UP;
.LBB0_488:
	s_andn2_b64 vcc, exec, s[38:39]
	s_cbranch_vccnz .LBB0_506
	s_add_i32 s30, s55, 0xeb80
	s_and_b32 s38, s30, 0xffff
	s_mul_i32 s38, s38, 0xaaab
	s_lshr_b32 s38, s38, 23
	s_mul_i32 s39, s38, 0xc0
	s_sub_i32 s39, s30, s39
	s_lshl_b32 s30, s38, 6
	s_lshl_b32 s38, s39, 5
	s_and_b32 s40, s38, 0xffe0
	v_or_b32_e32 v0, s40, v25
	v_lshlrev_b32_e32 v0, 2, v0
	v_or_b32_e32 v22, s30, v6
	v_lshl_add_u64 v[20:21], s[10:11], 0, v[0:1]
	v_mul_u32_u24_e32 v0, 0x1800, v22
	v_lshlrev_b32_e32 v0, 2, v0
	v_lshl_add_u64 v[2:3], v[20:21], 0, v[0:1]
	flat_load_dwordx4 v[2:5], v[2:3] nt
	v_cndmask_b32_e64 v0, 0, 1, s[14:15]
	v_cmp_ne_u32_e64 s[38:39], 1, v0
	s_andn2_b64 vcc, exec, s[14:15]
	s_cbranch_vccnz .LBB0_491
	v_lshlrev_b32_e32 v0, 2, v22
	v_lshl_add_u64 v[22:23], s[12:13], 0, v[0:1]
	flat_load_dword v0, v[22:23]
	s_waitcnt vmcnt(0) lgkmcnt(0)
	v_pk_mul_f32 v[4:5], v[4:5], v[0:1] op_sel_hi:[1,0]
	v_pk_mul_f32 v[2:3], v[2:3], v[0:1] op_sel_hi:[1,0]
.LBB0_491:
	v_or_b32_e32 v0, s30, v28
	v_mul_u32_u24_e32 v0, 0x1800, v0
	v_add_u32_e32 v36, v26, v27
	v_lshlrev_b32_e32 v0, 2, v0
	s_waitcnt vmcnt(0) lgkmcnt(0)
	ds_write2_b32 v36, v2, v3 offset1:1
	ds_write2_b32 v36, v4, v5 offset0:2 offset1:3
	v_lshl_add_u64 v[2:3], v[20:21], 0, v[0:1]
	flat_load_dwordx4 v[2:5], v[2:3] nt
	s_and_b64 vcc, exec, s[38:39]
	v_add_lshl_u32 v22, v6, s30, 2
	s_cbranch_vccnz .LBB0_493
	v_mov_b32_e32 v23, v1
	v_lshl_add_u64 v[38:39], s[12:13], 0, v[22:23]
	flat_load_dword v0, v[38:39] offset:32
	s_waitcnt vmcnt(0) lgkmcnt(0)
	v_pk_mul_f32 v[4:5], v[4:5], v[0:1] op_sel_hi:[1,0]
	v_pk_mul_f32 v[2:3], v[2:3], v[0:1] op_sel_hi:[1,0]
.LBB0_493:
	v_add_u32_e32 v0, 0x420, v36
	s_waitcnt vmcnt(0) lgkmcnt(0)
	ds_write2_b32 v0, v2, v3 offset1:1
	v_add_u32_e32 v0, 0x428, v36
	ds_write2_b32 v0, v4, v5 offset1:1
	v_or_b32_e32 v0, s30, v29
	v_mul_u32_u24_e32 v0, 0x1800, v0
	v_lshlrev_b32_e32 v0, 2, v0
	v_lshl_add_u64 v[2:3], v[20:21], 0, v[0:1]
	flat_load_dwordx4 v[2:5], v[2:3] nt
	s_and_b64 vcc, exec, s[38:39]
	s_cbranch_vccnz .LBB0_495
	v_mov_b32_e32 v23, v1
	v_lshl_add_u64 v[38:39], s[12:13], 0, v[22:23]
	flat_load_dword v0, v[38:39] offset:64
	s_waitcnt vmcnt(0) lgkmcnt(0)
	v_pk_mul_f32 v[4:5], v[4:5], v[0:1] op_sel_hi:[1,0]
	v_pk_mul_f32 v[2:3], v[2:3], v[0:1] op_sel_hi:[1,0]
.LBB0_495:
	v_add_u32_e32 v0, 0x840, v36
	s_waitcnt vmcnt(0) lgkmcnt(0)
	ds_write2_b32 v0, v2, v3 offset1:1
	v_add_u32_e32 v0, 0x848, v36
	ds_write2_b32 v0, v4, v5 offset1:1
	v_or_b32_e32 v0, s30, v30
	v_mul_u32_u24_e32 v0, 0x1800, v0
	v_lshlrev_b32_e32 v0, 2, v0
	v_lshl_add_u64 v[2:3], v[20:21], 0, v[0:1]
	flat_load_dwordx4 v[2:5], v[2:3] nt
	s_and_b64 vcc, exec, s[38:39]
	s_cbranch_vccnz .LBB0_497
	v_mov_b32_e32 v23, v1
	v_lshl_add_u64 v[38:39], s[12:13], 0, v[22:23]
	flat_load_dword v0, v[38:39] offset:96
	s_waitcnt vmcnt(0) lgkmcnt(0)
	v_pk_mul_f32 v[4:5], v[4:5], v[0:1] op_sel_hi:[1,0]
	v_pk_mul_f32 v[2:3], v[2:3], v[0:1] op_sel_hi:[1,0]
.LBB0_497:
	v_add_u32_e32 v0, 0xc60, v36
	s_waitcnt vmcnt(0) lgkmcnt(0)
	ds_write2_b32 v0, v2, v3 offset1:1
	v_add_u32_e32 v0, 0xc68, v36
	ds_write2_b32 v0, v4, v5 offset1:1
	v_or_b32_e32 v0, s30, v31
	v_mul_u32_u24_e32 v0, 0x1800, v0
	v_lshlrev_b32_e32 v0, 2, v0
	v_lshl_add_u64 v[2:3], v[20:21], 0, v[0:1]
	flat_load_dwordx4 v[2:5], v[2:3] nt
	s_and_b64 vcc, exec, s[38:39]
	s_cbranch_vccnz .LBB0_499
	v_mov_b32_e32 v23, v1
	v_lshl_add_u64 v[38:39], s[12:13], 0, v[22:23]
	flat_load_dword v0, v[38:39] offset:128
	s_waitcnt vmcnt(0) lgkmcnt(0)
	v_pk_mul_f32 v[4:5], v[4:5], v[0:1] op_sel_hi:[1,0]
	v_pk_mul_f32 v[2:3], v[2:3], v[0:1] op_sel_hi:[1,0]
.LBB0_499:
	v_add_u32_e32 v0, 0x1080, v36
	s_waitcnt vmcnt(0) lgkmcnt(0)
	ds_write2_b32 v0, v2, v3 offset1:1
	v_add_u32_e32 v0, 0x1088, v36
	ds_write2_b32 v0, v4, v5 offset1:1
	v_or_b32_e32 v0, s30, v32
	v_mul_u32_u24_e32 v0, 0x1800, v0
	v_lshlrev_b32_e32 v0, 2, v0
	v_lshl_add_u64 v[2:3], v[20:21], 0, v[0:1]
	flat_load_dwordx4 v[2:5], v[2:3] nt
	s_and_b64 vcc, exec, s[38:39]
	s_cbranch_vccnz .LBB0_501
	v_mov_b32_e32 v23, v1
	v_lshl_add_u64 v[38:39], s[12:13], 0, v[22:23]
	flat_load_dword v0, v[38:39] offset:160
	s_waitcnt vmcnt(0) lgkmcnt(0)
	v_pk_mul_f32 v[4:5], v[4:5], v[0:1] op_sel_hi:[1,0]
	v_pk_mul_f32 v[2:3], v[2:3], v[0:1] op_sel_hi:[1,0]
.LBB0_501:
	v_add_u32_e32 v0, 0x14a0, v36
	s_waitcnt vmcnt(0) lgkmcnt(0)
	ds_write2_b32 v0, v2, v3 offset1:1
	v_add_u32_e32 v0, 0x14a8, v36
	ds_write2_b32 v0, v4, v5 offset1:1
	v_or_b32_e32 v0, s30, v33
	v_mul_u32_u24_e32 v0, 0x1800, v0
	v_lshlrev_b32_e32 v0, 2, v0
	v_lshl_add_u64 v[2:3], v[20:21], 0, v[0:1]
	flat_load_dwordx4 v[2:5], v[2:3] nt
	s_and_b64 vcc, exec, s[38:39]
	s_cbranch_vccnz .LBB0_503
	v_mov_b32_e32 v23, v1
	v_lshl_add_u64 v[38:39], s[12:13], 0, v[22:23]
	flat_load_dword v0, v[38:39] offset:192
	s_waitcnt vmcnt(0) lgkmcnt(0)
	v_pk_mul_f32 v[4:5], v[4:5], v[0:1] op_sel_hi:[1,0]
	v_pk_mul_f32 v[2:3], v[2:3], v[0:1] op_sel_hi:[1,0]
.LBB0_503:
	v_add_u32_e32 v0, 0x18c0, v36
	s_waitcnt vmcnt(0) lgkmcnt(0)
	ds_write2_b32 v0, v2, v3 offset1:1
	v_add_u32_e32 v0, 0x18c8, v36
	ds_write2_b32 v0, v4, v5 offset1:1
	v_or_b32_e32 v0, s30, v34
	v_mul_u32_u24_e32 v0, 0x1800, v0
	v_lshlrev_b32_e32 v0, 2, v0
	v_lshl_add_u64 v[2:3], v[20:21], 0, v[0:1]
	flat_load_dwordx4 v[2:5], v[2:3] nt
	s_and_b64 vcc, exec, s[38:39]
	s_cbranch_vccnz .LBB0_505
	v_mov_b32_e32 v23, v1
	v_lshl_add_u64 v[20:21], s[12:13], 0, v[22:23]
	flat_load_dword v0, v[20:21] offset:224
	s_waitcnt vmcnt(0) lgkmcnt(0)
	v_pk_mul_f32 v[4:5], v[4:5], v[0:1] op_sel_hi:[1,0]
	v_pk_mul_f32 v[2:3], v[2:3], v[0:1] op_sel_hi:[1,0]

; #define LAS __attribute__((address_space(3)))
; __device__ __forceinline__ unsigned pk2(float lo, float hi) { f32x2 v = {lo, hi}; bf16x2_t b = __builtin_convertvector(v, bf16x2_t); return __builtin_bit_cast(unsigned, b); }
; #define WAVE_LDS_FENCE() asm volatile("s_waitcnt lgkmcnt(0)" ::: "memory")
; template <int MODE>
; __device__ __forceinline__ void transpose_item(const float* W, int K, int Nsrc, const float* g, bf16_t* WT, LAS float* scr, int kb, int nb, int lane) {
;     const int k0 = 64 * kb, n0 = 32 * nb, nd = n0 + (lane & 7) * 4;
;     int src = nd;
;     if (MODE == 1) src = nd < 4096 ? nd : (nd < 7168 ? nd + 16 : (nd < 7184 ? nd - 7168 + 4096 : -1));
; #pragma unroll
;     for (int i = 0; i < 8; ++i) { const int kk = 8 * i + (lane >> 3); f32x4 v = {0.f, 0.f, 0.f, 0.f};
;         if (src >= 0) { v = *(const f32x4*)(W + (size_t)(k0 + kk) * Nsrc + src); if (g) v = v * g[k0 + kk]; }
;         LAS float* d = scr + kk * 33 + (lane & 7) * 4; d[0] = v[0]; d[1] = v[1]; d[2] = v[2]; d[3] = v[3]; }
;     WAVE_LDS_FENCE();
;     const int c = lane & 7;
; #pragma unroll
;     for (int j = 0; j < 4; ++j) { const int n = (lane >> 3) + 8 * j; const LAS float* s = scr + (8 * c) * 33 + n;
;         u32x4 o; o.x = pk2(s[0 * 33], s[1 * 33]); o.y = pk2(s[2 * 33], s[3 * 33]); o.z = pk2(s[4 * 33], s[5 * 33]); o.w = pk2(s[6 * 33], s[7 * 33]);
;         *(u32x4*)(WT + (size_t)(n0 + n) * K + k0 + 8 * c) = o; }
;     WAVE_LDS_FENCE();
; }
; __device__ __forceinline__ void prep_weights(const Ctx& P, LAS unsigned char* lds, int l, int gw, int NGW) {
;     ...
;         if (r < I_SQ) { transpose_item<0>(p_wo + (size_t)l * D * D, D, D, nullptr, (bf16_t*)(ws + WS_WO) + (size_t)l * D * D, scr, r / 32, r % 32, lane); continue; } r -= I_SQ;
.LBB0_507:
	s_andn2_b64 vcc, exec, s[38:39]
	s_cbranch_vccnz .LBB0_509
	s_and_b32 s38, s1, 0x3e0
	s_and_b32 s30, s53, 0x3fc0
	v_or_b32_e32 v0, s38, v25
	s_addk_i32 s30, 0xdb00
	v_lshlrev_b32_e32 v0, 2, v0
	v_lshl_add_u64 v[20:21], s[22:23], 0, v[0:1]
	v_or_b32_e32 v0, s30, v6
	v_lshlrev_b32_e32 v0, 10, v0
	v_lshl_add_u64 v[2:3], v[0:1], 2, v[20:21]
	flat_load_dwordx4 v[2:5], v[2:3] nt
	v_or_b32_e32 v0, s30, v28
	v_add_u32_e32 v22, v26, v27
	v_lshlrev_b32_e32 v0, 10, v0
	s_waitcnt vmcnt(0) lgkmcnt(0)
	ds_write2_b32 v22, v2, v3 offset1:1
	ds_write2_b32 v22, v4, v5 offset0:2 offset1:3
	v_lshl_add_u64 v[2:3], v[0:1], 2, v[20:21]
	flat_load_dwordx4 v[2:5], v[2:3] nt
	v_add_u32_e32 v0, 0x420, v22
	s_waitcnt vmcnt(0) lgkmcnt(0)
	ds_write2_b32 v0, v2, v3 offset1:1
	v_add_u32_e32 v0, 0x428, v22
	ds_write2_b32 v0, v4, v5 offset1:1
	v_or_b32_e32 v0, s30, v29
	v_lshlrev_b32_e32 v0, 10, v0
	v_lshl_add_u64 v[2:3], v[0:1], 2, v[20:21]
	flat_load_dwordx4 v[2:5], v[2:3] nt
	v_add_u32_e32 v0, 0x840, v22
	s_waitcnt vmcnt(0) lgkmcnt(0)
	ds_write2_b32 v0, v2, v3 offset1:1
	v_add_u32_e32 v0, 0x848, v22
	ds_write2_b32 v0, v4, v5 offset1:1
	v_or_b32_e32 v0, s30, v30
	v_lshlrev_b32_e32 v0, 10, v0
	v_lshl_add_u64 v[2:3], v[0:1], 2, v[20:21]
	flat_load_dwordx4 v[2:5], v[2:3] nt
	v_add_u32_e32 v0, 0xc60, v22
	s_waitcnt vmcnt(0) lgkmcnt(0)
	ds_write2_b32 v0, v2, v3 offset1:1
	v_add_u32_e32 v0, 0xc68, v22
	ds_write2_b32 v0, v4, v5 offset1:1
	v_or_b32_e32 v0, s30, v31
	v_lshlrev_b32_e32 v0, 10, v0
	v_lshl_add_u64 v[2:3], v[0:1], 2, v[20:21]
	flat_load_dwordx4 v[2:5], v[2:3] nt
	v_add_u32_e32 v0, 0x1080, v22
	s_waitcnt vmcnt(0) lgkmcnt(0)
	ds_write2_b32 v0, v2, v3 offset1:1
	v_add_u32_e32 v0, 0x1088, v22
	ds_write2_b32 v0, v4, v5 offset1:1
	v_or_b32_e32 v0, s30, v32
	v_lshlrev_b32_e32 v0, 10, v0
	v_lshl_add_u64 v[2:3], v[0:1], 2, v[20:21]
	flat_load_dwordx4 v[2:5], v[2:3] nt
	v_add_u32_e32 v0, 0x14a0, v22
	s_waitcnt vmcnt(0) lgkmcnt(0)
	ds_write2_b32 v0, v2, v3 offset1:1
	v_add_u32_e32 v0, 0x14a8, v22
	ds_write2_b32 v0, v4, v5 offset1:1
	v_or_b32_e32 v0, s30, v33
	v_lshlrev_b32_e32 v0, 10, v0
	v_lshl_add_u64 v[2:3], v[0:1], 2, v[20:21]
	flat_load_dwordx4 v[2:5], v[2:3] nt
	v_add_u32_e32 v0, 0x18c0, v22
	s_waitcnt vmcnt(0) lgkmcnt(0)
	ds_write2_b32 v0, v2, v3 offset1:1
	v_add_u32_e32 v0, 0x18c8, v22
	ds_write2_b32 v0, v4, v5 offset1:1
	v_or_b32_e32 v0, s30, v34
	v_lshlrev_b32_e32 v0, 10, v0
	v_lshl_add_u64 v[2:3], v[0:1], 2, v[20:21]
	flat_load_dwordx4 v[2:5], v[2:3] nt
	v_add_u32_e32 v0, 0x1ce0, v22
	s_waitcnt vmcnt(0) lgkmcnt(0)
	ds_write2_b32 v0, v2, v3 offset1:1
	v_add_u32_e32 v0, 0x1ce8, v22
	ds_write2_b32 v0, v4, v5 offset1:1
	s_waitcnt lgkmcnt(0)
	ds_read2_b32 v[4:5], v35 offset0:33 offset1:41
	ds_read2_b32 v[36:37], v35 offset1:8
	ds_read2_b32 v[38:39], v35 offset0:66 offset1:74
	ds_read2_b32 v[40:41], v35 offset0:99 offset1:107
	ds_read2_b32 v[42:43], v35 offset0:132 offset1:140
	ds_read2_b32 v[44:45], v35 offset0:165 offset1:173
	ds_read2_b32 v[46:47], v35 offset0:198 offset1:206
	ds_read2_b32 v[48:49], v35 offset0:231 offset1:239
	v_or_b32_e32 v0, s38, v6
	v_lshl_add_u64 v[2:3], s[30:31], 1, v[12:13]
	v_lshlrev_b32_e32 v0, 11, v0
	v_lshl_add_u64 v[50:51], v[2:3], 0, v[0:1]
	v_or_b32_e32 v0, s38, v28
	s_waitcnt lgkmcnt(6)
	v_cvt_pk_bf16_f32 v20, v36, v4
	s_waitcnt lgkmcnt(4)
	v_cvt_pk_bf16_f32 v21, v38, v40
	s_waitcnt lgkmcnt(2)
	v_cvt_pk_bf16_f32 v22, v42, v44
	s_waitcnt lgkmcnt(0)
	v_cvt_pk_bf16_f32 v23, v46, v48
	v_lshlrev_b32_e32 v0, 11, v0
	global_store_dwordx4 v[50:51], v[20:23], off
	s_nop 1
	v_cvt_pk_bf16_f32 v20, v37, v5
	v_cvt_pk_bf16_f32 v21, v39, v41
	v_cvt_pk_bf16_f32 v22, v43, v45
	v_cvt_pk_bf16_f32 v23, v47, v49
	v_lshl_add_u64 v[4:5], v[2:3], 0, v[0:1]
	global_store_dwordx4 v[4:5], v[20:23], off
	ds_read2_b32 v[4:5], v35 offset0:49 offset1:57
	ds_read2_b32 v[36:37], v35 offset0:16 offset1:24
	ds_read2_b32 v[38:39], v35 offset0:82 offset1:90
	ds_read2_b32 v[40:41], v35 offset0:115 offset1:123
	ds_read2_b32 v[42:43], v35 offset0:148 offset1:156
	ds_read2_b32 v[44:45], v35 offset0:181 offset1:189
	ds_read2_b32 v[46:47], v35 offset0:214 offset1:222
	ds_read2_b32 v[48:49], v35 offset0:247 offset1:255
	v_or_b32_e32 v0, s38, v29
	v_lshlrev_b32_e32 v0, 11, v0
	v_lshl_add_u64 v[50:51], v[2:3], 0, v[0:1]
	v_or_b32_e32 v0, s38, v30
	s_waitcnt lgkmcnt(6)
	v_cvt_pk_bf16_f32 v20, v36, v4
	s_waitcnt lgkmcnt(4)
	v_cvt_pk_bf16_f32 v21, v38, v40
	s_waitcnt lgkmcnt(2)
	v_cvt_pk_bf16_f32 v22, v42, v44
	s_waitcnt lgkmcnt(0)
	v_cvt_pk_bf16_f32 v23, v46, v48
	v_lshlrev_b32_e32 v0, 11, v0
	global_store_dwordx4 v[50:51], v[20:23], off
	v_lshl_add_u64 v[2:3], v[2:3], 0, v[0:1]
	s_nop 0
	v_cvt_pk_bf16_f32 v20, v37, v5
	v_cvt_pk_bf16_f32 v21, v39, v41
	v_cvt_pk_bf16_f32 v22, v43, v45
	v_cvt_pk_bf16_f32 v23, v47, v49
	global_store_dwordx4 v[2:3], v[20:23], off
	s_waitcnt lgkmcnt(0)

; #define LAS __attribute__((address_space(3)))
; __device__ __forceinline__ unsigned pk2(float lo, float hi) { f32x2 v = {lo, hi}; bf16x2_t b = __builtin_convertvector(v, bf16x2_t); return __builtin_bit_cast(unsigned, b); }
; #define WAVE_LDS_FENCE() asm volatile("s_waitcnt lgkmcnt(0)" ::: "memory")
; template <int MODE>
; __device__ __forceinline__ void transpose_item(const float* W, int K, int Nsrc, const float* g, bf16_t* WT, LAS float* scr, int kb, int nb, int lane) {
;     const int k0 = 64 * kb, n0 = 32 * nb, nd = n0 + (lane & 7) * 4;
;     int src = nd;
;     if (MODE == 1) src = nd < 4096 ? nd : (nd < 7168 ? nd + 16 : (nd < 7184 ? nd - 7168 + 4096 : -1));
; #pragma unroll
;     for (int i = 0; i < 8; ++i) { const int kk = 8 * i + (lane >> 3); f32x4 v = {0.f, 0.f, 0.f, 0.f};
;         if (src >= 0) { v = *(const f32x4*)(W + (size_t)(k0 + kk) * Nsrc + src); if (g) v = v * g[k0 + kk]; }
;         LAS float* d = scr + kk * 33 + (lane & 7) * 4; d[0] = v[0]; d[1] = v[1]; d[2] = v[2]; d[3] = v[3]; }
;     WAVE_LDS_FENCE();
;     const int c = lane & 7;
; #pragma unroll
;     for (int j = 0; j < 4; ++j) { const int n = (lane >> 3) + 8 * j; const LAS float* s = scr + (8 * c) * 33 + n;
;         u32x4 o; o.x = pk2(s[0 * 33], s[1 * 33]); o.y = pk2(s[2 * 33], s[3 * 33]); o.z = pk2(s[4 * 33], s[5 * 33]); o.w = pk2(s[6 * 33], s[7 * 33]);
;         *(u32x4*)(WT + (size_t)(n0 + n) * K + k0 + 8 * c) = o; }
;     WAVE_LDS_FENCE();
; }
; __device__ __forceinline__ void prep_weights(const Ctx& P, LAS unsigned char* lds, int l, int gw, int NGW) {
;     ...
;         if (r < I_SQ) { transpose_item<0>(p_wb + (size_t)l * D * D, D, D, nullptr, (bf16_t*)(ws + WS_WB) + (size_t)l * D * D, scr, r / 32, r % 32, lane); continue; } r -= I_SQ;
.LBB0_510:
	s_andn2_b64 vcc, exec, s[38:39]
	s_cbranch_vccnz .LBB0_512
	s_and_b32 s38, s1, 0x3e0
	s_and_b32 s30, s53, 0x3fc0
	v_or_b32_e32 v0, s38, v25
	s_addk_i32 s30, 0xdf00
	v_lshlrev_b32_e32 v0, 2, v0
	v_lshl_add_u64 v[20:21], s[28:29], 0, v[0:1]
	v_or_b32_e32 v0, s30, v6
	v_lshlrev_b32_e32 v0, 10, v0
	v_lshl_add_u64 v[2:3], v[0:1], 2, v[20:21]
	flat_load_dwordx4 v[2:5], v[2:3] nt
	v_or_b32_e32 v0, s30, v28
	v_add_u32_e32 v22, v26, v27
	v_lshlrev_b32_e32 v0, 10, v0
	s_waitcnt vmcnt(0) lgkmcnt(0)
	ds_write2_b32 v22, v2, v3 offset1:1
	ds_write2_b32 v22, v4, v5 offset0:2 offset1:3
	v_lshl_add_u64 v[2:3], v[0:1], 2, v[20:21]
	flat_load_dwordx4 v[2:5], v[2:3] nt
	v_add_u32_e32 v0, 0x420, v22
	s_waitcnt vmcnt(0) lgkmcnt(0)
	ds_write2_b32 v0, v2, v3 offset1:1
	v_add_u32_e32 v0, 0x428, v22
	ds_write2_b32 v0, v4, v5 offset1:1
	v_or_b32_e32 v0, s30, v29
	v_lshlrev_b32_e32 v0, 10, v0
	v_lshl_add_u64 v[2:3], v[0:1], 2, v[20:21]
	flat_load_dwordx4 v[2:5], v[2:3] nt
	v_add_u32_e32 v0, 0x840, v22
	s_waitcnt vmcnt(0) lgkmcnt(0)
	ds_write2_b32 v0, v2, v3 offset1:1
	v_add_u32_e32 v0, 0x848, v22
	ds_write2_b32 v0, v4, v5 offset1:1
	v_or_b32_e32 v0, s30, v30
	v_lshlrev_b32_e32 v0, 10, v0
	v_lshl_add_u64 v[2:3], v[0:1], 2, v[20:21]
	flat_load_dwordx4 v[2:5], v[2:3] nt
	v_add_u32_e32 v0, 0xc60, v22
	s_waitcnt vmcnt(0) lgkmcnt(0)
	ds_write2_b32 v0, v2, v3 offset1:1
	v_add_u32_e32 v0, 0xc68, v22
	ds_write2_b32 v0, v4, v5 offset1:1
	v_or_b32_e32 v0, s30, v31
	v_lshlrev_b32_e32 v0, 10, v0
	v_lshl_add_u64 v[2:3], v[0:1], 2, v[20:21]
	flat_load_dwordx4 v[2:5], v[2:3] nt
	v_add_u32_e32 v0, 0x1080, v22
	s_waitcnt vmcnt(0) lgkmcnt(0)
	ds_write2_b32 v0, v2, v3 offset1:1
	v_add_u32_e32 v0, 0x1088, v22
	ds_write2_b32 v0, v4, v5 offset1:1
	v_or_b32_e32 v0, s30, v32
	v_lshlrev_b32_e32 v0, 10, v0
	v_lshl_add_u64 v[2:3], v[0:1], 2, v[20:21]
	flat_load_dwordx4 v[2:5], v[2:3] nt
	v_add_u32_e32 v0, 0x14a0, v22
	s_waitcnt vmcnt(0) lgkmcnt(0)
	ds_write2_b32 v0, v2, v3 offset1:1
	v_add_u32_e32 v0, 0x14a8, v22
	ds_write2_b32 v0, v4, v5 offset1:1
	v_or_b32_e32 v0, s30, v33
	v_lshlrev_b32_e32 v0, 10, v0
	v_lshl_add_u64 v[2:3], v[0:1], 2, v[20:21]
	flat_load_dwordx4 v[2:5], v[2:3] nt
	v_add_u32_e32 v0, 0x18c0, v22
	s_waitcnt vmcnt(0) lgkmcnt(0)
	ds_write2_b32 v0, v2, v3 offset1:1
	v_add_u32_e32 v0, 0x18c8, v22
	ds_write2_b32 v0, v4, v5 offset1:1
	v_or_b32_e32 v0, s30, v34
	v_lshlrev_b32_e32 v0, 10, v0
	v_lshl_add_u64 v[2:3], v[0:1], 2, v[20:21]
	flat_load_dwordx4 v[2:5], v[2:3] nt
	v_add_u32_e32 v0, 0x1ce0, v22
	s_waitcnt vmcnt(0) lgkmcnt(0)
	ds_write2_b32 v0, v2, v3 offset1:1
	v_add_u32_e32 v0, 0x1ce8, v22
	ds_write2_b32 v0, v4, v5 offset1:1
	s_waitcnt lgkmcnt(0)
	ds_read2_b32 v[4:5], v35 offset0:33 offset1:41
	ds_read2_b32 v[36:37], v35 offset1:8
	ds_read2_b32 v[38:39], v35 offset0:66 offset1:74
	ds_read2_b32 v[40:41], v35 offset0:99 offset1:107
	ds_read2_b32 v[42:43], v35 offset0:132 offset1:140
	ds_read2_b32 v[44:45], v35 offset0:165 offset1:173
	ds_read2_b32 v[46:47], v35 offset0:198 offset1:206
	ds_read2_b32 v[48:49], v35 offset0:231 offset1:239
	v_or_b32_e32 v0, s38, v6
	v_lshl_add_u64 v[2:3], s[30:31], 1, v[14:15]
	v_lshlrev_b32_e32 v0, 11, v0
	v_lshl_add_u64 v[50:51], v[2:3], 0, v[0:1]
	v_or_b32_e32 v0, s38, v28
	s_waitcnt lgkmcnt(6)
	v_cvt_pk_bf16_f32 v20, v36, v4
	s_waitcnt lgkmcnt(4)
	v_cvt_pk_bf16_f32 v21, v38, v40
	s_waitcnt lgkmcnt(2)
	v_cvt_pk_bf16_f32 v22, v42, v44
	s_waitcnt lgkmcnt(0)
	v_cvt_pk_bf16_f32 v23, v46, v48
	v_lshlrev_b32_e32 v0, 11, v0
	global_store_dwordx4 v[50:51], v[20:23], off
	s_nop 1
	v_cvt_pk_bf16_f32 v20, v37, v5
	v_cvt_pk_bf16_f32 v21, v39, v41
	v_cvt_pk_bf16_f32 v22, v43, v45
	v_cvt_pk_bf16_f32 v23, v47, v49
	v_lshl_add_u64 v[4:5], v[2:3], 0, v[0:1]
	global_store_dwordx4 v[4:5], v[20:23], off
	ds_read2_b32 v[4:5], v35 offset0:49 offset1:57
	ds_read2_b32 v[36:37], v35 offset0:16 offset1:24
	ds_read2_b32 v[38:39], v35 offset0:82 offset1:90
	ds_read2_b32 v[40:41], v35 offset0:115 offset1:123
	ds_read2_b32 v[42:43], v35 offset0:148 offset1:156
	ds_read2_b32 v[44:45], v35 offset0:181 offset1:189
	ds_read2_b32 v[46:47], v35 offset0:214 offset1:222
	ds_read2_b32 v[48:49], v35 offset0:247 offset1:255
	v_or_b32_e32 v0, s38, v29
	v_lshlrev_b32_e32 v0, 11, v0
	v_lshl_add_u64 v[50:51], v[2:3], 0, v[0:1]
	v_or_b32_e32 v0, s38, v30
	s_waitcnt lgkmcnt(6)
	v_cvt_pk_bf16_f32 v20, v36, v4
	s_waitcnt lgkmcnt(4)
	v_cvt_pk_bf16_f32 v21, v38, v40
	s_waitcnt lgkmcnt(2)
	v_cvt_pk_bf16_f32 v22, v42, v44
	s_waitcnt lgkmcnt(0)
	v_cvt_pk_bf16_f32 v23, v46, v48
	v_lshlrev_b32_e32 v0, 11, v0
	global_store_dwordx4 v[50:51], v[20:23], off
	v_lshl_add_u64 v[2:3], v[2:3], 0, v[0:1]
	s_nop 0
	v_cvt_pk_bf16_f32 v20, v37, v5
	v_cvt_pk_bf16_f32 v21, v39, v41
	v_cvt_pk_bf16_f32 v22, v43, v45
	v_cvt_pk_bf16_f32 v23, v47, v49
	global_store_dwordx4 v[2:3], v[20:23], off
	s_waitcnt lgkmcnt(0)

; #define LAS __attribute__((address_space(3)))
; __device__ __forceinline__ unsigned pk2(float lo, float hi) { f32x2 v = {lo, hi}; bf16x2_t b = __builtin_convertvector(v, bf16x2_t); return __builtin_bit_cast(unsigned, b); }
; #define WAVE_LDS_FENCE() asm volatile("s_waitcnt lgkmcnt(0)" ::: "memory")
; template <int MODE>
; __device__ __forceinline__ void transpose_item(const float* W, int K, int Nsrc, const float* g, bf16_t* WT, LAS float* scr, int kb, int nb, int lane) {
;     const int k0 = 64 * kb, n0 = 32 * nb, nd = n0 + (lane & 7) * 4;
;     int src = nd;
;     if (MODE == 1) src = nd < 4096 ? nd : (nd < 7168 ? nd + 16 : (nd < 7184 ? nd - 7168 + 4096 : -1));
; #pragma unroll
;     for (int i = 0; i < 8; ++i) { const int kk = 8 * i + (lane >> 3); f32x4 v = {0.f, 0.f, 0.f, 0.f};
;         if (src >= 0) { v = *(const f32x4*)(W + (size_t)(k0 + kk) * Nsrc + src); if (g) v = v * g[k0 + kk]; }
;         LAS float* d = scr + kk * 33 + (lane & 7) * 4; d[0] = v[0]; d[1] = v[1]; d[2] = v[2]; d[3] = v[3]; }
;     WAVE_LDS_FENCE();
;     const int c = lane & 7;
; #pragma unroll
;     for (int j = 0; j < 4; ++j) { const int n = (lane >> 3) + 8 * j; const LAS float* s = scr + (8 * c) * 33 + n;
;         u32x4 o; o.x = pk2(s[0 * 33], s[1 * 33]); o.y = pk2(s[2 * 33], s[3 * 33]); o.z = pk2(s[4 * 33], s[5 * 33]); o.w = pk2(s[6 * 33], s[7 * 33]);
;         *(u32x4*)(WT + (size_t)(n0 + n) * K + k0 + 8 * c) = o; }
;     WAVE_LDS_FENCE();
; }
; __device__ __forceinline__ void prep_weights(const Ctx& P, LAS unsigned char* lds, int l, int gw, int NGW) {
;     ...
;         if (r < I_SQ) { transpose_item<0>(p_wa + (size_t)l * D * D, D, D, nullptr, (bf16_t*)(ws + WS_WA) + (size_t)l * D * D, scr, r / 32, r % 32, lane); continue; } r -= I_SQ;
.LBB0_513:
	s_andn2_b64 vcc, exec, s[38:39]
	s_cbranch_vccnz .LBB0_515
	s_and_b32 s38, s1, 0x3e0
	s_and_b32 s30, s53, 0x3fc0
	v_or_b32_e32 v0, s38, v25
	s_addk_i32 s30, 0xe300
	v_lshlrev_b32_e32 v0, 2, v0
	v_lshl_add_u64 v[20:21], s[34:35], 0, v[0:1]
	v_or_b32_e32 v0, s30, v6
	v_lshlrev_b32_e32 v0, 10, v0
	v_lshl_add_u64 v[2:3], v[0:1], 2, v[20:21]
	flat_load_dwordx4 v[2:5], v[2:3] nt
	v_or_b32_e32 v0, s30, v28
	v_add_u32_e32 v22, v26, v27
	v_lshlrev_b32_e32 v0, 10, v0
	s_waitcnt vmcnt(0) lgkmcnt(0)
	ds_write2_b32 v22, v2, v3 offset1:1
	ds_write2_b32 v22, v4, v5 offset0:2 offset1:3
	v_lshl_add_u64 v[2:3], v[0:1], 2, v[20:21]
	flat_load_dwordx4 v[2:5], v[2:3] nt
	v_add_u32_e32 v0, 0x420, v22
	s_waitcnt vmcnt(0) lgkmcnt(0)
	ds_write2_b32 v0, v2, v3 offset1:1
	v_add_u32_e32 v0, 0x428, v22
	ds_write2_b32 v0, v4, v5 offset1:1
	v_or_b32_e32 v0, s30, v29
	v_lshlrev_b32_e32 v0, 10, v0
	v_lshl_add_u64 v[2:3], v[0:1], 2, v[20:21]
	flat_load_dwordx4 v[2:5], v[2:3] nt
	v_add_u32_e32 v0, 0x840, v22
	s_waitcnt vmcnt(0) lgkmcnt(0)
	ds_write2_b32 v0, v2, v3 offset1:1
	v_add_u32_e32 v0, 0x848, v22
	ds_write2_b32 v0, v4, v5 offset1:1
	v_or_b32_e32 v0, s30, v30
	v_lshlrev_b32_e32 v0, 10, v0
	v_lshl_add_u64 v[2:3], v[0:1], 2, v[20:21]
	flat_load_dwordx4 v[2:5], v[2:3] nt
	v_add_u32_e32 v0, 0xc60, v22
	s_waitcnt vmcnt(0) lgkmcnt(0)
	ds_write2_b32 v0, v2, v3 offset1:1
	v_add_u32_e32 v0, 0xc68, v22
	ds_write2_b32 v0, v4, v5 offset1:1
	v_or_b32_e32 v0, s30, v31
	v_lshlrev_b32_e32 v0, 10, v0
	v_lshl_add_u64 v[2:3], v[0:1], 2, v[20:21]
	flat_load_dwordx4 v[2:5], v[2:3] nt
	v_add_u32_e32 v0, 0x1080, v22
	s_waitcnt vmcnt(0) lgkmcnt(0)
	ds_write2_b32 v0, v2, v3 offset1:1
	v_add_u32_e32 v0, 0x1088, v22
	ds_write2_b32 v0, v4, v5 offset1:1
	v_or_b32_e32 v0, s30, v32
	v_lshlrev_b32_e32 v0, 10, v0
	v_lshl_add_u64 v[2:3], v[0:1], 2, v[20:21]
	flat_load_dwordx4 v[2:5], v[2:3] nt
	v_add_u32_e32 v0, 0x14a0, v22
	s_waitcnt vmcnt(0) lgkmcnt(0)
	ds_write2_b32 v0, v2, v3 offset1:1
	v_add_u32_e32 v0, 0x14a8, v22
	ds_write2_b32 v0, v4, v5 offset1:1
	v_or_b32_e32 v0, s30, v33
	v_lshlrev_b32_e32 v0, 10, v0
	v_lshl_add_u64 v[2:3], v[0:1], 2, v[20:21]
	flat_load_dwordx4 v[2:5], v[2:3] nt
	v_add_u32_e32 v0, 0x18c0, v22
	s_waitcnt vmcnt(0) lgkmcnt(0)
	ds_write2_b32 v0, v2, v3 offset1:1
	v_add_u32_e32 v0, 0x18c8, v22
	ds_write2_b32 v0, v4, v5 offset1:1
	v_or_b32_e32 v0, s30, v34
	v_lshlrev_b32_e32 v0, 10, v0
	v_lshl_add_u64 v[2:3], v[0:1], 2, v[20:21]
	flat_load_dwordx4 v[2:5], v[2:3] nt
	v_add_u32_e32 v0, 0x1ce0, v22
	s_waitcnt vmcnt(0) lgkmcnt(0)
	ds_write2_b32 v0, v2, v3 offset1:1
	v_add_u32_e32 v0, 0x1ce8, v22
	ds_write2_b32 v0, v4, v5 offset1:1
	s_waitcnt lgkmcnt(0)
	ds_read2_b32 v[4:5], v35 offset0:33 offset1:41
	ds_read2_b32 v[36:37], v35 offset1:8
	ds_read2_b32 v[38:39], v35 offset0:66 offset1:74
	ds_read2_b32 v[40:41], v35 offset0:99 offset1:107
	ds_read2_b32 v[42:43], v35 offset0:132 offset1:140
	ds_read2_b32 v[44:45], v35 offset0:165 offset1:173
	ds_read2_b32 v[46:47], v35 offset0:198 offset1:206
	ds_read2_b32 v[48:49], v35 offset0:231 offset1:239
	v_or_b32_e32 v0, s38, v6
	v_lshl_add_u64 v[2:3], s[30:31], 1, v[16:17]
	v_lshlrev_b32_e32 v0, 11, v0
	v_lshl_add_u64 v[50:51], v[2:3], 0, v[0:1]
	v_or_b32_e32 v0, s38, v28
	s_waitcnt lgkmcnt(6)
	v_cvt_pk_bf16_f32 v20, v36, v4
	s_waitcnt lgkmcnt(4)
	v_cvt_pk_bf16_f32 v21, v38, v40
	s_waitcnt lgkmcnt(2)
	v_cvt_pk_bf16_f32 v22, v42, v44
	s_waitcnt lgkmcnt(0)
	v_cvt_pk_bf16_f32 v23, v46, v48
	v_lshlrev_b32_e32 v0, 11, v0
	global_store_dwordx4 v[50:51], v[20:23], off
	s_nop 1
	v_cvt_pk_bf16_f32 v20, v37, v5
	v_cvt_pk_bf16_f32 v21, v39, v41
	v_cvt_pk_bf16_f32 v22, v43, v45
	v_cvt_pk_bf16_f32 v23, v47, v49
	v_lshl_add_u64 v[4:5], v[2:3], 0, v[0:1]
	global_store_dwordx4 v[4:5], v[20:23], off
	ds_read2_b32 v[4:5], v35 offset0:49 offset1:57
	ds_read2_b32 v[36:37], v35 offset0:16 offset1:24
	ds_read2_b32 v[38:39], v35 offset0:82 offset1:90
	ds_read2_b32 v[40:41], v35 offset0:115 offset1:123
	ds_read2_b32 v[42:43], v35 offset0:148 offset1:156
	ds_read2_b32 v[44:45], v35 offset0:181 offset1:189
	ds_read2_b32 v[46:47], v35 offset0:214 offset1:222
	ds_read2_b32 v[48:49], v35 offset0:247 offset1:255
	v_or_b32_e32 v0, s38, v29
	v_lshlrev_b32_e32 v0, 11, v0
	v_lshl_add_u64 v[50:51], v[2:3], 0, v[0:1]
	v_or_b32_e32 v0, s38, v30
	s_waitcnt lgkmcnt(6)
	v_cvt_pk_bf16_f32 v20, v36, v4
	s_waitcnt lgkmcnt(4)
	v_cvt_pk_bf16_f32 v21, v38, v40
	s_waitcnt lgkmcnt(2)
	v_cvt_pk_bf16_f32 v22, v42, v44
	s_waitcnt lgkmcnt(0)
	v_cvt_pk_bf16_f32 v23, v46, v48
	v_lshlrev_b32_e32 v0, 11, v0
	global_store_dwordx4 v[50:51], v[20:23], off
	v_lshl_add_u64 v[2:3], v[2:3], 0, v[0:1]
	s_nop 0
	v_cvt_pk_bf16_f32 v20, v37, v5
	v_cvt_pk_bf16_f32 v21, v39, v41
	v_cvt_pk_bf16_f32 v22, v43, v45
	v_cvt_pk_bf16_f32 v23, v47, v49
	global_store_dwordx4 v[2:3], v[20:23], off
	s_waitcnt lgkmcnt(0)

; #define LAS __attribute__((address_space(3)))
; template <int MODE>
; __device__ __forceinline__ void transpose_item(const float* W, int K, int Nsrc, const float* g, bf16_t* WT, LAS float* scr, int kb, int nb, int lane) {
;     const int k0 = 64 * kb, n0 = 32 * nb, nd = n0 + (lane & 7) * 4;
;     int src = nd;
;     if (MODE == 1) src = nd < 4096 ? nd : (nd < 7168 ? nd + 16 : (nd < 7184 ? nd - 7168 + 4096 : -1));
; #pragma unroll
;     for (int i = 0; i < 8; ++i) { const int kk = 8 * i + (lane >> 3); f32x4 v = {0.f, 0.f, 0.f, 0.f};
;         if (src >= 0) { v = *(const f32x4*)(W + (size_t)(k0 + kk) * Nsrc + src); if (g) v = v * g[k0 + kk]; }
;         LAS float* d = scr + kk * 33 + (lane & 7) * 4; d[0] = v[0]; d[1] = v[1]; d[2] = v[2]; d[3] = v[3]; }
; __device__ __forceinline__ void prep_weights(const Ctx& P, LAS unsigned char* lds, int l, int gw, int NGW) {
;     ...
;         if (r < I_IN) { transpose_item<1>(p_win + (size_t)l * D * 7184, D, 7184, p_g1 + l * D, (bf16_t*)(ws + WS_WIN) + (size_t)l * NZ * D, scr, r / 232, r % 232, lane); continue; } r -= I_IN;
.LBB0_524:
	s_or_saveexec_b64 s[50:51], s[38:39]
	v_lshl_add_u64 v[20:21], v[0:1], 2, s[42:43]
	v_cndmask_b32_e64 v0, 0, 1, s[46:47]
	s_lshl_b32 s48, s48, 6
	v_mov_b32_e32 v5, 0
	v_cmp_ne_u32_e64 s[38:39], 1, v0
	v_mov_b32_e32 v4, 0
	v_mov_b32_e32 v3, 0
	v_mov_b32_e32 v2, 0
	s_xor_b64 exec, exec, s[50:51]
	s_cbranch_execz .LBB0_529
	v_or_b32_e32 v22, s48, v6
	s_movk_i32 s49, 0x7040
	v_mad_i64_i32 v[2:3], s[56:57], v22, s49, v[20:21]
	flat_load_dwordx4 v[2:5], v[2:3] nt
	s_and_b64 vcc, exec, s[38:39]
	s_cbranch_vccnz .LBB0_527
	v_ashrrev_i32_e32 v23, 31, v22
	v_lshl_add_u64 v[22:23], v[22:23], 2, s[44:45]
	flat_load_dword v0, v[22:23]
	s_waitcnt vmcnt(0) lgkmcnt(0)
	v_pk_mul_f32 v[4:5], v[4:5], v[0:1] op_sel_hi:[1,0]
	v_pk_mul_f32 v[2:3], v[2:3], v[0:1] op_sel_hi:[1,0]
.LBB0_527:
	v_or_b32_e32 v0, s48, v28
	s_waitcnt vmcnt(0) lgkmcnt(0)
	ds_write2_b32 v36, v2, v3 offset1:1
	ds_write2_b32 v36, v4, v5 offset0:2 offset1:3
	v_mad_i64_i32 v[2:3], s[56:57], v0, s49, v[20:21]
	flat_load_dwordx4 v[2:5], v[2:3] nt
	s_and_b64 vcc, exec, s[38:39]
	s_cbranch_vccnz .LBB0_529
	s_ashr_i32 s49, s48, 31
	v_lshl_add_u64 v[22:23], s[48:49], 0, v[6:7]
	v_lshl_add_u64 v[22:23], v[22:23], 2, s[44:45]
	flat_load_dword v0, v[22:23] offset:32
	s_waitcnt vmcnt(0) lgkmcnt(0)
	v_pk_mul_f32 v[4:5], v[4:5], v[0:1] op_sel_hi:[1,0]
	v_pk_mul_f32 v[2:3], v[2:3], v[0:1] op_sel_hi:[1,0]

; #define LAS __attribute__((address_space(3)))
; template <int MODE>
; __device__ __forceinline__ void transpose_item(const float* W, int K, int Nsrc, const float* g, bf16_t* WT, LAS float* scr, int kb, int nb, int lane) {
;     const int k0 = 64 * kb, n0 = 32 * nb, nd = n0 + (lane & 7) * 4;
;     int src = nd;
;     if (MODE == 1) src = nd < 4096 ? nd : (nd < 7168 ? nd + 16 : (nd < 7184 ? nd - 7168 + 4096 : -1));
; #pragma unroll
;     for (int i = 0; i < 8; ++i) { const int kk = 8 * i + (lane >> 3); f32x4 v = {0.f, 0.f, 0.f, 0.f};
;         if (src >= 0) { v = *(const f32x4*)(W + (size_t)(k0 + kk) * Nsrc + src); if (g) v = v * g[k0 + kk]; }
;         LAS float* d = scr + kk * 33 + (lane & 7) * 4; d[0] = v[0]; d[1] = v[1]; d[2] = v[2]; d[3] = v[3]; }
; __device__ __forceinline__ void prep_weights(const Ctx& P, LAS unsigned char* lds, int l, int gw, int NGW) {
;     ...
;         if (r < I_IN) { transpose_item<1>(p_win + (size_t)l * D * 7184, D, 7184, p_g1 + l * D, (bf16_t*)(ws + WS_WIN) + (size_t)l * NZ * D, scr, r / 232, r % 232, lane); continue; } r -= I_IN;
.LBB0_531:
	s_or_saveexec_b64 s[50:51], s[50:51]
	v_mov_b32_e32 v5, 0
	v_mov_b32_e32 v4, 0
	v_mov_b32_e32 v3, 0
	v_mov_b32_e32 v2, 0
	s_xor_b64 exec, exec, s[50:51]
	s_cbranch_execz .LBB0_536
	v_or_b32_e32 v2, s48, v29
	s_movk_i32 s49, 0x7040
	v_mad_i64_i32 v[2:3], s[56:57], v2, s49, v[20:21]
	flat_load_dwordx4 v[2:5], v[2:3] nt
	s_and_b64 vcc, exec, s[38:39]
	s_cbranch_vccnz .LBB0_534
	s_ashr_i32 s49, s48, 31
	v_lshl_add_u64 v[38:39], s[48:49], 0, v[6:7]
	v_lshl_add_u64 v[38:39], v[38:39], 2, s[44:45]
	flat_load_dword v38, v[38:39] offset:64
	s_waitcnt vmcnt(0) lgkmcnt(0)
	v_pk_mul_f32 v[4:5], v[4:5], v[38:39] op_sel_hi:[1,0]
	v_pk_mul_f32 v[2:3], v[2:3], v[38:39] op_sel_hi:[1,0]
.LBB0_534:
	s_waitcnt vmcnt(0) lgkmcnt(0)
	ds_write2_b32 v0, v2, v3 offset1:1
	ds_write2_b32 v22, v4, v5 offset1:1
	v_or_b32_e32 v0, s48, v30
	s_movk_i32 s49, 0x7040
	v_mad_i64_i32 v[2:3], s[56:57], v0, s49, v[20:21]
	flat_load_dwordx4 v[2:5], v[2:3] nt
	s_and_b64 vcc, exec, s[38:39]
	s_cbranch_vccnz .LBB0_536
	s_ashr_i32 s49, s48, 31
	v_lshl_add_u64 v[22:23], s[48:49], 0, v[6:7]
	v_lshl_add_u64 v[22:23], v[22:23], 2, s[44:45]
	flat_load_dword v0, v[22:23] offset:96
	s_waitcnt vmcnt(0) lgkmcnt(0)
	v_pk_mul_f32 v[4:5], v[4:5], v[0:1] op_sel_hi:[1,0]
	v_pk_mul_f32 v[2:3], v[2:3], v[0:1] op_sel_hi:[1,0]

; #define LAS __attribute__((address_space(3)))
; template <int MODE>
; __device__ __forceinline__ void transpose_item(const float* W, int K, int Nsrc, const float* g, bf16_t* WT, LAS float* scr, int kb, int nb, int lane) {
;     const int k0 = 64 * kb, n0 = 32 * nb, nd = n0 + (lane & 7) * 4;
;     int src = nd;
;     if (MODE == 1) src = nd < 4096 ? nd : (nd < 7168 ? nd + 16 : (nd < 7184 ? nd - 7168 + 4096 : -1));
; #pragma unroll
;     for (int i = 0; i < 8; ++i) { const int kk = 8 * i + (lane >> 3); f32x4 v = {0.f, 0.f, 0.f, 0.f};
;         if (src >= 0) { v = *(const f32x4*)(W + (size_t)(k0 + kk) * Nsrc + src); if (g) v = v * g[k0 + kk]; }
;         LAS float* d = scr + kk * 33 + (lane & 7) * 4; d[0] = v[0]; d[1] = v[1]; d[2] = v[2]; d[3] = v[3]; }
; __device__ __forceinline__ void prep_weights(const Ctx& P, LAS unsigned char* lds, int l, int gw, int NGW) {
;     ...
;         if (r < I_IN) { transpose_item<1>(p_win + (size_t)l * D * 7184, D, 7184, p_g1 + l * D, (bf16_t*)(ws + WS_WIN) + (size_t)l * NZ * D, scr, r / 232, r % 232, lane); continue; } r -= I_IN;
.LBB0_538:
	s_or_saveexec_b64 s[50:51], s[50:51]
	v_mov_b32_e32 v5, 0
	v_mov_b32_e32 v4, 0
	v_mov_b32_e32 v3, 0
	v_mov_b32_e32 v2, 0
	s_xor_b64 exec, exec, s[50:51]
	s_cbranch_execz .LBB0_543
	v_or_b32_e32 v2, s48, v31
	s_movk_i32 s49, 0x7040
	v_mad_i64_i32 v[2:3], s[56:57], v2, s49, v[20:21]
	flat_load_dwordx4 v[2:5], v[2:3] nt
	s_and_b64 vcc, exec, s[38:39]
	s_cbranch_vccnz .LBB0_541
	s_ashr_i32 s49, s48, 31
	v_lshl_add_u64 v[38:39], s[48:49], 0, v[6:7]
	v_lshl_add_u64 v[38:39], v[38:39], 2, s[44:45]
	flat_load_dword v38, v[38:39] offset:128
	s_waitcnt vmcnt(0) lgkmcnt(0)
	v_pk_mul_f32 v[4:5], v[4:5], v[38:39] op_sel_hi:[1,0]
	v_pk_mul_f32 v[2:3], v[2:3], v[38:39] op_sel_hi:[1,0]
.LBB0_541:
	s_waitcnt vmcnt(0) lgkmcnt(0)
	ds_write2_b32 v0, v2, v3 offset1:1
	ds_write2_b32 v22, v4, v5 offset1:1
	v_or_b32_e32 v0, s48, v32
	s_movk_i32 s49, 0x7040
	v_mad_i64_i32 v[2:3], s[56:57], v0, s49, v[20:21]
	flat_load_dwordx4 v[2:5], v[2:3] nt
	s_and_b64 vcc, exec, s[38:39]
	s_cbranch_vccnz .LBB0_543
	s_ashr_i32 s49, s48, 31
	v_lshl_add_u64 v[22:23], s[48:49], 0, v[6:7]
	v_lshl_add_u64 v[22:23], v[22:23], 2, s[44:45]
	flat_load_dword v0, v[22:23] offset:160
	s_waitcnt vmcnt(0) lgkmcnt(0)
	v_pk_mul_f32 v[4:5], v[4:5], v[0:1] op_sel_hi:[1,0]
	v_pk_mul_f32 v[2:3], v[2:3], v[0:1] op_sel_hi:[1,0]

; #define LAS __attribute__((address_space(3)))
; template <int MODE>
; __device__ __forceinline__ void transpose_item(const float* W, int K, int Nsrc, const float* g, bf16_t* WT, LAS float* scr, int kb, int nb, int lane) {
;     const int k0 = 64 * kb, n0 = 32 * nb, nd = n0 + (lane & 7) * 4;
;     int src = nd;
;     if (MODE == 1) src = nd < 4096 ? nd : (nd < 7168 ? nd + 16 : (nd < 7184 ? nd - 7168 + 4096 : -1));
; #pragma unroll
;     for (int i = 0; i < 8; ++i) { const int kk = 8 * i + (lane >> 3); f32x4 v = {0.f, 0.f, 0.f, 0.f};
;         if (src >= 0) { v = *(const f32x4*)(W + (size_t)(k0 + kk) * Nsrc + src); if (g) v = v * g[k0 + kk]; }
;         LAS float* d = scr + kk * 33 + (lane & 7) * 4; d[0] = v[0]; d[1] = v[1]; d[2] = v[2]; d[3] = v[3]; }
; __device__ __forceinline__ void prep_weights(const Ctx& P, LAS unsigned char* lds, int l, int gw, int NGW) {
;     ...
;         if (r < I_IN) { transpose_item<1>(p_win + (size_t)l * D * 7184, D, 7184, p_g1 + l * D, (bf16_t*)(ws + WS_WIN) + (size_t)l * NZ * D, scr, r / 232, r % 232, lane); continue; } r -= I_IN;
.LBB0_545:
	s_or_saveexec_b64 s[40:41], s[40:41]
	v_mov_b32_e32 v5, 0
	v_mov_b32_e32 v4, 0
	v_mov_b32_e32 v3, 0
	v_mov_b32_e32 v2, 0
	s_xor_b64 exec, exec, s[40:41]
	s_cbranch_execz .LBB0_480
	v_or_b32_e32 v2, s48, v33
	s_movk_i32 s49, 0x7040
	v_mad_i64_i32 v[2:3], s[50:51], v2, s49, v[20:21]
	flat_load_dwordx4 v[2:5], v[2:3] nt
	s_and_b64 vcc, exec, s[38:39]
	s_cbranch_vccnz .LBB0_548
	s_ashr_i32 s49, s48, 31
	v_lshl_add_u64 v[38:39], s[48:49], 0, v[6:7]
	v_lshl_add_u64 v[38:39], v[38:39], 2, s[44:45]
	flat_load_dword v38, v[38:39] offset:192
	s_waitcnt vmcnt(0) lgkmcnt(0)
	v_pk_mul_f32 v[4:5], v[4:5], v[38:39] op_sel_hi:[1,0]
	v_pk_mul_f32 v[2:3], v[2:3], v[38:39] op_sel_hi:[1,0]
.LBB0_548:
	s_waitcnt vmcnt(0) lgkmcnt(0)
	ds_write2_b32 v0, v2, v3 offset1:1
	ds_write2_b32 v22, v4, v5 offset1:1
	v_or_b32_e32 v0, s48, v34
	s_movk_i32 s49, 0x7040
	v_mad_i64_i32 v[2:3], s[50:51], v0, s49, v[20:21]
	flat_load_dwordx4 v[2:5], v[2:3] nt
	s_and_b64 vcc, exec, s[38:39]
	s_cbranch_vccnz .LBB0_480
	s_ashr_i32 s49, s48, 31
	v_lshl_add_u64 v[20:21], s[48:49], 0, v[6:7]
	v_lshl_add_u64 v[20:21], v[20:21], 2, s[44:45]
	flat_load_dword v0, v[20:21] offset:224
	s_waitcnt vmcnt(0) lgkmcnt(0)
	v_pk_mul_f32 v[4:5], v[4:5], v[0:1] op_sel_hi:[1,0]
	v_pk_mul_f32 v[2:3], v[2:3], v[0:1] op_sel_hi:[1,0]
	s_branch .LBB0_480
